# trimmed post-barrier setprio and redundant lgkmcnt wait ahead of every GEMM MFMA segment
# baseline (speedup 1.0000x reference)
.LBB0_138:
	ds_read_b128 v[146:149], v153
	ds_read_b128 v[156:159], v153 offset:1024
	ds_read_b128 v[160:163], v153 offset:2048
	ds_read_b128 v[164:167], v153 offset:3072
	ds_read_b128 v[168:171], v154
	ds_read_b128 v[172:175], v154 offset:1024
	ds_read_b128 v[176:179], v154 offset:2048
	ds_read_b128 v[180:183], v154 offset:3072
	s_add_u32 s24, s22, 0xfff00080
	s_addc_u32 s25, s23, -1
	s_cmp_eq_u32 s53, 60
	s_cselect_b32 s27, s15, s25
	s_cselect_b32 s26, s49, s24
	s_cselect_b32 s25, s13, s52
	s_cselect_b32 s24, s50, s51
	v_lshl_add_u64 v[216:217], s[22:23], 0, v[138:139]
	s_add_i32 m0, s21, 0xc000
	ds_read_b128 v[184:187], v155
	ds_read_b128 v[188:191], v155 offset:1024
	ds_read_b128 v[192:195], v155 offset:2048
	ds_read_b128 v[196:199], v155 offset:3072
	ds_read_b128 v[200:203], v155 offset:4096
	ds_read_b128 v[204:207], v155 offset:5120
	ds_read_b128 v[208:211], v155 offset:6144
	ds_read_b128 v[212:215], v155 offset:7168
	global_load_lds_dwordx4 v[216:217], off
	v_lshl_add_u64 v[216:217], s[22:23], 0, v[140:141]
	s_add_i32 m0, s21, 0xe000
	s_nop 0
	global_load_lds_dwordx4 v[216:217], off
	s_waitcnt vmcnt(8)
	s_waitcnt lgkmcnt(0)
	s_setprio 1
	s_barrier
	v_mfma_f32_16x16x32_bf16 v[126:129], v[146:149], v[184:187], v[126:129]
	v_mfma_f32_16x16x32_bf16 v[122:125], v[160:163], v[184:187], v[122:125]
	v_mfma_f32_16x16x32_bf16 v[118:121], v[146:149], v[192:195], v[118:121]
	v_mfma_f32_16x16x32_bf16 v[110:113], v[160:163], v[192:195], v[110:113]
	v_mfma_f32_16x16x32_bf16 v[102:105], v[146:149], v[200:203], v[102:105]
	v_mfma_f32_16x16x32_bf16 v[94:97], v[160:163], v[200:203], v[94:97]
	v_mfma_f32_16x16x32_bf16 v[86:89], v[146:149], v[208:211], v[86:89]
	v_mfma_f32_16x16x32_bf16 v[78:81], v[160:163], v[208:211], v[78:81]
	v_mfma_f32_16x16x32_bf16 v[126:129], v[156:159], v[188:191], v[126:129]
	v_mfma_f32_16x16x32_bf16 v[122:125], v[164:167], v[188:191], v[122:125]
	v_mfma_f32_16x16x32_bf16 v[118:121], v[156:159], v[196:199], v[118:121]
	v_mfma_f32_16x16x32_bf16 v[110:113], v[164:167], v[196:199], v[110:113]
	v_mfma_f32_16x16x32_bf16 v[102:105], v[156:159], v[204:207], v[102:105]
	v_mfma_f32_16x16x32_bf16 v[94:97], v[164:167], v[204:207], v[94:97]
	v_mfma_f32_16x16x32_bf16 v[86:89], v[156:159], v[212:215], v[86:89]
	v_mfma_f32_16x16x32_bf16 v[78:81], v[164:167], v[212:215], v[78:81]
	s_setprio 0
	s_setprio 1
	v_mfma_f32_16x16x32_bf16 v[114:117], v[168:171], v[184:187], v[114:117]
	v_mfma_f32_16x16x32_bf16 v[106:109], v[176:179], v[184:187], v[106:109]
	v_mfma_f32_16x16x32_bf16 v[98:101], v[168:171], v[192:195], v[98:101]
	v_mfma_f32_16x16x32_bf16 v[90:93], v[176:179], v[192:195], v[90:93]
	v_mfma_f32_16x16x32_bf16 v[82:85], v[168:171], v[200:203], v[82:85]
	v_mfma_f32_16x16x32_bf16 v[74:77], v[176:179], v[200:203], v[74:77]
	v_mfma_f32_16x16x32_bf16 v[70:73], v[168:171], v[208:211], v[70:73]
	v_mfma_f32_16x16x32_bf16 v[66:69], v[176:179], v[208:211], v[66:69]
	v_mfma_f32_16x16x32_bf16 v[114:117], v[172:175], v[188:191], v[114:117]
	v_mfma_f32_16x16x32_bf16 v[106:109], v[180:183], v[188:191], v[106:109]
	v_mfma_f32_16x16x32_bf16 v[98:101], v[172:175], v[196:199], v[98:101]
	v_mfma_f32_16x16x32_bf16 v[90:93], v[180:183], v[196:199], v[90:93]
	v_mfma_f32_16x16x32_bf16 v[82:85], v[172:175], v[204:207], v[82:85]
	v_mfma_f32_16x16x32_bf16 v[74:77], v[180:183], v[204:207], v[74:77]
	v_mfma_f32_16x16x32_bf16 v[70:73], v[172:175], v[212:215], v[70:73]
	v_mfma_f32_16x16x32_bf16 v[66:69], v[180:183], v[212:215], v[66:69]
	s_setprio 0
	s_barrier
	s_add_i32 s54, s45, s33
	v_lshl_add_u64 v[216:217], s[24:25], 0, v[134:135]
	s_mov_b32 m0, s54
	ds_read_b128 v[184:187], v155 offset:16384
	ds_read_b128 v[188:191], v155 offset:17408
	ds_read_b128 v[192:195], v155 offset:18432
	ds_read_b128 v[196:199], v155 offset:19456
	ds_read_b128 v[200:203], v155 offset:20480
	ds_read_b128 v[204:207], v155 offset:21504
	ds_read_b128 v[208:211], v155 offset:22528
	ds_read_b128 v[212:215], v155 offset:23552
	global_load_lds_dwordx4 v[216:217], off
	s_add_i32 m0, s54, 0x2000
	s_add_u32 s54, s24, 0x100000
	v_lshl_add_u64 v[218:219], s[24:25], 0, v[130:131]
	s_addc_u32 s55, s25, 0
	s_add_i32 s56, s46, s33
	global_load_lds_dwordx4 v[218:219], off
	v_lshl_add_u64 v[220:221], s[54:55], 0, v[134:135]
	s_mov_b32 m0, s56
	v_lshl_add_u64 v[222:223], s[26:27], 0, v[132:133]
	global_load_lds_dwordx4 v[220:221], off
	v_lshl_add_u64 v[220:221], s[54:55], 0, v[130:131]
	s_add_i32 m0, s56, 0x2000
	s_nop 0
	global_load_lds_dwordx4 v[220:221], off
	v_lshl_add_u64 v[220:221], s[26:27], 0, v[136:137]
	s_mov_b32 m0, s21
	s_nop 0
	global_load_lds_dwordx4 v[220:221], off
	s_mov_b32 m0, s36
	s_nop 0
	global_load_lds_dwordx4 v[222:223], off
	s_waitcnt vmcnt(8)
	s_waitcnt lgkmcnt(0)
	s_setprio 1
	s_barrier
	v_mfma_f32_16x16x32_bf16 v[62:65], v[146:149], v[184:187], v[62:65]
	v_mfma_f32_16x16x32_bf16 v[58:61], v[160:163], v[184:187], v[58:61]
	v_mfma_f32_16x16x32_bf16 v[54:57], v[146:149], v[192:195], v[54:57]
	v_mfma_f32_16x16x32_bf16 v[46:49], v[160:163], v[192:195], v[46:49]
	v_mfma_f32_16x16x32_bf16 v[38:41], v[146:149], v[200:203], v[38:41]
	v_mfma_f32_16x16x32_bf16 v[30:33], v[160:163], v[200:203], v[30:33]
	v_mfma_f32_16x16x32_bf16 v[22:25], v[146:149], v[208:211], v[22:25]
	v_mfma_f32_16x16x32_bf16 v[14:17], v[160:163], v[208:211], v[14:17]
	v_mfma_f32_16x16x32_bf16 v[62:65], v[156:159], v[188:191], v[62:65]
	v_mfma_f32_16x16x32_bf16 v[58:61], v[164:167], v[188:191], v[58:61]
	v_mfma_f32_16x16x32_bf16 v[54:57], v[156:159], v[196:199], v[54:57]
	v_mfma_f32_16x16x32_bf16 v[46:49], v[164:167], v[196:199], v[46:49]
	v_mfma_f32_16x16x32_bf16 v[38:41], v[156:159], v[204:207], v[38:41]
	v_mfma_f32_16x16x32_bf16 v[30:33], v[164:167], v[204:207], v[30:33]
	v_mfma_f32_16x16x32_bf16 v[22:25], v[156:159], v[212:215], v[22:25]
	v_mfma_f32_16x16x32_bf16 v[14:17], v[164:167], v[212:215], v[14:17]
	s_setprio 0
	s_setprio 1
	v_mfma_f32_16x16x32_bf16 v[50:53], v[168:171], v[184:187], v[50:53]
	v_mfma_f32_16x16x32_bf16 v[42:45], v[176:179], v[184:187], v[42:45]
	v_mfma_f32_16x16x32_bf16 v[34:37], v[168:171], v[192:195], v[34:37]
	v_mfma_f32_16x16x32_bf16 v[26:29], v[176:179], v[192:195], v[26:29]
	v_mfma_f32_16x16x32_bf16 v[18:21], v[168:171], v[200:203], v[18:21]
	v_mfma_f32_16x16x32_bf16 v[10:13], v[176:179], v[200:203], v[10:13]
	v_mfma_f32_16x16x32_bf16 v[6:9], v[168:171], v[208:211], v[6:9]
	v_mfma_f32_16x16x32_bf16 v[2:5], v[176:179], v[208:211], v[2:5]
	v_mfma_f32_16x16x32_bf16 v[50:53], v[172:175], v[188:191], v[50:53]
	v_mfma_f32_16x16x32_bf16 v[42:45], v[180:183], v[188:191], v[42:45]
	v_mfma_f32_16x16x32_bf16 v[34:37], v[172:175], v[196:199], v[34:37]
	v_mfma_f32_16x16x32_bf16 v[26:29], v[180:183], v[196:199], v[26:29]
	v_mfma_f32_16x16x32_bf16 v[18:21], v[172:175], v[204:207], v[18:21]
	v_mfma_f32_16x16x32_bf16 v[10:13], v[180:183], v[204:207], v[10:13]
	v_mfma_f32_16x16x32_bf16 v[6:9], v[172:175], v[212:215], v[6:9]
	v_mfma_f32_16x16x32_bf16 v[2:5], v[180:183], v[212:215], v[2:5]
	s_setprio 0
	s_barrier
	s_add_i32 s54, 0, 0x18000
	s_add_i32 s55, 0, 0x1c000
	v_add_u32_e32 v164, s54, v152
	v_add_u32_e32 v180, s55, v152
	ds_read_b128 v[146:149], v164
	ds_read_b128 v[156:159], v164 offset:1024
	ds_read_b128 v[160:163], v164 offset:2048
	ds_read_b128 v[164:167], v164 offset:3072
	ds_read_b128 v[168:171], v180
	ds_read_b128 v[172:175], v180 offset:1024
	ds_read_b128 v[176:179], v180 offset:2048
	ds_read_b128 v[180:183], v180 offset:3072
	s_add_u32 s26, s26, 0x100000
	s_addc_u32 s27, s27, 0
	s_mov_b32 m0, s37
	v_lshl_add_u64 v[224:225], s[26:27], 0, v[136:137]
	ds_read_b128 v[184:187], v155 offset:32768
	ds_read_b128 v[188:191], v155 offset:33792
	ds_read_b128 v[192:195], v155 offset:34816
	ds_read_b128 v[196:199], v155 offset:35840
	ds_read_b128 v[200:203], v155 offset:36864
	ds_read_b128 v[204:207], v155 offset:37888
	ds_read_b128 v[208:211], v155 offset:38912
	ds_read_b128 v[212:215], v155 offset:39936
	global_load_lds_dwordx4 v[224:225], off
	v_lshl_add_u64 v[224:225], s[26:27], 0, v[132:133]
	s_mov_b32 m0, s38
	s_nop 0
	global_load_lds_dwordx4 v[224:225], off
	s_waitcnt vmcnt(8)
	s_waitcnt lgkmcnt(0)
	s_setprio 1
	s_barrier
	v_mfma_f32_16x16x32_bf16 v[126:129], v[146:149], v[184:187], v[126:129]
	v_mfma_f32_16x16x32_bf16 v[122:125], v[160:163], v[184:187], v[122:125]
	v_mfma_f32_16x16x32_bf16 v[118:121], v[146:149], v[192:195], v[118:121]
	v_mfma_f32_16x16x32_bf16 v[110:113], v[160:163], v[192:195], v[110:113]
	v_mfma_f32_16x16x32_bf16 v[102:105], v[146:149], v[200:203], v[102:105]
	v_mfma_f32_16x16x32_bf16 v[94:97], v[160:163], v[200:203], v[94:97]
	v_mfma_f32_16x16x32_bf16 v[86:89], v[146:149], v[208:211], v[86:89]
	v_mfma_f32_16x16x32_bf16 v[78:81], v[160:163], v[208:211], v[78:81]
	v_mfma_f32_16x16x32_bf16 v[126:129], v[156:159], v[188:191], v[126:129]
	v_mfma_f32_16x16x32_bf16 v[122:125], v[164:167], v[188:191], v[122:125]
	v_mfma_f32_16x16x32_bf16 v[118:121], v[156:159], v[196:199], v[118:121]
	v_mfma_f32_16x16x32_bf16 v[110:113], v[164:167], v[196:199], v[110:113]
	v_mfma_f32_16x16x32_bf16 v[102:105], v[156:159], v[204:207], v[102:105]
	v_mfma_f32_16x16x32_bf16 v[94:97], v[164:167], v[204:207], v[94:97]
	v_mfma_f32_16x16x32_bf16 v[86:89], v[156:159], v[212:215], v[86:89]
	v_mfma_f32_16x16x32_bf16 v[78:81], v[164:167], v[212:215], v[78:81]
	s_setprio 0
	s_setprio 1
	v_mfma_f32_16x16x32_bf16 v[114:117], v[168:171], v[184:187], v[114:117]
	v_mfma_f32_16x16x32_bf16 v[106:109], v[176:179], v[184:187], v[106:109]
	v_mfma_f32_16x16x32_bf16 v[98:101], v[168:171], v[192:195], v[98:101]
	v_mfma_f32_16x16x32_bf16 v[90:93], v[176:179], v[192:195], v[90:93]
	v_mfma_f32_16x16x32_bf16 v[82:85], v[168:171], v[200:203], v[82:85]
	v_mfma_f32_16x16x32_bf16 v[74:77], v[176:179], v[200:203], v[74:77]
	v_mfma_f32_16x16x32_bf16 v[70:73], v[168:171], v[208:211], v[70:73]
	v_mfma_f32_16x16x32_bf16 v[66:69], v[176:179], v[208:211], v[66:69]
	v_mfma_f32_16x16x32_bf16 v[114:117], v[172:175], v[188:191], v[114:117]
	v_mfma_f32_16x16x32_bf16 v[106:109], v[180:183], v[188:191], v[106:109]
	v_mfma_f32_16x16x32_bf16 v[98:101], v[172:175], v[196:199], v[98:101]
	v_mfma_f32_16x16x32_bf16 v[90:93], v[180:183], v[196:199], v[90:93]
	v_mfma_f32_16x16x32_bf16 v[82:85], v[172:175], v[204:207], v[82:85]
	v_mfma_f32_16x16x32_bf16 v[74:77], v[180:183], v[204:207], v[74:77]
	v_mfma_f32_16x16x32_bf16 v[70:73], v[172:175], v[212:215], v[70:73]
	v_mfma_f32_16x16x32_bf16 v[66:69], v[180:183], v[212:215], v[66:69]
	s_setprio 0
	s_barrier
	s_add_i32 s26, s54, s33
	v_lshl_add_u64 v[216:217], v[216:217], 0, s[8:9]
	s_mov_b32 m0, s26
	ds_read_b128 v[184:187], v155 offset:49152
	ds_read_b128 v[188:191], v155 offset:50176
	ds_read_b128 v[192:195], v155 offset:51200
	ds_read_b128 v[196:199], v155 offset:52224
	ds_read_b128 v[200:203], v155 offset:53248
	ds_read_b128 v[204:207], v155 offset:54272
	ds_read_b128 v[208:211], v155 offset:55296
	ds_read_b128 v[212:215], v155 offset:56320
	global_load_lds_dwordx4 v[216:217], off
	s_add_i32 m0, s26, 0x2000
	s_add_u32 s24, s24, 0x100080
	v_lshl_add_u64 v[216:217], v[218:219], 0, s[8:9]
	s_addc_u32 s25, s25, 0
	s_add_i32 s26, s55, s33
	global_load_lds_dwordx4 v[216:217], off
	v_lshl_add_u64 v[216:217], s[24:25], 0, v[134:135]
	s_mov_b32 m0, s26
	s_nop 0
	global_load_lds_dwordx4 v[216:217], off
	v_lshl_add_u64 v[216:217], s[24:25], 0, v[130:131]
	s_add_i32 m0, s26, 0x2000
	s_nop 0
	global_load_lds_dwordx4 v[216:217], off
	v_lshl_add_u64 v[216:217], v[220:221], 0, s[8:9]
	s_mov_b32 m0, s42
	s_nop 0
	global_load_lds_dwordx4 v[216:217], off
	v_lshl_add_u64 v[216:217], v[222:223], 0, s[8:9]
	s_mov_b32 m0, s43
	s_nop 0
	global_load_lds_dwordx4 v[216:217], off
	s_waitcnt vmcnt(8)
	s_waitcnt lgkmcnt(0)
	s_setprio 1
	s_barrier
	v_mfma_f32_16x16x32_bf16 v[62:65], v[146:149], v[184:187], v[62:65]
	v_mfma_f32_16x16x32_bf16 v[58:61], v[160:163], v[184:187], v[58:61]
	v_mfma_f32_16x16x32_bf16 v[54:57], v[146:149], v[192:195], v[54:57]
	v_mfma_f32_16x16x32_bf16 v[46:49], v[160:163], v[192:195], v[46:49]
	v_mfma_f32_16x16x32_bf16 v[38:41], v[146:149], v[200:203], v[38:41]
	v_mfma_f32_16x16x32_bf16 v[30:33], v[160:163], v[200:203], v[30:33]
	v_mfma_f32_16x16x32_bf16 v[22:25], v[146:149], v[208:211], v[22:25]
	v_mfma_f32_16x16x32_bf16 v[14:17], v[160:163], v[208:211], v[14:17]
	v_mfma_f32_16x16x32_bf16 v[62:65], v[156:159], v[188:191], v[62:65]
	v_mfma_f32_16x16x32_bf16 v[58:61], v[164:167], v[188:191], v[58:61]
	v_mfma_f32_16x16x32_bf16 v[54:57], v[156:159], v[196:199], v[54:57]
	v_mfma_f32_16x16x32_bf16 v[46:49], v[164:167], v[196:199], v[46:49]
	v_mfma_f32_16x16x32_bf16 v[38:41], v[156:159], v[204:207], v[38:41]
	v_mfma_f32_16x16x32_bf16 v[30:33], v[164:167], v[204:207], v[30:33]
	v_mfma_f32_16x16x32_bf16 v[22:25], v[156:159], v[212:215], v[22:25]
	v_mfma_f32_16x16x32_bf16 v[14:17], v[164:167], v[212:215], v[14:17]
	s_setprio 0
	s_setprio 1
	v_mfma_f32_16x16x32_bf16 v[50:53], v[168:171], v[184:187], v[50:53]
	v_mfma_f32_16x16x32_bf16 v[42:45], v[176:179], v[184:187], v[42:45]
	v_mfma_f32_16x16x32_bf16 v[34:37], v[168:171], v[192:195], v[34:37]
	v_mfma_f32_16x16x32_bf16 v[26:29], v[176:179], v[192:195], v[26:29]
	v_mfma_f32_16x16x32_bf16 v[18:21], v[168:171], v[200:203], v[18:21]
	v_mfma_f32_16x16x32_bf16 v[10:13], v[176:179], v[200:203], v[10:13]
	v_mfma_f32_16x16x32_bf16 v[6:9], v[168:171], v[208:211], v[6:9]
	v_mfma_f32_16x16x32_bf16 v[2:5], v[176:179], v[208:211], v[2:5]
	v_mfma_f32_16x16x32_bf16 v[50:53], v[172:175], v[188:191], v[50:53]
	v_mfma_f32_16x16x32_bf16 v[42:45], v[180:183], v[188:191], v[42:45]
	v_mfma_f32_16x16x32_bf16 v[34:37], v[172:175], v[196:199], v[34:37]
	v_mfma_f32_16x16x32_bf16 v[26:29], v[180:183], v[196:199], v[26:29]
	v_mfma_f32_16x16x32_bf16 v[18:21], v[172:175], v[204:207], v[18:21]
	v_mfma_f32_16x16x32_bf16 v[10:13], v[180:183], v[204:207], v[10:13]
	v_mfma_f32_16x16x32_bf16 v[6:9], v[172:175], v[212:215], v[6:9]
	v_mfma_f32_16x16x32_bf16 v[2:5], v[180:183], v[212:215], v[2:5]
	s_setprio 0
	s_barrier
	s_add_i32 s53, s53, 2
	s_add_u32 s22, s22, 0x100
	s_addc_u32 s23, s23, 0
	s_add_u32 s51, s51, 0x100
	s_addc_u32 s52, s52, 0
	s_cmp_gt_u32 s53, 61
	s_cbranch_scc0 .LBB0_138
	s_and_b64 vcc, exec, s[10:11]
	s_cbranch_vccz .LBB0_141
	s_barrier

.LBB0_183:
	v_add_u32_e32 v2, s73, v192
	v_add_u32_e32 v6, s74, v192
	s_add_u32 s20, s44, s0
	ds_read_b128 v[26:29], v2
	ds_read_b128 v[30:33], v2 offset:1024
	ds_read_b128 v[18:21], v2 offset:2048
	ds_read_b128 v[22:25], v2 offset:3072
	ds_read_b128 v[10:13], v6
	ds_read_b128 v[14:17], v6 offset:1024
	ds_read_b128 v[2:5], v6 offset:2048
	ds_read_b128 v[6:9], v6 offset:3072
	s_addc_u32 s21, s45, s1
	s_add_u32 s20, s20, 0x100
	s_addc_u32 s21, s21, 0
	s_add_u32 s47, s34, s0
	s_addc_u32 s49, s35, s1
	s_cmpk_eq_i32 s0, 0xf00
	s_cselect_b32 s23, s14, s21
	s_cselect_b32 s22, s30, s20
	s_cselect_b32 s21, s31, s49
	s_cselect_b32 s20, s36, s47
	v_lshl_add_u64 v[218:219], v[176:177], 0, s[0:1]
	s_add_i32 m0, s11, 0xc000
	ds_read_b128 v[180:183], v193
	ds_read_b128 v[184:187], v193 offset:1024
	ds_read_b128 v[194:197], v193 offset:2048
	ds_read_b128 v[198:201], v193 offset:3072
	ds_read_b128 v[202:205], v193 offset:4096
	ds_read_b128 v[206:209], v193 offset:5120
	ds_read_b128 v[210:213], v193 offset:6144
	ds_read_b128 v[214:217], v193 offset:7168
	global_load_lds_dwordx4 v[218:219], off
	v_lshl_add_u64 v[218:219], v[178:179], 0, s[0:1]
	s_add_i32 m0, s11, 0xe000
	s_nop 0
	global_load_lds_dwordx4 v[218:219], off
	s_waitcnt vmcnt(8)
	s_waitcnt lgkmcnt(0)
	s_setprio 1
	s_barrier
	v_mfma_scale_f32_16x16x128_f8f6f4 v[158:161], v[26:33], v[180:187], v[158:161], v189, v189 op_sel_hi:[0,0,0]
	v_mfma_scale_f32_16x16x128_f8f6f4 v[154:157], v[18:25], v[180:187], v[154:157], v189, v189 op_sel_hi:[0,0,0]
	v_mfma_scale_f32_16x16x128_f8f6f4 v[150:153], v[26:33], v[194:201], v[150:153], v189, v189 op_sel_hi:[0,0,0]
	v_mfma_scale_f32_16x16x128_f8f6f4 v[146:149], v[18:25], v[194:201], v[146:149], v189, v189 op_sel_hi:[0,0,0]
	v_mfma_scale_f32_16x16x128_f8f6f4 v[142:145], v[26:33], v[202:209], v[142:145], v189, v189 op_sel_hi:[0,0,0]
	v_mfma_scale_f32_16x16x128_f8f6f4 v[138:141], v[18:25], v[202:209], v[138:141], v189, v189 op_sel_hi:[0,0,0]
	v_mfma_scale_f32_16x16x128_f8f6f4 v[134:137], v[26:33], v[210:217], v[134:137], v189, v189 op_sel_hi:[0,0,0]
	v_mfma_scale_f32_16x16x128_f8f6f4 v[130:133], v[18:25], v[210:217], v[130:133], v189, v189 op_sel_hi:[0,0,0]
	s_setprio 0
	s_setprio 1
	v_mfma_scale_f32_16x16x128_f8f6f4 v[126:129], v[10:17], v[180:187], v[126:129], v189, v189 op_sel_hi:[0,0,0]
	v_mfma_scale_f32_16x16x128_f8f6f4 v[122:125], v[2:9], v[180:187], v[122:125], v189, v189 op_sel_hi:[0,0,0]
	v_mfma_scale_f32_16x16x128_f8f6f4 v[118:121], v[10:17], v[194:201], v[118:121], v189, v189 op_sel_hi:[0,0,0]
	v_mfma_scale_f32_16x16x128_f8f6f4 v[114:117], v[2:9], v[194:201], v[114:117], v189, v189 op_sel_hi:[0,0,0]
	v_mfma_scale_f32_16x16x128_f8f6f4 v[110:113], v[10:17], v[202:209], v[110:113], v189, v189 op_sel_hi:[0,0,0]
	v_mfma_scale_f32_16x16x128_f8f6f4 v[106:109], v[2:9], v[202:209], v[106:109], v189, v189 op_sel_hi:[0,0,0]
	v_mfma_scale_f32_16x16x128_f8f6f4 v[102:105], v[10:17], v[210:217], v[102:105], v189, v189 op_sel_hi:[0,0,0]
	v_mfma_scale_f32_16x16x128_f8f6f4 v[98:101], v[2:9], v[210:217], v[98:101], v189, v189 op_sel_hi:[0,0,0]
	s_setprio 0
	s_barrier
	s_add_i32 s47, s73, s63
	v_lshl_add_u64 v[180:181], s[20:21], 0, v[164:165]
	s_mov_b32 m0, s47
	ds_read_b128 v[194:197], v193 offset:16384
	ds_read_b128 v[198:201], v193 offset:17408
	ds_read_b128 v[202:205], v193 offset:18432
	ds_read_b128 v[206:209], v193 offset:19456
	ds_read_b128 v[210:213], v193 offset:20480
	ds_read_b128 v[214:217], v193 offset:21504
	ds_read_b128 v[218:221], v193 offset:22528
	ds_read_b128 v[222:225], v193 offset:23552
	global_load_lds_dwordx4 v[180:181], off
	s_add_i32 m0, s47, 0x2000
	s_add_u32 s78, s20, 0x80000
	v_lshl_add_u64 v[182:183], s[20:21], 0, v[168:169]
	s_addc_u32 s79, s21, 0
	s_add_i32 s47, s74, s63
	global_load_lds_dwordx4 v[182:183], off
	v_lshl_add_u64 v[184:185], s[78:79], 0, v[164:165]
	s_mov_b32 m0, s47
	v_lshl_add_u64 v[186:187], s[22:23], 0, v[166:167]
	global_load_lds_dwordx4 v[184:185], off
	v_lshl_add_u64 v[184:185], s[78:79], 0, v[168:169]
	s_add_i32 m0, s47, 0x2000
	s_nop 0
	global_load_lds_dwordx4 v[184:185], off
	v_lshl_add_u64 v[184:185], s[22:23], 0, v[162:163]
	s_mov_b32 m0, s11
	s_nop 0
	global_load_lds_dwordx4 v[184:185], off
	s_mov_b32 m0, s13
	s_nop 0
	global_load_lds_dwordx4 v[186:187], off
	s_waitcnt vmcnt(8)
	s_waitcnt lgkmcnt(0)
	s_setprio 1
	s_barrier
	v_mfma_scale_f32_16x16x128_f8f6f4 v[94:97], v[26:33], v[194:201], v[94:97], v189, v189 op_sel_hi:[0,0,0]
	v_mfma_scale_f32_16x16x128_f8f6f4 v[90:93], v[18:25], v[194:201], v[90:93], v189, v189 op_sel_hi:[0,0,0]
	v_mfma_scale_f32_16x16x128_f8f6f4 v[86:89], v[26:33], v[202:209], v[86:89], v189, v189 op_sel_hi:[0,0,0]
	v_mfma_scale_f32_16x16x128_f8f6f4 v[82:85], v[18:25], v[202:209], v[82:85], v189, v189 op_sel_hi:[0,0,0]
	v_mfma_scale_f32_16x16x128_f8f6f4 v[78:81], v[26:33], v[210:217], v[78:81], v189, v189 op_sel_hi:[0,0,0]
	v_mfma_scale_f32_16x16x128_f8f6f4 v[74:77], v[18:25], v[210:217], v[74:77], v189, v189 op_sel_hi:[0,0,0]
	v_mfma_scale_f32_16x16x128_f8f6f4 v[70:73], v[26:33], v[218:225], v[70:73], v189, v189 op_sel_hi:[0,0,0]
	v_mfma_scale_f32_16x16x128_f8f6f4 v[66:69], v[18:25], v[218:225], v[66:69], v189, v189 op_sel_hi:[0,0,0]
	s_setprio 0
	s_setprio 1
	v_mfma_scale_f32_16x16x128_f8f6f4 v[62:65], v[10:17], v[194:201], v[62:65], v189, v189 op_sel_hi:[0,0,0]
	v_mfma_scale_f32_16x16x128_f8f6f4 v[58:61], v[2:9], v[194:201], v[58:61], v189, v189 op_sel_hi:[0,0,0]
	v_mfma_scale_f32_16x16x128_f8f6f4 v[54:57], v[10:17], v[202:209], v[54:57], v189, v189 op_sel_hi:[0,0,0]
	v_mfma_scale_f32_16x16x128_f8f6f4 v[50:53], v[2:9], v[202:209], v[50:53], v189, v189 op_sel_hi:[0,0,0]
	v_mfma_scale_f32_16x16x128_f8f6f4 v[46:49], v[10:17], v[210:217], v[46:49], v189, v189 op_sel_hi:[0,0,0]
	v_mfma_scale_f32_16x16x128_f8f6f4 v[42:45], v[2:9], v[210:217], v[42:45], v189, v189 op_sel_hi:[0,0,0]
	v_mfma_scale_f32_16x16x128_f8f6f4 v[38:41], v[10:17], v[218:225], v[38:41], v189, v189 op_sel_hi:[0,0,0]
	v_mfma_scale_f32_16x16x128_f8f6f4 v[34:37], v[2:9], v[218:225], v[34:37], v189, v189 op_sel_hi:[0,0,0]
	s_setprio 0
	s_barrier
	s_add_i32 s47, 0, 0x18000
	s_add_i32 s49, 0, 0x1c000
	v_add_u32_e32 v14, s47, v192
	v_add_u32_e32 v30, s49, v192
	ds_read_b128 v[2:5], v14
	ds_read_b128 v[6:9], v14 offset:1024
	ds_read_b128 v[10:13], v14 offset:2048
	ds_read_b128 v[14:17], v14 offset:3072
	ds_read_b128 v[18:21], v30
	ds_read_b128 v[22:25], v30 offset:1024
	ds_read_b128 v[26:29], v30 offset:2048
	ds_read_b128 v[30:33], v30 offset:3072
	s_add_u32 s22, s22, 0x80000
	s_addc_u32 s23, s23, 0
	s_mov_b32 m0, s64
	v_lshl_add_u64 v[226:227], s[22:23], 0, v[162:163]
	ds_read_b128 v[194:197], v193 offset:32768
	ds_read_b128 v[198:201], v193 offset:33792
	ds_read_b128 v[202:205], v193 offset:34816
	ds_read_b128 v[206:209], v193 offset:35840
	ds_read_b128 v[210:213], v193 offset:36864
	ds_read_b128 v[214:217], v193 offset:37888
	ds_read_b128 v[218:221], v193 offset:38912
	ds_read_b128 v[222:225], v193 offset:39936
	global_load_lds_dwordx4 v[226:227], off
	v_lshl_add_u64 v[226:227], s[22:23], 0, v[166:167]
	s_mov_b32 m0, s65
	s_nop 0
	global_load_lds_dwordx4 v[226:227], off
	s_waitcnt vmcnt(8)
	s_waitcnt lgkmcnt(0)
	s_setprio 1
	s_barrier
	v_mfma_scale_f32_16x16x128_f8f6f4 v[158:161], v[2:9], v[194:201], v[158:161], v189, v189 op_sel_hi:[0,0,0]
	v_mfma_scale_f32_16x16x128_f8f6f4 v[154:157], v[10:17], v[194:201], v[154:157], v189, v189 op_sel_hi:[0,0,0]
	v_mfma_scale_f32_16x16x128_f8f6f4 v[150:153], v[2:9], v[202:209], v[150:153], v189, v189 op_sel_hi:[0,0,0]
	v_mfma_scale_f32_16x16x128_f8f6f4 v[146:149], v[10:17], v[202:209], v[146:149], v189, v189 op_sel_hi:[0,0,0]
	v_mfma_scale_f32_16x16x128_f8f6f4 v[142:145], v[2:9], v[210:217], v[142:145], v189, v189 op_sel_hi:[0,0,0]
	v_mfma_scale_f32_16x16x128_f8f6f4 v[138:141], v[10:17], v[210:217], v[138:141], v189, v189 op_sel_hi:[0,0,0]
	v_mfma_scale_f32_16x16x128_f8f6f4 v[134:137], v[2:9], v[218:225], v[134:137], v189, v189 op_sel_hi:[0,0,0]
	v_mfma_scale_f32_16x16x128_f8f6f4 v[130:133], v[10:17], v[218:225], v[130:133], v189, v189 op_sel_hi:[0,0,0]
	s_setprio 0
	s_setprio 1
	v_mfma_scale_f32_16x16x128_f8f6f4 v[126:129], v[18:25], v[194:201], v[126:129], v189, v189 op_sel_hi:[0,0,0]
	v_mfma_scale_f32_16x16x128_f8f6f4 v[122:125], v[26:33], v[194:201], v[122:125], v189, v189 op_sel_hi:[0,0,0]
	v_mfma_scale_f32_16x16x128_f8f6f4 v[118:121], v[18:25], v[202:209], v[118:121], v189, v189 op_sel_hi:[0,0,0]
	v_mfma_scale_f32_16x16x128_f8f6f4 v[114:117], v[26:33], v[202:209], v[114:117], v189, v189 op_sel_hi:[0,0,0]
	v_mfma_scale_f32_16x16x128_f8f6f4 v[110:113], v[18:25], v[210:217], v[110:113], v189, v189 op_sel_hi:[0,0,0]
	v_mfma_scale_f32_16x16x128_f8f6f4 v[106:109], v[26:33], v[210:217], v[106:109], v189, v189 op_sel_hi:[0,0,0]
	v_mfma_scale_f32_16x16x128_f8f6f4 v[102:105], v[18:25], v[218:225], v[102:105], v189, v189 op_sel_hi:[0,0,0]
	v_mfma_scale_f32_16x16x128_f8f6f4 v[98:101], v[26:33], v[218:225], v[98:101], v189, v189 op_sel_hi:[0,0,0]
	s_setprio 0
	s_barrier
	s_add_i32 s22, s47, s63
	v_lshl_add_u64 v[180:181], v[180:181], 0, s[26:27]
	s_mov_b32 m0, s22
	ds_read_b128 v[194:197], v193 offset:49152
	ds_read_b128 v[198:201], v193 offset:50176
	ds_read_b128 v[202:205], v193 offset:51200
	ds_read_b128 v[206:209], v193 offset:52224
	ds_read_b128 v[210:213], v193 offset:53248
	ds_read_b128 v[214:217], v193 offset:54272
	ds_read_b128 v[218:221], v193 offset:55296
	ds_read_b128 v[222:225], v193 offset:56320
	global_load_lds_dwordx4 v[180:181], off
	s_add_i32 m0, s22, 0x2000
	s_add_u32 s20, s20, 0x80080
	v_lshl_add_u64 v[180:181], v[182:183], 0, s[26:27]
	s_addc_u32 s21, s21, 0
	s_add_i32 s22, s49, s63
	global_load_lds_dwordx4 v[180:181], off
	v_lshl_add_u64 v[180:181], s[20:21], 0, v[164:165]
	s_mov_b32 m0, s22
	s_nop 0
	global_load_lds_dwordx4 v[180:181], off
	v_lshl_add_u64 v[180:181], s[20:21], 0, v[168:169]
	s_add_i32 m0, s22, 0x2000
	s_nop 0
	global_load_lds_dwordx4 v[180:181], off
	v_lshl_add_u64 v[180:181], v[184:185], 0, s[26:27]
	s_mov_b32 m0, s66
	s_nop 0
	global_load_lds_dwordx4 v[180:181], off
	v_lshl_add_u64 v[180:181], v[186:187], 0, s[26:27]
	s_mov_b32 m0, s67
	s_nop 0
	global_load_lds_dwordx4 v[180:181], off
	s_waitcnt vmcnt(8)
	s_waitcnt lgkmcnt(0)
	s_setprio 1
	s_barrier
	v_mfma_scale_f32_16x16x128_f8f6f4 v[94:97], v[2:9], v[194:201], v[94:97], v189, v189 op_sel_hi:[0,0,0]
	v_mfma_scale_f32_16x16x128_f8f6f4 v[90:93], v[10:17], v[194:201], v[90:93], v189, v189 op_sel_hi:[0,0,0]
	v_mfma_scale_f32_16x16x128_f8f6f4 v[86:89], v[2:9], v[202:209], v[86:89], v189, v189 op_sel_hi:[0,0,0]
	v_mfma_scale_f32_16x16x128_f8f6f4 v[82:85], v[10:17], v[202:209], v[82:85], v189, v189 op_sel_hi:[0,0,0]
	v_mfma_scale_f32_16x16x128_f8f6f4 v[78:81], v[2:9], v[210:217], v[78:81], v189, v189 op_sel_hi:[0,0,0]
	v_mfma_scale_f32_16x16x128_f8f6f4 v[74:77], v[10:17], v[210:217], v[74:77], v189, v189 op_sel_hi:[0,0,0]
	v_mfma_scale_f32_16x16x128_f8f6f4 v[70:73], v[2:9], v[218:225], v[70:73], v189, v189 op_sel_hi:[0,0,0]
	v_mfma_scale_f32_16x16x128_f8f6f4 v[66:69], v[10:17], v[218:225], v[66:69], v189, v189 op_sel_hi:[0,0,0]
	s_setprio 0
	s_setprio 1
	v_mfma_scale_f32_16x16x128_f8f6f4 v[62:65], v[18:25], v[194:201], v[62:65], v189, v189 op_sel_hi:[0,0,0]
	v_mfma_scale_f32_16x16x128_f8f6f4 v[58:61], v[26:33], v[194:201], v[58:61], v189, v189 op_sel_hi:[0,0,0]
	v_mfma_scale_f32_16x16x128_f8f6f4 v[54:57], v[18:25], v[202:209], v[54:57], v189, v189 op_sel_hi:[0,0,0]
	v_mfma_scale_f32_16x16x128_f8f6f4 v[50:53], v[26:33], v[202:209], v[50:53], v189, v189 op_sel_hi:[0,0,0]
	v_mfma_scale_f32_16x16x128_f8f6f4 v[46:49], v[18:25], v[210:217], v[46:49], v189, v189 op_sel_hi:[0,0,0]
	v_mfma_scale_f32_16x16x128_f8f6f4 v[42:45], v[26:33], v[210:217], v[42:45], v189, v189 op_sel_hi:[0,0,0]
	v_mfma_scale_f32_16x16x128_f8f6f4 v[38:41], v[18:25], v[218:225], v[38:41], v189, v189 op_sel_hi:[0,0,0]
	v_mfma_scale_f32_16x16x128_f8f6f4 v[34:37], v[26:33], v[218:225], v[34:37], v189, v189 op_sel_hi:[0,0,0]
	s_setprio 0
	s_barrier
	s_add_i32 s37, s37, 2
	s_add_u32 s0, s0, 0x100
	s_addc_u32 s1, s1, 0
	s_cmp_gt_u32 s37, 29
	s_cbranch_scc0 .LBB0_183
	s_and_b64 vcc, exec, s[28:29]
	s_cbranch_vccz .LBB0_186
	s_barrier

.LBB0_292:
	s_add_u32 s40, s38, 0xfff80080
	s_addc_u32 s41, s39, -1
	s_add_i32 s81, 0, 0x10000
	s_cmp_eq_u32 s80, 4
	s_cselect_b32 s43, s29, s41
	s_cselect_b32 s42, s76, s40
	v_add_u32_e32 v142, s81, v147
	s_cselect_b32 s41, s27, s79
	s_cselect_b32 s40, s77, s78
	s_add_i32 s84, 0, 0x14000
	ds_read_b128 v[150:153], v142
	ds_read_b128 v[154:157], v142 offset:1024
	ds_read_b128 v[158:161], v142 offset:2048
	ds_read_b128 v[162:165], v142 offset:3072
	v_add_u32_e32 v142, s84, v147
	ds_read_b128 v[166:169], v142
	ds_read_b128 v[170:173], v142 offset:1024
	ds_read_b128 v[174:177], v142 offset:2048
	ds_read_b128 v[178:181], v142 offset:3072
	v_lshl_add_u64 v[142:143], s[38:39], 0, v[138:139]
	s_add_i32 m0, s37, 0xc000
	ds_read_b128 v[182:185], v148
	ds_read_b128 v[186:189], v148 offset:1024
	ds_read_b128 v[190:193], v148 offset:2048
	ds_read_b128 v[194:197], v148 offset:3072
	ds_read_b128 v[198:201], v148 offset:4096
	ds_read_b128 v[202:205], v148 offset:5120
	ds_read_b128 v[206:209], v148 offset:6144
	ds_read_b128 v[210:213], v148 offset:7168
	global_load_lds_dwordx4 v[142:143], off
	v_lshl_add_u64 v[142:143], s[38:39], 0, v[140:141]
	s_add_i32 m0, s37, 0xe000
	s_nop 0
	global_load_lds_dwordx4 v[142:143], off
	s_waitcnt vmcnt(8)
	s_waitcnt lgkmcnt(0)
	s_setprio 1
	s_barrier
	v_mfma_f32_16x16x32_bf16 v[126:129], v[150:153], v[182:185], v[126:129]
	v_mfma_f32_16x16x32_bf16 v[122:125], v[158:161], v[182:185], v[122:125]
	v_mfma_f32_16x16x32_bf16 v[118:121], v[150:153], v[190:193], v[118:121]
	v_mfma_f32_16x16x32_bf16 v[110:113], v[158:161], v[190:193], v[110:113]
	v_mfma_f32_16x16x32_bf16 v[102:105], v[150:153], v[198:201], v[102:105]
	v_mfma_f32_16x16x32_bf16 v[94:97], v[158:161], v[198:201], v[94:97]
	v_mfma_f32_16x16x32_bf16 v[86:89], v[150:153], v[206:209], v[86:89]
	v_mfma_f32_16x16x32_bf16 v[78:81], v[158:161], v[206:209], v[78:81]
	v_mfma_f32_16x16x32_bf16 v[126:129], v[154:157], v[186:189], v[126:129]
	v_mfma_f32_16x16x32_bf16 v[122:125], v[162:165], v[186:189], v[122:125]
	v_mfma_f32_16x16x32_bf16 v[118:121], v[154:157], v[194:197], v[118:121]
	v_mfma_f32_16x16x32_bf16 v[110:113], v[162:165], v[194:197], v[110:113]
	v_mfma_f32_16x16x32_bf16 v[102:105], v[154:157], v[202:205], v[102:105]
	v_mfma_f32_16x16x32_bf16 v[94:97], v[162:165], v[202:205], v[94:97]
	v_mfma_f32_16x16x32_bf16 v[86:89], v[154:157], v[210:213], v[86:89]
	v_mfma_f32_16x16x32_bf16 v[78:81], v[162:165], v[210:213], v[78:81]
	s_setprio 0
	s_setprio 1
	v_mfma_f32_16x16x32_bf16 v[114:117], v[166:169], v[182:185], v[114:117]
	v_mfma_f32_16x16x32_bf16 v[106:109], v[174:177], v[182:185], v[106:109]
	v_mfma_f32_16x16x32_bf16 v[98:101], v[166:169], v[190:193], v[98:101]
	v_mfma_f32_16x16x32_bf16 v[90:93], v[174:177], v[190:193], v[90:93]
	v_mfma_f32_16x16x32_bf16 v[82:85], v[166:169], v[198:201], v[82:85]
	v_mfma_f32_16x16x32_bf16 v[74:77], v[174:177], v[198:201], v[74:77]
	v_mfma_f32_16x16x32_bf16 v[70:73], v[166:169], v[206:209], v[70:73]
	v_mfma_f32_16x16x32_bf16 v[66:69], v[174:177], v[206:209], v[66:69]
	v_mfma_f32_16x16x32_bf16 v[114:117], v[170:173], v[186:189], v[114:117]
	v_mfma_f32_16x16x32_bf16 v[106:109], v[178:181], v[186:189], v[106:109]
	v_mfma_f32_16x16x32_bf16 v[98:101], v[170:173], v[194:197], v[98:101]
	v_mfma_f32_16x16x32_bf16 v[90:93], v[178:181], v[194:197], v[90:93]
	v_mfma_f32_16x16x32_bf16 v[82:85], v[170:173], v[202:205], v[82:85]
	v_mfma_f32_16x16x32_bf16 v[74:77], v[178:181], v[202:205], v[74:77]
	v_mfma_f32_16x16x32_bf16 v[70:73], v[170:173], v[210:213], v[70:73]
	v_mfma_f32_16x16x32_bf16 v[66:69], v[178:181], v[210:213], v[66:69]
	s_setprio 0
	s_barrier
	s_add_i32 s81, s81, s66
	v_lshl_add_u64 v[142:143], s[40:41], 0, v[130:131]
	s_mov_b32 m0, s81
	ds_read_b128 v[182:185], v148 offset:16384
	ds_read_b128 v[186:189], v148 offset:17408
	ds_read_b128 v[190:193], v148 offset:18432
	ds_read_b128 v[194:197], v148 offset:19456
	ds_read_b128 v[198:201], v148 offset:20480
	ds_read_b128 v[202:205], v148 offset:21504
	ds_read_b128 v[206:209], v148 offset:22528
	ds_read_b128 v[210:213], v148 offset:23552
	global_load_lds_dwordx4 v[142:143], off
	s_add_i32 m0, s81, 0x2000
	s_add_u32 s82, s40, 0x20000
	v_lshl_add_u64 v[214:215], s[40:41], 0, v[136:137]
	s_addc_u32 s83, s41, 0
	s_add_i32 s81, s84, s66
	global_load_lds_dwordx4 v[214:215], off
	v_lshl_add_u64 v[216:217], s[82:83], 0, v[130:131]
	s_mov_b32 m0, s81
	v_lshl_add_u64 v[218:219], s[42:43], 0, v[134:135]
	global_load_lds_dwordx4 v[216:217], off
	v_lshl_add_u64 v[216:217], s[82:83], 0, v[136:137]
	s_add_i32 m0, s81, 0x2000
	s_nop 0
	global_load_lds_dwordx4 v[216:217], off
	v_lshl_add_u64 v[216:217], s[42:43], 0, v[132:133]
	s_mov_b32 m0, s37
	s_nop 0
	global_load_lds_dwordx4 v[216:217], off
	s_mov_b32 m0, s67
	s_nop 0
	global_load_lds_dwordx4 v[218:219], off
	s_waitcnt vmcnt(8)
	s_waitcnt lgkmcnt(0)
	s_setprio 1
	s_barrier
	v_mfma_f32_16x16x32_bf16 v[62:65], v[150:153], v[182:185], v[62:65]
	v_mfma_f32_16x16x32_bf16 v[58:61], v[158:161], v[182:185], v[58:61]
	v_mfma_f32_16x16x32_bf16 v[54:57], v[150:153], v[190:193], v[54:57]
	v_mfma_f32_16x16x32_bf16 v[46:49], v[158:161], v[190:193], v[46:49]
	v_mfma_f32_16x16x32_bf16 v[38:41], v[150:153], v[198:201], v[38:41]
	v_mfma_f32_16x16x32_bf16 v[30:33], v[158:161], v[198:201], v[30:33]
	v_mfma_f32_16x16x32_bf16 v[22:25], v[150:153], v[206:209], v[22:25]
	v_mfma_f32_16x16x32_bf16 v[14:17], v[158:161], v[206:209], v[14:17]
	v_mfma_f32_16x16x32_bf16 v[62:65], v[154:157], v[186:189], v[62:65]
	v_mfma_f32_16x16x32_bf16 v[58:61], v[162:165], v[186:189], v[58:61]
	v_mfma_f32_16x16x32_bf16 v[54:57], v[154:157], v[194:197], v[54:57]
	v_mfma_f32_16x16x32_bf16 v[46:49], v[162:165], v[194:197], v[46:49]
	v_mfma_f32_16x16x32_bf16 v[38:41], v[154:157], v[202:205], v[38:41]
	v_mfma_f32_16x16x32_bf16 v[30:33], v[162:165], v[202:205], v[30:33]
	v_mfma_f32_16x16x32_bf16 v[22:25], v[154:157], v[210:213], v[22:25]
	v_mfma_f32_16x16x32_bf16 v[14:17], v[162:165], v[210:213], v[14:17]
	s_setprio 0
	s_setprio 1
	v_mfma_f32_16x16x32_bf16 v[50:53], v[166:169], v[182:185], v[50:53]
	v_mfma_f32_16x16x32_bf16 v[42:45], v[174:177], v[182:185], v[42:45]
	v_mfma_f32_16x16x32_bf16 v[34:37], v[166:169], v[190:193], v[34:37]
	v_mfma_f32_16x16x32_bf16 v[26:29], v[174:177], v[190:193], v[26:29]
	v_mfma_f32_16x16x32_bf16 v[18:21], v[166:169], v[198:201], v[18:21]
	v_mfma_f32_16x16x32_bf16 v[10:13], v[174:177], v[198:201], v[10:13]
	v_mfma_f32_16x16x32_bf16 v[6:9], v[166:169], v[206:209], v[6:9]
	v_mfma_f32_16x16x32_bf16 v[2:5], v[174:177], v[206:209], v[2:5]
	v_mfma_f32_16x16x32_bf16 v[50:53], v[170:173], v[186:189], v[50:53]
	v_mfma_f32_16x16x32_bf16 v[42:45], v[178:181], v[186:189], v[42:45]
	v_mfma_f32_16x16x32_bf16 v[34:37], v[170:173], v[194:197], v[34:37]
	v_mfma_f32_16x16x32_bf16 v[26:29], v[178:181], v[194:197], v[26:29]
	v_mfma_f32_16x16x32_bf16 v[18:21], v[170:173], v[202:205], v[18:21]
	v_mfma_f32_16x16x32_bf16 v[10:13], v[178:181], v[202:205], v[10:13]
	v_mfma_f32_16x16x32_bf16 v[6:9], v[170:173], v[210:213], v[6:9]
	v_mfma_f32_16x16x32_bf16 v[2:5], v[178:181], v[210:213], v[2:5]
	s_setprio 0
	s_barrier
	s_add_i32 s81, 0, 0x18000
	v_add_u32_e32 v149, s81, v147
	s_add_i32 s82, 0, 0x1c000
	ds_read_b128 v[150:153], v149
	ds_read_b128 v[154:157], v149 offset:1024
	ds_read_b128 v[158:161], v149 offset:2048
	ds_read_b128 v[162:165], v149 offset:3072
	v_add_u32_e32 v149, s82, v147
	ds_read_b128 v[166:169], v149
	ds_read_b128 v[170:173], v149 offset:1024
	ds_read_b128 v[174:177], v149 offset:2048
	ds_read_b128 v[178:181], v149 offset:3072
	s_add_u32 s42, s42, 0x80000
	s_addc_u32 s43, s43, 0
	s_mov_b32 m0, s68
	v_lshl_add_u64 v[220:221], s[42:43], 0, v[132:133]
	ds_read_b128 v[182:185], v148 offset:32768
	ds_read_b128 v[186:189], v148 offset:33792
	ds_read_b128 v[190:193], v148 offset:34816
	ds_read_b128 v[194:197], v148 offset:35840
	ds_read_b128 v[198:201], v148 offset:36864
	ds_read_b128 v[202:205], v148 offset:37888
	ds_read_b128 v[206:209], v148 offset:38912
	ds_read_b128 v[210:213], v148 offset:39936
	global_load_lds_dwordx4 v[220:221], off
	v_lshl_add_u64 v[220:221], s[42:43], 0, v[134:135]
	s_mov_b32 m0, s69
	s_nop 0
	global_load_lds_dwordx4 v[220:221], off
	s_waitcnt vmcnt(8)
	s_waitcnt lgkmcnt(0)
	s_setprio 1
	s_barrier
	v_mfma_f32_16x16x32_bf16 v[126:129], v[150:153], v[182:185], v[126:129]
	v_mfma_f32_16x16x32_bf16 v[122:125], v[158:161], v[182:185], v[122:125]
	v_mfma_f32_16x16x32_bf16 v[118:121], v[150:153], v[190:193], v[118:121]
	v_mfma_f32_16x16x32_bf16 v[110:113], v[158:161], v[190:193], v[110:113]
	v_mfma_f32_16x16x32_bf16 v[102:105], v[150:153], v[198:201], v[102:105]
	v_mfma_f32_16x16x32_bf16 v[94:97], v[158:161], v[198:201], v[94:97]
	v_mfma_f32_16x16x32_bf16 v[86:89], v[150:153], v[206:209], v[86:89]
	v_mfma_f32_16x16x32_bf16 v[78:81], v[158:161], v[206:209], v[78:81]
	v_mfma_f32_16x16x32_bf16 v[126:129], v[154:157], v[186:189], v[126:129]
	v_mfma_f32_16x16x32_bf16 v[122:125], v[162:165], v[186:189], v[122:125]
	v_mfma_f32_16x16x32_bf16 v[118:121], v[154:157], v[194:197], v[118:121]
	v_mfma_f32_16x16x32_bf16 v[110:113], v[162:165], v[194:197], v[110:113]
	v_mfma_f32_16x16x32_bf16 v[102:105], v[154:157], v[202:205], v[102:105]
	v_mfma_f32_16x16x32_bf16 v[94:97], v[162:165], v[202:205], v[94:97]
	v_mfma_f32_16x16x32_bf16 v[86:89], v[154:157], v[210:213], v[86:89]
	v_mfma_f32_16x16x32_bf16 v[78:81], v[162:165], v[210:213], v[78:81]
	s_setprio 0
	s_setprio 1
	v_mfma_f32_16x16x32_bf16 v[114:117], v[166:169], v[182:185], v[114:117]
	v_mfma_f32_16x16x32_bf16 v[106:109], v[174:177], v[182:185], v[106:109]
	v_mfma_f32_16x16x32_bf16 v[98:101], v[166:169], v[190:193], v[98:101]
	v_mfma_f32_16x16x32_bf16 v[90:93], v[174:177], v[190:193], v[90:93]
	v_mfma_f32_16x16x32_bf16 v[82:85], v[166:169], v[198:201], v[82:85]
	v_mfma_f32_16x16x32_bf16 v[74:77], v[174:177], v[198:201], v[74:77]
	v_mfma_f32_16x16x32_bf16 v[70:73], v[166:169], v[206:209], v[70:73]
	v_mfma_f32_16x16x32_bf16 v[66:69], v[174:177], v[206:209], v[66:69]
	v_mfma_f32_16x16x32_bf16 v[114:117], v[170:173], v[186:189], v[114:117]
	v_mfma_f32_16x16x32_bf16 v[106:109], v[178:181], v[186:189], v[106:109]
	v_mfma_f32_16x16x32_bf16 v[98:101], v[170:173], v[194:197], v[98:101]
	v_mfma_f32_16x16x32_bf16 v[90:93], v[178:181], v[194:197], v[90:93]
	v_mfma_f32_16x16x32_bf16 v[82:85], v[170:173], v[202:205], v[82:85]
	v_mfma_f32_16x16x32_bf16 v[74:77], v[178:181], v[202:205], v[74:77]
	v_mfma_f32_16x16x32_bf16 v[70:73], v[170:173], v[210:213], v[70:73]
	v_mfma_f32_16x16x32_bf16 v[66:69], v[178:181], v[210:213], v[66:69]
	s_setprio 0
	s_barrier
	s_add_i32 s42, s81, s66
	v_lshl_add_u64 v[142:143], v[142:143], 0, s[4:5]
	s_mov_b32 m0, s42
	ds_read_b128 v[182:185], v148 offset:49152
	ds_read_b128 v[186:189], v148 offset:50176
	ds_read_b128 v[190:193], v148 offset:51200
	ds_read_b128 v[194:197], v148 offset:52224
	ds_read_b128 v[198:201], v148 offset:53248
	ds_read_b128 v[202:205], v148 offset:54272
	ds_read_b128 v[206:209], v148 offset:55296
	ds_read_b128 v[210:213], v148 offset:56320
	global_load_lds_dwordx4 v[142:143], off
	s_add_i32 m0, s42, 0x2000
	s_add_u32 s40, s40, 0x20080
	v_lshl_add_u64 v[142:143], v[214:215], 0, s[4:5]
	s_addc_u32 s41, s41, 0
	s_add_i32 s42, s82, s66
	global_load_lds_dwordx4 v[142:143], off
	v_lshl_add_u64 v[142:143], s[40:41], 0, v[130:131]
	s_mov_b32 m0, s42
	s_nop 0
	global_load_lds_dwordx4 v[142:143], off
	v_lshl_add_u64 v[142:143], s[40:41], 0, v[136:137]
	s_add_i32 m0, s42, 0x2000
	s_nop 0
	global_load_lds_dwordx4 v[142:143], off
	v_lshl_add_u64 v[142:143], v[216:217], 0, s[4:5]
	s_mov_b32 m0, s72
	s_nop 0
	global_load_lds_dwordx4 v[142:143], off
	v_lshl_add_u64 v[142:143], v[218:219], 0, s[4:5]
	s_mov_b32 m0, s73
	s_nop 0
	global_load_lds_dwordx4 v[142:143], off
	s_waitcnt vmcnt(8)
	s_waitcnt lgkmcnt(0)
	s_setprio 1
	s_barrier
	v_mfma_f32_16x16x32_bf16 v[62:65], v[150:153], v[182:185], v[62:65]
	v_mfma_f32_16x16x32_bf16 v[58:61], v[158:161], v[182:185], v[58:61]
	v_mfma_f32_16x16x32_bf16 v[54:57], v[150:153], v[190:193], v[54:57]
	v_mfma_f32_16x16x32_bf16 v[46:49], v[158:161], v[190:193], v[46:49]
	v_mfma_f32_16x16x32_bf16 v[38:41], v[150:153], v[198:201], v[38:41]
	v_mfma_f32_16x16x32_bf16 v[30:33], v[158:161], v[198:201], v[30:33]
	v_mfma_f32_16x16x32_bf16 v[22:25], v[150:153], v[206:209], v[22:25]
	v_mfma_f32_16x16x32_bf16 v[14:17], v[158:161], v[206:209], v[14:17]
	v_mfma_f32_16x16x32_bf16 v[62:65], v[154:157], v[186:189], v[62:65]
	v_mfma_f32_16x16x32_bf16 v[58:61], v[162:165], v[186:189], v[58:61]
	v_mfma_f32_16x16x32_bf16 v[54:57], v[154:157], v[194:197], v[54:57]
	v_mfma_f32_16x16x32_bf16 v[46:49], v[162:165], v[194:197], v[46:49]
	v_mfma_f32_16x16x32_bf16 v[38:41], v[154:157], v[202:205], v[38:41]
	v_mfma_f32_16x16x32_bf16 v[30:33], v[162:165], v[202:205], v[30:33]
	v_mfma_f32_16x16x32_bf16 v[22:25], v[154:157], v[210:213], v[22:25]
	v_mfma_f32_16x16x32_bf16 v[14:17], v[162:165], v[210:213], v[14:17]
	s_setprio 0
	s_setprio 1
	v_mfma_f32_16x16x32_bf16 v[50:53], v[166:169], v[182:185], v[50:53]
	v_mfma_f32_16x16x32_bf16 v[42:45], v[174:177], v[182:185], v[42:45]
	v_mfma_f32_16x16x32_bf16 v[34:37], v[166:169], v[190:193], v[34:37]
	v_mfma_f32_16x16x32_bf16 v[26:29], v[174:177], v[190:193], v[26:29]
	v_mfma_f32_16x16x32_bf16 v[18:21], v[166:169], v[198:201], v[18:21]
	v_mfma_f32_16x16x32_bf16 v[10:13], v[174:177], v[198:201], v[10:13]
	v_mfma_f32_16x16x32_bf16 v[6:9], v[166:169], v[206:209], v[6:9]
	v_mfma_f32_16x16x32_bf16 v[2:5], v[174:177], v[206:209], v[2:5]
	v_mfma_f32_16x16x32_bf16 v[50:53], v[170:173], v[186:189], v[50:53]
	v_mfma_f32_16x16x32_bf16 v[42:45], v[178:181], v[186:189], v[42:45]
	v_mfma_f32_16x16x32_bf16 v[34:37], v[170:173], v[194:197], v[34:37]
	v_mfma_f32_16x16x32_bf16 v[26:29], v[178:181], v[194:197], v[26:29]
	v_mfma_f32_16x16x32_bf16 v[18:21], v[170:173], v[202:205], v[18:21]
	v_mfma_f32_16x16x32_bf16 v[10:13], v[178:181], v[202:205], v[10:13]
	v_mfma_f32_16x16x32_bf16 v[6:9], v[170:173], v[210:213], v[6:9]
	v_mfma_f32_16x16x32_bf16 v[2:5], v[178:181], v[210:213], v[2:5]
	s_setprio 0
	s_barrier
	s_add_i32 s80, s80, 2
	s_add_u32 s38, s38, 0x100
	s_addc_u32 s39, s39, 0
	s_add_u32 s78, s78, 0x100
	s_addc_u32 s79, s79, 0
	s_cmp_gt_u32 s80, 5
	s_cbranch_scc0 .LBB0_292
	s_and_b64 vcc, exec, s[22:23]
	s_cbranch_vccz .LBB0_295
	s_barrier

.LBB0_307:
	ds_read_b128 v[26:29], v191
	ds_read_b128 v[30:33], v191 offset:1024
	ds_read_b128 v[18:21], v191 offset:2048
	ds_read_b128 v[22:25], v191 offset:3072
	ds_read_b128 v[10:13], v192
	ds_read_b128 v[14:17], v192 offset:1024
	ds_read_b128 v[2:5], v192 offset:2048
	ds_read_b128 v[6:9], v192 offset:3072
	s_add_u32 s26, s24, 0xfffe0080
	s_addc_u32 s27, s25, -1
	s_cmp_eq_u32 s54, 4
	s_cselect_b32 s29, s17, s27
	s_cselect_b32 s28, s50, s26
	s_cselect_b32 s27, s15, s53
	s_cselect_b32 s26, s51, s52
	v_lshl_add_u64 v[218:219], s[24:25], 0, v[170:171]
	s_add_i32 m0, s23, 0xc000
	ds_read_b128 v[178:181], v193
	ds_read_b128 v[182:185], v193 offset:1024
	ds_read_b128 v[194:197], v193 offset:2048
	ds_read_b128 v[198:201], v193 offset:3072
	ds_read_b128 v[202:205], v193 offset:4096
	ds_read_b128 v[206:209], v193 offset:5120
	ds_read_b128 v[210:213], v193 offset:6144
	ds_read_b128 v[214:217], v193 offset:7168
	global_load_lds_dwordx4 v[218:219], off
	v_lshl_add_u64 v[218:219], s[24:25], 0, v[172:173]
	s_add_i32 m0, s23, 0xe000
	s_nop 0
	global_load_lds_dwordx4 v[218:219], off
	s_waitcnt vmcnt(8)
	s_waitcnt lgkmcnt(0)
	s_setprio 1
	s_barrier
	v_mfma_scale_f32_16x16x128_f8f6f4 v[158:161], v[26:33], v[178:185], v[158:161], v187, v187 op_sel_hi:[0,0,0]
	v_mfma_scale_f32_16x16x128_f8f6f4 v[154:157], v[18:25], v[178:185], v[154:157], v187, v187 op_sel_hi:[0,0,0]
	v_mfma_scale_f32_16x16x128_f8f6f4 v[150:153], v[26:33], v[194:201], v[150:153], v187, v187 op_sel_hi:[0,0,0]
	v_mfma_scale_f32_16x16x128_f8f6f4 v[142:145], v[18:25], v[194:201], v[142:145], v187, v187 op_sel_hi:[0,0,0]
	v_mfma_scale_f32_16x16x128_f8f6f4 v[134:137], v[26:33], v[202:209], v[134:137], v187, v187 op_sel_hi:[0,0,0]
	v_mfma_scale_f32_16x16x128_f8f6f4 v[126:129], v[18:25], v[202:209], v[126:129], v187, v187 op_sel_hi:[0,0,0]
	v_mfma_scale_f32_16x16x128_f8f6f4 v[118:121], v[26:33], v[210:217], v[118:121], v187, v187 op_sel_hi:[0,0,0]
	v_mfma_scale_f32_16x16x128_f8f6f4 v[110:113], v[18:25], v[210:217], v[110:113], v187, v187 op_sel_hi:[0,0,0]
	s_setprio 0
	s_setprio 1
	v_mfma_scale_f32_16x16x128_f8f6f4 v[146:149], v[10:17], v[178:185], v[146:149], v187, v187 op_sel_hi:[0,0,0]
	v_mfma_scale_f32_16x16x128_f8f6f4 v[138:141], v[2:9], v[178:185], v[138:141], v187, v187 op_sel_hi:[0,0,0]
	v_mfma_scale_f32_16x16x128_f8f6f4 v[130:133], v[10:17], v[194:201], v[130:133], v187, v187 op_sel_hi:[0,0,0]
	v_mfma_scale_f32_16x16x128_f8f6f4 v[122:125], v[2:9], v[194:201], v[122:125], v187, v187 op_sel_hi:[0,0,0]
	v_mfma_scale_f32_16x16x128_f8f6f4 v[114:117], v[10:17], v[202:209], v[114:117], v187, v187 op_sel_hi:[0,0,0]
	v_mfma_scale_f32_16x16x128_f8f6f4 v[106:109], v[2:9], v[202:209], v[106:109], v187, v187 op_sel_hi:[0,0,0]
	v_mfma_scale_f32_16x16x128_f8f6f4 v[102:105], v[10:17], v[210:217], v[102:105], v187, v187 op_sel_hi:[0,0,0]
	v_mfma_scale_f32_16x16x128_f8f6f4 v[98:101], v[2:9], v[210:217], v[98:101], v187, v187 op_sel_hi:[0,0,0]
	s_setprio 0
	s_barrier
	s_add_i32 s55, s46, s33
	v_lshl_add_u64 v[178:179], s[26:27], 0, v[166:167]
	s_mov_b32 m0, s55
	ds_read_b128 v[194:197], v193 offset:16384
	ds_read_b128 v[198:201], v193 offset:17408
	ds_read_b128 v[202:205], v193 offset:18432
	ds_read_b128 v[206:209], v193 offset:19456
	ds_read_b128 v[210:213], v193 offset:20480
	ds_read_b128 v[214:217], v193 offset:21504
	ds_read_b128 v[218:221], v193 offset:22528
	ds_read_b128 v[222:225], v193 offset:23552
	global_load_lds_dwordx4 v[178:179], off
	s_add_i32 m0, s55, 0x2000
	s_add_u32 s60, s26, 0x20000
	v_lshl_add_u64 v[180:181], s[26:27], 0, v[162:163]
	s_addc_u32 s61, s27, 0
	s_add_i32 s55, s47, s33
	global_load_lds_dwordx4 v[180:181], off
	v_lshl_add_u64 v[182:183], s[60:61], 0, v[166:167]
	s_mov_b32 m0, s55
	v_lshl_add_u64 v[184:185], s[28:29], 0, v[164:165]
	global_load_lds_dwordx4 v[182:183], off
	v_lshl_add_u64 v[182:183], s[60:61], 0, v[162:163]
	s_add_i32 m0, s55, 0x2000
	s_nop 0
	global_load_lds_dwordx4 v[182:183], off
	v_lshl_add_u64 v[182:183], s[28:29], 0, v[168:169]
	s_mov_b32 m0, s23
	s_nop 0
	global_load_lds_dwordx4 v[182:183], off
	s_mov_b32 m0, s38
	s_nop 0
	global_load_lds_dwordx4 v[184:185], off
	s_waitcnt vmcnt(8)
	s_waitcnt lgkmcnt(0)
	s_setprio 1
	s_barrier
	v_mfma_scale_f32_16x16x128_f8f6f4 v[94:97], v[26:33], v[194:201], v[94:97], v187, v187 op_sel_hi:[0,0,0]
	v_mfma_scale_f32_16x16x128_f8f6f4 v[90:93], v[18:25], v[194:201], v[90:93], v187, v187 op_sel_hi:[0,0,0]
	v_mfma_scale_f32_16x16x128_f8f6f4 v[86:89], v[26:33], v[202:209], v[86:89], v187, v187 op_sel_hi:[0,0,0]
	v_mfma_scale_f32_16x16x128_f8f6f4 v[78:81], v[18:25], v[202:209], v[78:81], v187, v187 op_sel_hi:[0,0,0]
	v_mfma_scale_f32_16x16x128_f8f6f4 v[70:73], v[26:33], v[210:217], v[70:73], v187, v187 op_sel_hi:[0,0,0]
	v_mfma_scale_f32_16x16x128_f8f6f4 v[62:65], v[18:25], v[210:217], v[62:65], v187, v187 op_sel_hi:[0,0,0]
	v_mfma_scale_f32_16x16x128_f8f6f4 v[54:57], v[26:33], v[218:225], v[54:57], v187, v187 op_sel_hi:[0,0,0]
	v_mfma_scale_f32_16x16x128_f8f6f4 v[46:49], v[18:25], v[218:225], v[46:49], v187, v187 op_sel_hi:[0,0,0]
	s_setprio 0
	s_setprio 1
	v_mfma_scale_f32_16x16x128_f8f6f4 v[82:85], v[10:17], v[194:201], v[82:85], v187, v187 op_sel_hi:[0,0,0]
	v_mfma_scale_f32_16x16x128_f8f6f4 v[74:77], v[2:9], v[194:201], v[74:77], v187, v187 op_sel_hi:[0,0,0]
	v_mfma_scale_f32_16x16x128_f8f6f4 v[66:69], v[10:17], v[202:209], v[66:69], v187, v187 op_sel_hi:[0,0,0]
	v_mfma_scale_f32_16x16x128_f8f6f4 v[58:61], v[2:9], v[202:209], v[58:61], v187, v187 op_sel_hi:[0,0,0]
	v_mfma_scale_f32_16x16x128_f8f6f4 v[50:53], v[10:17], v[210:217], v[50:53], v187, v187 op_sel_hi:[0,0,0]
	v_mfma_scale_f32_16x16x128_f8f6f4 v[42:45], v[2:9], v[210:217], v[42:45], v187, v187 op_sel_hi:[0,0,0]
	v_mfma_scale_f32_16x16x128_f8f6f4 v[38:41], v[10:17], v[218:225], v[38:41], v187, v187 op_sel_hi:[0,0,0]
	v_mfma_scale_f32_16x16x128_f8f6f4 v[34:37], v[2:9], v[218:225], v[34:37], v187, v187 op_sel_hi:[0,0,0]
	s_setprio 0
	s_barrier
	s_add_i32 s55, 0, 0x18000
	s_add_i32 s57, 0, 0x1c000
	v_add_u32_e32 v14, s55, v190
	v_add_u32_e32 v30, s57, v190
	ds_read_b128 v[2:5], v14
	ds_read_b128 v[6:9], v14 offset:1024
	ds_read_b128 v[10:13], v14 offset:2048
	ds_read_b128 v[14:17], v14 offset:3072
	ds_read_b128 v[18:21], v30
	ds_read_b128 v[22:25], v30 offset:1024
	ds_read_b128 v[26:29], v30 offset:2048
	ds_read_b128 v[30:33], v30 offset:3072
	s_add_u32 s28, s28, 0x20000
	s_addc_u32 s29, s29, 0
	s_mov_b32 m0, s39
	v_lshl_add_u64 v[226:227], s[28:29], 0, v[168:169]
	ds_read_b128 v[194:197], v193 offset:32768
	ds_read_b128 v[198:201], v193 offset:33792
	ds_read_b128 v[202:205], v193 offset:34816
	ds_read_b128 v[206:209], v193 offset:35840
	ds_read_b128 v[210:213], v193 offset:36864
	ds_read_b128 v[214:217], v193 offset:37888
	ds_read_b128 v[218:221], v193 offset:38912
	ds_read_b128 v[222:225], v193 offset:39936
	global_load_lds_dwordx4 v[226:227], off
	v_lshl_add_u64 v[226:227], s[28:29], 0, v[164:165]
	s_mov_b32 m0, s40
	s_nop 0
	global_load_lds_dwordx4 v[226:227], off
	s_waitcnt vmcnt(8)
	s_waitcnt lgkmcnt(0)
	s_setprio 1
	s_barrier
	v_mfma_scale_f32_16x16x128_f8f6f4 v[158:161], v[2:9], v[194:201], v[158:161], v187, v187 op_sel_hi:[0,0,0]
	v_mfma_scale_f32_16x16x128_f8f6f4 v[154:157], v[10:17], v[194:201], v[154:157], v187, v187 op_sel_hi:[0,0,0]
	v_mfma_scale_f32_16x16x128_f8f6f4 v[150:153], v[2:9], v[202:209], v[150:153], v187, v187 op_sel_hi:[0,0,0]
	v_mfma_scale_f32_16x16x128_f8f6f4 v[142:145], v[10:17], v[202:209], v[142:145], v187, v187 op_sel_hi:[0,0,0]
	v_mfma_scale_f32_16x16x128_f8f6f4 v[134:137], v[2:9], v[210:217], v[134:137], v187, v187 op_sel_hi:[0,0,0]
	v_mfma_scale_f32_16x16x128_f8f6f4 v[126:129], v[10:17], v[210:217], v[126:129], v187, v187 op_sel_hi:[0,0,0]
	v_mfma_scale_f32_16x16x128_f8f6f4 v[118:121], v[2:9], v[218:225], v[118:121], v187, v187 op_sel_hi:[0,0,0]
	v_mfma_scale_f32_16x16x128_f8f6f4 v[110:113], v[10:17], v[218:225], v[110:113], v187, v187 op_sel_hi:[0,0,0]
	s_setprio 0
	s_setprio 1
	v_mfma_scale_f32_16x16x128_f8f6f4 v[146:149], v[18:25], v[194:201], v[146:149], v187, v187 op_sel_hi:[0,0,0]
	v_mfma_scale_f32_16x16x128_f8f6f4 v[138:141], v[26:33], v[194:201], v[138:141], v187, v187 op_sel_hi:[0,0,0]
	v_mfma_scale_f32_16x16x128_f8f6f4 v[130:133], v[18:25], v[202:209], v[130:133], v187, v187 op_sel_hi:[0,0,0]
	v_mfma_scale_f32_16x16x128_f8f6f4 v[122:125], v[26:33], v[202:209], v[122:125], v187, v187 op_sel_hi:[0,0,0]
	v_mfma_scale_f32_16x16x128_f8f6f4 v[114:117], v[18:25], v[210:217], v[114:117], v187, v187 op_sel_hi:[0,0,0]
	v_mfma_scale_f32_16x16x128_f8f6f4 v[106:109], v[26:33], v[210:217], v[106:109], v187, v187 op_sel_hi:[0,0,0]
	v_mfma_scale_f32_16x16x128_f8f6f4 v[102:105], v[18:25], v[218:225], v[102:105], v187, v187 op_sel_hi:[0,0,0]
	v_mfma_scale_f32_16x16x128_f8f6f4 v[98:101], v[26:33], v[218:225], v[98:101], v187, v187 op_sel_hi:[0,0,0]
	s_setprio 0
	s_barrier
	s_add_i32 s28, s55, s33
	v_lshl_add_u64 v[178:179], v[178:179], 0, s[10:11]
	s_mov_b32 m0, s28
	ds_read_b128 v[194:197], v193 offset:49152
	ds_read_b128 v[198:201], v193 offset:50176
	ds_read_b128 v[202:205], v193 offset:51200
	ds_read_b128 v[206:209], v193 offset:52224
	ds_read_b128 v[210:213], v193 offset:53248
	ds_read_b128 v[214:217], v193 offset:54272
	ds_read_b128 v[218:221], v193 offset:55296
	ds_read_b128 v[222:225], v193 offset:56320
	global_load_lds_dwordx4 v[178:179], off
	s_add_i32 m0, s28, 0x2000
	s_add_u32 s26, s26, 0x20080
	v_lshl_add_u64 v[178:179], v[180:181], 0, s[10:11]
	s_addc_u32 s27, s27, 0
	s_add_i32 s28, s57, s33
	global_load_lds_dwordx4 v[178:179], off
	v_lshl_add_u64 v[178:179], s[26:27], 0, v[166:167]
	s_mov_b32 m0, s28
	s_nop 0
	global_load_lds_dwordx4 v[178:179], off
	v_lshl_add_u64 v[178:179], s[26:27], 0, v[162:163]
	s_add_i32 m0, s28, 0x2000
	s_nop 0
	global_load_lds_dwordx4 v[178:179], off
	v_lshl_add_u64 v[178:179], v[182:183], 0, s[10:11]
	s_mov_b32 m0, s44
	s_nop 0
	global_load_lds_dwordx4 v[178:179], off
	v_lshl_add_u64 v[178:179], v[184:185], 0, s[10:11]
	s_mov_b32 m0, s45
	s_nop 0
	global_load_lds_dwordx4 v[178:179], off
	s_waitcnt vmcnt(8)
	s_waitcnt lgkmcnt(0)
	s_setprio 1
	s_barrier
	v_mfma_scale_f32_16x16x128_f8f6f4 v[94:97], v[2:9], v[194:201], v[94:97], v187, v187 op_sel_hi:[0,0,0]
	v_mfma_scale_f32_16x16x128_f8f6f4 v[90:93], v[10:17], v[194:201], v[90:93], v187, v187 op_sel_hi:[0,0,0]
	v_mfma_scale_f32_16x16x128_f8f6f4 v[86:89], v[2:9], v[202:209], v[86:89], v187, v187 op_sel_hi:[0,0,0]
	v_mfma_scale_f32_16x16x128_f8f6f4 v[78:81], v[10:17], v[202:209], v[78:81], v187, v187 op_sel_hi:[0,0,0]
	v_mfma_scale_f32_16x16x128_f8f6f4 v[70:73], v[2:9], v[210:217], v[70:73], v187, v187 op_sel_hi:[0,0,0]
	v_mfma_scale_f32_16x16x128_f8f6f4 v[62:65], v[10:17], v[210:217], v[62:65], v187, v187 op_sel_hi:[0,0,0]
	v_mfma_scale_f32_16x16x128_f8f6f4 v[54:57], v[2:9], v[218:225], v[54:57], v187, v187 op_sel_hi:[0,0,0]
	v_mfma_scale_f32_16x16x128_f8f6f4 v[46:49], v[10:17], v[218:225], v[46:49], v187, v187 op_sel_hi:[0,0,0]
	s_setprio 0
	s_setprio 1
	v_mfma_scale_f32_16x16x128_f8f6f4 v[82:85], v[18:25], v[194:201], v[82:85], v187, v187 op_sel_hi:[0,0,0]
	v_mfma_scale_f32_16x16x128_f8f6f4 v[74:77], v[26:33], v[194:201], v[74:77], v187, v187 op_sel_hi:[0,0,0]
	v_mfma_scale_f32_16x16x128_f8f6f4 v[66:69], v[18:25], v[202:209], v[66:69], v187, v187 op_sel_hi:[0,0,0]
	v_mfma_scale_f32_16x16x128_f8f6f4 v[58:61], v[26:33], v[202:209], v[58:61], v187, v187 op_sel_hi:[0,0,0]
	v_mfma_scale_f32_16x16x128_f8f6f4 v[50:53], v[18:25], v[210:217], v[50:53], v187, v187 op_sel_hi:[0,0,0]
	v_mfma_scale_f32_16x16x128_f8f6f4 v[42:45], v[26:33], v[210:217], v[42:45], v187, v187 op_sel_hi:[0,0,0]
	v_mfma_scale_f32_16x16x128_f8f6f4 v[38:41], v[18:25], v[218:225], v[38:41], v187, v187 op_sel_hi:[0,0,0]
	v_mfma_scale_f32_16x16x128_f8f6f4 v[34:37], v[26:33], v[218:225], v[34:37], v187, v187 op_sel_hi:[0,0,0]
	s_setprio 0
	s_barrier
	s_add_i32 s54, s54, 2
	s_add_u32 s24, s24, 0x100
	s_addc_u32 s25, s25, 0
	s_add_u32 s52, s52, 0x100
	s_addc_u32 s53, s53, 0
	s_cmp_gt_u32 s54, 5
	s_cbranch_scc0 .LBB0_307
	s_and_b64 vcc, exec, s[12:13]
	s_cbranch_vccz .LBB0_310
	s_barrier

.LBB0_322:
	ds_read_b128 v[26:29], v169
	ds_read_b128 v[30:33], v169 offset:1024
	ds_read_b128 v[42:45], v169 offset:2048
	ds_read_b128 v[46:49], v169 offset:3072
	ds_read_b128 v[10:13], v170
	ds_read_b128 v[14:17], v170 offset:1024
	ds_read_b128 v[2:5], v170 offset:2048
	ds_read_b128 v[6:9], v170 offset:3072
	s_ashr_i32 s41, s40, 31
	s_lshl_b64 s[6:7], s[40:41], 17
	s_add_u32 s42, s34, s6
	s_addc_u32 s43, s35, s7
	s_and_b64 s[6:7], s[4:5], exec
	s_cselect_b32 s21, s43, s23
	s_cselect_b32 s20, s42, s22
	s_ashr_i32 s27, s26, 31
	s_lshl_b64 s[6:7], s[26:27], 17
	s_add_u32 s44, s36, s6
	s_addc_u32 s45, s37, s7
	s_and_b64 s[6:7], s[4:5], exec
	s_cselect_b32 s7, s45, s31
	s_cselect_b32 s6, s44, s30
	s_add_u32 s66, s22, 0x10080
	s_addc_u32 s67, s23, 0
	s_mov_b32 m0, s62
	v_lshl_add_u64 v[22:23], s[66:67], 0, v[152:153]
	ds_read_b128 v[34:37], v171
	ds_read_b128 v[38:41], v171 offset:1024
	ds_read_b128 v[50:53], v171 offset:2048
	ds_read_b128 v[54:57], v171 offset:3072
	ds_read_b128 v[58:61], v171 offset:4096
	ds_read_b128 v[62:65], v171 offset:5120
	ds_read_b128 v[66:69], v171 offset:6144
	ds_read_b128 v[70:73], v171 offset:7168
	global_load_lds_dwordx4 v[22:23], off
	v_lshl_add_u64 v[22:23], s[66:67], 0, v[148:149]
	s_mov_b32 m0, s63
	s_nop 0
	global_load_lds_dwordx4 v[22:23], off
	s_waitcnt vmcnt(8)
	s_waitcnt lgkmcnt(0)
	s_barrier
	s_setprio 1
	v_mov_b64_e32 v[132:133], v[20:21]
	v_mov_b64_e32 v[136:137], v[20:21]
	v_mov_b64_e32 v[116:117], v[20:21]
	v_mov_b64_e32 v[120:121], v[20:21]
	v_mov_b64_e32 v[100:101], v[20:21]
	v_mov_b64_e32 v[104:105], v[20:21]
	v_mov_b64_e32 v[84:85], v[20:21]
	v_mov_b64_e32 v[88:89], v[20:21]
	v_mov_b64_e32 v[130:131], v[18:19]
	v_mov_b64_e32 v[134:135], v[18:19]
	v_mov_b64_e32 v[114:115], v[18:19]
	v_mov_b64_e32 v[118:119], v[18:19]
	v_mov_b64_e32 v[98:99], v[18:19]
	v_mov_b64_e32 v[102:103], v[18:19]
	v_mov_b64_e32 v[82:83], v[18:19]
	v_mov_b64_e32 v[86:87], v[18:19]
	s_waitcnt lgkmcnt(0)
	v_mfma_scale_f32_16x16x128_f8f6f4 v[130:133], v[26:33], v[34:41], v[130:133], v186, v186 op_sel_hi:[0,0,0]
	v_mfma_scale_f32_16x16x128_f8f6f4 v[134:137], v[42:49], v[34:41], v[134:137], v186, v186 op_sel_hi:[0,0,0]
	v_mfma_scale_f32_16x16x128_f8f6f4 v[114:117], v[26:33], v[50:57], v[114:117], v186, v186 op_sel_hi:[0,0,0]
	v_mfma_scale_f32_16x16x128_f8f6f4 v[118:121], v[42:49], v[50:57], v[118:121], v186, v186 op_sel_hi:[0,0,0]
	v_mfma_scale_f32_16x16x128_f8f6f4 v[98:101], v[26:33], v[58:65], v[98:101], v186, v186 op_sel_hi:[0,0,0]
	v_mfma_scale_f32_16x16x128_f8f6f4 v[102:105], v[42:49], v[58:65], v[102:105], v186, v186 op_sel_hi:[0,0,0]
	v_mfma_scale_f32_16x16x128_f8f6f4 v[82:85], v[26:33], v[66:73], v[82:85], v186, v186 op_sel_hi:[0,0,0]
	v_mfma_scale_f32_16x16x128_f8f6f4 v[86:89], v[42:49], v[66:73], v[86:89], v186, v186 op_sel_hi:[0,0,0]
	s_setprio 0
	s_setprio 1
	v_mov_b64_e32 v[140:141], v[20:21]
	v_mov_b64_e32 v[144:145], v[20:21]
	v_mov_b64_e32 v[124:125], v[20:21]
	v_mov_b64_e32 v[128:129], v[20:21]
	v_mov_b64_e32 v[108:109], v[20:21]
	v_mov_b64_e32 v[112:113], v[20:21]
	v_mov_b64_e32 v[92:93], v[20:21]
	v_mov_b64_e32 v[96:97], v[20:21]
	v_mov_b64_e32 v[138:139], v[18:19]
	v_mov_b64_e32 v[142:143], v[18:19]
	v_mov_b64_e32 v[122:123], v[18:19]
	v_mov_b64_e32 v[126:127], v[18:19]
	v_mov_b64_e32 v[106:107], v[18:19]
	v_mov_b64_e32 v[110:111], v[18:19]
	v_mov_b64_e32 v[90:91], v[18:19]
	v_mov_b64_e32 v[94:95], v[18:19]
	v_mfma_scale_f32_16x16x128_f8f6f4 v[138:141], v[10:17], v[34:41], v[138:141], v186, v186 op_sel_hi:[0,0,0]
	v_mfma_scale_f32_16x16x128_f8f6f4 v[142:145], v[2:9], v[34:41], v[142:145], v186, v186 op_sel_hi:[0,0,0]
	v_mfma_scale_f32_16x16x128_f8f6f4 v[122:125], v[10:17], v[50:57], v[122:125], v186, v186 op_sel_hi:[0,0,0]
	v_mfma_scale_f32_16x16x128_f8f6f4 v[126:129], v[2:9], v[50:57], v[126:129], v186, v186 op_sel_hi:[0,0,0]
	v_mfma_scale_f32_16x16x128_f8f6f4 v[106:109], v[10:17], v[58:65], v[106:109], v186, v186 op_sel_hi:[0,0,0]
	v_mfma_scale_f32_16x16x128_f8f6f4 v[110:113], v[2:9], v[58:65], v[110:113], v186, v186 op_sel_hi:[0,0,0]
	v_mfma_scale_f32_16x16x128_f8f6f4 v[90:93], v[10:17], v[66:73], v[90:93], v186, v186 op_sel_hi:[0,0,0]
	v_mfma_scale_f32_16x16x128_f8f6f4 v[94:97], v[2:9], v[66:73], v[94:97], v186, v186 op_sel_hi:[0,0,0]
	s_setprio 0
	s_barrier
	v_lshl_add_u64 v[158:159], s[30:31], 0, v[150:151]
	s_add_i32 s1, s64, 0x2000
	s_mov_b32 m0, s64
	v_lshl_add_u64 v[22:23], v[158:159], 0, s[18:19]
	v_lshl_add_u64 v[160:161], s[30:31], 0, v[146:147]
	s_add_u32 s66, s30, 0x10100
	ds_read_b128 v[58:61], v171 offset:16384
	ds_read_b128 v[62:65], v171 offset:17408
	ds_read_b128 v[174:177], v171 offset:18432
	ds_read_b128 v[178:181], v171 offset:19456
	ds_read_b128 v[188:191], v171 offset:20480
	ds_read_b128 v[192:195], v171 offset:21504
	ds_read_b128 v[196:199], v171 offset:22528
	ds_read_b128 v[200:203], v171 offset:23552
	global_load_lds_dwordx4 v[22:23], off
	v_lshl_add_u64 v[22:23], v[160:161], 0, s[18:19]
	s_mov_b32 m0, s1
	s_addc_u32 s67, s31, 0
	s_add_i32 s27, s59, s33
	global_load_lds_dwordx4 v[22:23], off
	v_lshl_add_u64 v[22:23], s[66:67], 0, v[150:151]
	s_mov_b32 m0, s27
	s_add_i32 s41, s27, 0x2000
	global_load_lds_dwordx4 v[22:23], off
	v_lshl_add_u64 v[22:23], s[66:67], 0, v[146:147]
	s_mov_b32 m0, s41
	v_lshl_add_u64 v[162:163], s[22:23], 0, v[152:153]
	global_load_lds_dwordx4 v[22:23], off
	v_lshl_add_u64 v[22:23], v[162:163], 0, s[18:19]
	s_mov_b32 m0, s39
	v_lshl_add_u64 v[164:165], s[22:23], 0, v[148:149]
	global_load_lds_dwordx4 v[22:23], off
	v_lshl_add_u64 v[22:23], v[164:165], 0, s[18:19]
	s_mov_b32 m0, s46
	s_nop 0
	global_load_lds_dwordx4 v[22:23], off
	s_waitcnt vmcnt(8)
	s_waitcnt lgkmcnt(0)
	s_barrier
	s_setprio 1
	v_mov_b64_e32 v[68:69], v[20:21]
	v_mov_b64_e32 v[72:73], v[20:21]
	v_mov_b64_e32 v[52:53], v[20:21]
	v_mov_b64_e32 v[56:57], v[20:21]
	v_mov_b64_e32 v[36:37], v[20:21]
	v_mov_b64_e32 v[40:41], v[20:21]
	v_mov_b64_e32 v[24:25], v[20:21]
	v_mov_b64_e32 v[66:67], v[18:19]
	v_mov_b64_e32 v[70:71], v[18:19]
	v_mov_b64_e32 v[50:51], v[18:19]
	v_mov_b64_e32 v[54:55], v[18:19]
	v_mov_b64_e32 v[34:35], v[18:19]
	v_mov_b64_e32 v[38:39], v[18:19]
	v_mov_b64_e32 v[22:23], v[18:19]
	s_waitcnt lgkmcnt(0)
	v_mfma_scale_f32_16x16x128_f8f6f4 v[66:69], v[26:33], v[58:65], v[66:69], v186, v186 op_sel_hi:[0,0,0]
	v_mfma_scale_f32_16x16x128_f8f6f4 v[70:73], v[42:49], v[58:65], v[70:73], v186, v186 op_sel_hi:[0,0,0]
	v_mfma_scale_f32_16x16x128_f8f6f4 v[50:53], v[26:33], v[174:181], v[50:53], v186, v186 op_sel_hi:[0,0,0]
	v_mfma_scale_f32_16x16x128_f8f6f4 v[54:57], v[42:49], v[174:181], v[54:57], v186, v186 op_sel_hi:[0,0,0]
	v_mfma_scale_f32_16x16x128_f8f6f4 v[34:37], v[26:33], v[188:195], v[34:37], v186, v186 op_sel_hi:[0,0,0]
	v_mfma_scale_f32_16x16x128_f8f6f4 v[38:41], v[42:49], v[188:195], v[38:41], v186, v186 op_sel_hi:[0,0,0]
	v_mfma_scale_f32_16x16x128_f8f6f4 v[22:25], v[26:33], v[196:203], v[22:25], v186, v186 op_sel_hi:[0,0,0]
	v_mov_b64_e32 v[28:29], v[20:21]
	v_mov_b64_e32 v[26:27], v[18:19]
	v_mfma_scale_f32_16x16x128_f8f6f4 v[26:29], v[42:49], v[196:203], v[26:29], v186, v186 op_sel_hi:[0,0,0]
	s_setprio 0
	s_setprio 1
	v_mov_b64_e32 v[76:77], v[20:21]
	v_mov_b64_e32 v[80:81], v[20:21]
	v_mov_b64_e32 v[74:75], v[18:19]
	v_mov_b64_e32 v[78:79], v[18:19]
	v_mfma_scale_f32_16x16x128_f8f6f4 v[74:77], v[10:17], v[58:65], v[74:77], v186, v186 op_sel_hi:[0,0,0]
	v_mfma_scale_f32_16x16x128_f8f6f4 v[78:81], v[2:9], v[58:65], v[78:81], v186, v186 op_sel_hi:[0,0,0]
	v_mov_b64_e32 v[60:61], v[20:21]
	v_mov_b64_e32 v[64:65], v[20:21]
	v_mov_b64_e32 v[44:45], v[20:21]
	v_mov_b64_e32 v[48:49], v[20:21]
	v_mov_b64_e32 v[32:33], v[20:21]
	v_mov_b64_e32 v[58:59], v[18:19]
	v_mov_b64_e32 v[62:63], v[18:19]
	v_mov_b64_e32 v[42:43], v[18:19]
	v_mov_b64_e32 v[46:47], v[18:19]
	v_mov_b64_e32 v[30:31], v[18:19]
	v_mfma_scale_f32_16x16x128_f8f6f4 v[58:61], v[10:17], v[174:181], v[58:61], v186, v186 op_sel_hi:[0,0,0]
	v_mfma_scale_f32_16x16x128_f8f6f4 v[62:65], v[2:9], v[174:181], v[62:65], v186, v186 op_sel_hi:[0,0,0]
	v_mfma_scale_f32_16x16x128_f8f6f4 v[42:45], v[10:17], v[188:195], v[42:45], v186, v186 op_sel_hi:[0,0,0]
	v_mfma_scale_f32_16x16x128_f8f6f4 v[46:49], v[2:9], v[188:195], v[46:49], v186, v186 op_sel_hi:[0,0,0]
	v_mfma_scale_f32_16x16x128_f8f6f4 v[30:33], v[10:17], v[196:203], v[30:33], v186, v186 op_sel_hi:[0,0,0]
	v_mov_b64_e32 v[10:11], v[18:19]
	v_mov_b64_e32 v[12:13], v[20:21]
	v_mfma_scale_f32_16x16x128_f8f6f4 v[10:13], v[2:9], v[196:203], v[10:13], v186, v186 op_sel_hi:[0,0,0]
	s_setprio 0
	s_barrier
	s_add_i32 s68, 0, 0x18000
	s_add_i32 s70, 0, 0x1c000
	v_add_u32_e32 v187, s68, v168
	v_add_u32_e32 v236, s70, v168
	ds_read_b128 v[2:5], v187
	ds_read_b128 v[6:9], v187 offset:1024
	ds_read_b128 v[174:177], v187 offset:2048
	ds_read_b128 v[178:181], v187 offset:3072
	ds_read_b128 v[188:191], v236
	ds_read_b128 v[192:195], v236 offset:1024
	ds_read_b128 v[196:199], v236 offset:2048
	ds_read_b128 v[200:203], v236 offset:3072
	s_add_u32 s66, s22, 0x10100
	s_addc_u32 s67, s23, 0
	s_mov_b32 m0, s47
	v_lshl_add_u64 v[14:15], s[66:67], 0, v[152:153]
	ds_read_b128 v[204:207], v171 offset:32768
	ds_read_b128 v[208:211], v171 offset:33792
	ds_read_b128 v[212:215], v171 offset:34816
	ds_read_b128 v[216:219], v171 offset:35840
	ds_read_b128 v[220:223], v171 offset:36864
	ds_read_b128 v[224:227], v171 offset:37888
	ds_read_b128 v[228:231], v171 offset:38912
	ds_read_b128 v[232:235], v171 offset:39936
	global_load_lds_dwordx4 v[14:15], off
	v_lshl_add_u64 v[14:15], s[66:67], 0, v[148:149]
	s_mov_b32 m0, s48
	s_nop 0
	global_load_lds_dwordx4 v[14:15], off
	s_waitcnt vmcnt(8)
	s_waitcnt lgkmcnt(0)
	s_setprio 1
	s_barrier
	v_mfma_scale_f32_16x16x128_f8f6f4 v[130:133], v[2:9], v[204:211], v[130:133], v186, v186 op_sel_hi:[0,0,0]
	v_mfma_scale_f32_16x16x128_f8f6f4 v[134:137], v[174:181], v[204:211], v[134:137], v186, v186 op_sel_hi:[0,0,0]
	v_mfma_scale_f32_16x16x128_f8f6f4 v[114:117], v[2:9], v[212:219], v[114:117], v186, v186 op_sel_hi:[0,0,0]
	v_mfma_scale_f32_16x16x128_f8f6f4 v[118:121], v[174:181], v[212:219], v[118:121], v186, v186 op_sel_hi:[0,0,0]
	v_mfma_scale_f32_16x16x128_f8f6f4 v[98:101], v[2:9], v[220:227], v[98:101], v186, v186 op_sel_hi:[0,0,0]
	v_mfma_scale_f32_16x16x128_f8f6f4 v[102:105], v[174:181], v[220:227], v[102:105], v186, v186 op_sel_hi:[0,0,0]
	v_mfma_scale_f32_16x16x128_f8f6f4 v[82:85], v[2:9], v[228:235], v[82:85], v186, v186 op_sel_hi:[0,0,0]
	v_mfma_scale_f32_16x16x128_f8f6f4 v[86:89], v[174:181], v[228:235], v[86:89], v186, v186 op_sel_hi:[0,0,0]
	s_setprio 0
	s_setprio 1
	v_mfma_scale_f32_16x16x128_f8f6f4 v[138:141], v[188:195], v[204:211], v[138:141], v186, v186 op_sel_hi:[0,0,0]
	v_mfma_scale_f32_16x16x128_f8f6f4 v[142:145], v[196:203], v[204:211], v[142:145], v186, v186 op_sel_hi:[0,0,0]
	v_mfma_scale_f32_16x16x128_f8f6f4 v[122:125], v[188:195], v[212:219], v[122:125], v186, v186 op_sel_hi:[0,0,0]
	v_mfma_scale_f32_16x16x128_f8f6f4 v[126:129], v[196:203], v[212:219], v[126:129], v186, v186 op_sel_hi:[0,0,0]
	v_mfma_scale_f32_16x16x128_f8f6f4 v[106:109], v[188:195], v[220:227], v[106:109], v186, v186 op_sel_hi:[0,0,0]
	v_mfma_scale_f32_16x16x128_f8f6f4 v[110:113], v[196:203], v[220:227], v[110:113], v186, v186 op_sel_hi:[0,0,0]
	v_mfma_scale_f32_16x16x128_f8f6f4 v[90:93], v[188:195], v[228:235], v[90:93], v186, v186 op_sel_hi:[0,0,0]
	v_mfma_scale_f32_16x16x128_f8f6f4 v[94:97], v[196:203], v[228:235], v[94:97], v186, v186 op_sel_hi:[0,0,0]
	s_setprio 0
	s_barrier
	s_add_i32 s67, s68, s33
	s_add_i32 s66, s67, 0x2000
	v_lshl_add_u64 v[14:15], v[158:159], 0, s[24:25]
	s_mov_b32 m0, s67
	s_add_u32 s68, s30, 0x10180
	ds_read_b128 v[204:207], v171 offset:49152
	ds_read_b128 v[208:211], v171 offset:50176
	ds_read_b128 v[212:215], v171 offset:51200
	ds_read_b128 v[216:219], v171 offset:52224
	ds_read_b128 v[220:223], v171 offset:53248
	ds_read_b128 v[224:227], v171 offset:54272
	ds_read_b128 v[228:231], v171 offset:55296
	ds_read_b128 v[232:235], v171 offset:56320
	global_load_lds_dwordx4 v[14:15], off
	v_lshl_add_u64 v[14:15], v[160:161], 0, s[24:25]
	s_mov_b32 m0, s66
	s_addc_u32 s69, s31, 0
	s_add_i32 s30, s70, s33
	global_load_lds_dwordx4 v[14:15], off
	v_lshl_add_u64 v[14:15], s[68:69], 0, v[150:151]
	s_mov_b32 m0, s30
	s_add_i32 s31, s30, 0x2000
	global_load_lds_dwordx4 v[14:15], off
	v_lshl_add_u64 v[14:15], s[68:69], 0, v[146:147]
	s_mov_b32 m0, s31
	s_nop 0
	global_load_lds_dwordx4 v[14:15], off
	v_lshl_add_u64 v[14:15], v[162:163], 0, s[24:25]
	s_mov_b32 m0, s55
	s_nop 0
	global_load_lds_dwordx4 v[14:15], off
	v_lshl_add_u64 v[14:15], v[164:165], 0, s[24:25]
	s_mov_b32 m0, s57
	s_nop 0
	global_load_lds_dwordx4 v[14:15], off
	s_waitcnt vmcnt(8)
	s_waitcnt lgkmcnt(0)
	s_setprio 1
	s_barrier
	v_mfma_scale_f32_16x16x128_f8f6f4 v[66:69], v[2:9], v[204:211], v[66:69], v186, v186 op_sel_hi:[0,0,0]
	v_mfma_scale_f32_16x16x128_f8f6f4 v[70:73], v[174:181], v[204:211], v[70:73], v186, v186 op_sel_hi:[0,0,0]
	v_mfma_scale_f32_16x16x128_f8f6f4 v[50:53], v[2:9], v[212:219], v[50:53], v186, v186 op_sel_hi:[0,0,0]
	v_mfma_scale_f32_16x16x128_f8f6f4 v[54:57], v[174:181], v[212:219], v[54:57], v186, v186 op_sel_hi:[0,0,0]
	v_mfma_scale_f32_16x16x128_f8f6f4 v[34:37], v[2:9], v[220:227], v[34:37], v186, v186 op_sel_hi:[0,0,0]
	v_mfma_scale_f32_16x16x128_f8f6f4 v[38:41], v[174:181], v[220:227], v[38:41], v186, v186 op_sel_hi:[0,0,0]
	v_mfma_scale_f32_16x16x128_f8f6f4 v[22:25], v[2:9], v[228:235], v[22:25], v186, v186 op_sel_hi:[0,0,0]
	v_mfma_scale_f32_16x16x128_f8f6f4 v[26:29], v[174:181], v[228:235], v[26:29], v186, v186 op_sel_hi:[0,0,0]
	s_setprio 0
	s_setprio 1
	v_mfma_scale_f32_16x16x128_f8f6f4 v[74:77], v[188:195], v[204:211], v[74:77], v186, v186 op_sel_hi:[0,0,0]
	v_mfma_scale_f32_16x16x128_f8f6f4 v[78:81], v[196:203], v[204:211], v[78:81], v186, v186 op_sel_hi:[0,0,0]
	v_mfma_scale_f32_16x16x128_f8f6f4 v[58:61], v[188:195], v[212:219], v[58:61], v186, v186 op_sel_hi:[0,0,0]
	v_mfma_scale_f32_16x16x128_f8f6f4 v[62:65], v[196:203], v[212:219], v[62:65], v186, v186 op_sel_hi:[0,0,0]
	v_mfma_scale_f32_16x16x128_f8f6f4 v[42:45], v[188:195], v[220:227], v[42:45], v186, v186 op_sel_hi:[0,0,0]
	v_mfma_scale_f32_16x16x128_f8f6f4 v[46:49], v[196:203], v[220:227], v[46:49], v186, v186 op_sel_hi:[0,0,0]
	v_mfma_scale_f32_16x16x128_f8f6f4 v[30:33], v[188:195], v[228:235], v[30:33], v186, v186 op_sel_hi:[0,0,0]
	v_mfma_scale_f32_16x16x128_f8f6f4 v[10:13], v[196:203], v[228:235], v[10:13], v186, v186 op_sel_hi:[0,0,0]
	s_setprio 0
	s_barrier
	ds_read_b128 v[2:5], v169
	ds_read_b128 v[6:9], v169 offset:1024
	ds_read_b128 v[158:161], v169 offset:2048
	ds_read_b128 v[162:165], v169 offset:3072
	ds_read_b128 v[174:177], v170
	ds_read_b128 v[178:181], v170 offset:1024
	ds_read_b128 v[188:191], v170 offset:2048
	ds_read_b128 v[192:195], v170 offset:3072
	s_add_u32 s22, s22, 0x10180
	s_addc_u32 s23, s23, 0
	s_mov_b32 m0, s62
	v_lshl_add_u64 v[14:15], s[22:23], 0, v[152:153]
	ds_read_b128 v[196:199], v171
	ds_read_b128 v[200:203], v171 offset:1024
	ds_read_b128 v[204:207], v171 offset:2048
	ds_read_b128 v[208:211], v171 offset:3072
	ds_read_b128 v[212:215], v171 offset:4096
	ds_read_b128 v[216:219], v171 offset:5120
	ds_read_b128 v[220:223], v171 offset:6144
	ds_read_b128 v[224:227], v171 offset:7168
	global_load_lds_dwordx4 v[14:15], off
	v_lshl_add_u64 v[14:15], s[22:23], 0, v[148:149]
	s_mov_b32 m0, s63
	s_nop 0
	global_load_lds_dwordx4 v[14:15], off
	s_waitcnt vmcnt(8)
	s_waitcnt lgkmcnt(0)
	s_setprio 1
	s_barrier
	v_mfma_scale_f32_16x16x128_f8f6f4 v[130:133], v[2:9], v[196:203], v[130:133], v186, v186 op_sel_hi:[0,0,0]
	v_mfma_scale_f32_16x16x128_f8f6f4 v[134:137], v[158:165], v[196:203], v[134:137], v186, v186 op_sel_hi:[0,0,0]
	v_mfma_scale_f32_16x16x128_f8f6f4 v[114:117], v[2:9], v[204:211], v[114:117], v186, v186 op_sel_hi:[0,0,0]
	v_mfma_scale_f32_16x16x128_f8f6f4 v[118:121], v[158:165], v[204:211], v[118:121], v186, v186 op_sel_hi:[0,0,0]
	v_mfma_scale_f32_16x16x128_f8f6f4 v[98:101], v[2:9], v[212:219], v[98:101], v186, v186 op_sel_hi:[0,0,0]
	v_mfma_scale_f32_16x16x128_f8f6f4 v[102:105], v[158:165], v[212:219], v[102:105], v186, v186 op_sel_hi:[0,0,0]
	v_mfma_scale_f32_16x16x128_f8f6f4 v[82:85], v[2:9], v[220:227], v[82:85], v186, v186 op_sel_hi:[0,0,0]
	v_mfma_scale_f32_16x16x128_f8f6f4 v[86:89], v[158:165], v[220:227], v[86:89], v186, v186 op_sel_hi:[0,0,0]
	s_setprio 0
	s_setprio 1
	v_mfma_scale_f32_16x16x128_f8f6f4 v[138:141], v[174:181], v[196:203], v[138:141], v186, v186 op_sel_hi:[0,0,0]
	v_mfma_scale_f32_16x16x128_f8f6f4 v[142:145], v[188:195], v[196:203], v[142:145], v186, v186 op_sel_hi:[0,0,0]
	v_mfma_scale_f32_16x16x128_f8f6f4 v[122:125], v[174:181], v[204:211], v[122:125], v186, v186 op_sel_hi:[0,0,0]
	v_mfma_scale_f32_16x16x128_f8f6f4 v[126:129], v[188:195], v[204:211], v[126:129], v186, v186 op_sel_hi:[0,0,0]
	v_mfma_scale_f32_16x16x128_f8f6f4 v[106:109], v[174:181], v[212:219], v[106:109], v186, v186 op_sel_hi:[0,0,0]
	v_mfma_scale_f32_16x16x128_f8f6f4 v[110:113], v[188:195], v[212:219], v[110:113], v186, v186 op_sel_hi:[0,0,0]
	v_mfma_scale_f32_16x16x128_f8f6f4 v[90:93], v[174:181], v[220:227], v[90:93], v186, v186 op_sel_hi:[0,0,0]
	v_mfma_scale_f32_16x16x128_f8f6f4 v[94:97], v[188:195], v[220:227], v[94:97], v186, v186 op_sel_hi:[0,0,0]
	s_setprio 0
	s_barrier
	s_mov_b32 m0, s64
	v_lshl_add_u64 v[14:15], s[6:7], 0, v[150:151]
	s_add_u32 s22, s6, 0x10000
	ds_read_b128 v[196:199], v171 offset:16384
	ds_read_b128 v[200:203], v171 offset:17408
	ds_read_b128 v[204:207], v171 offset:18432
	ds_read_b128 v[208:211], v171 offset:19456
	ds_read_b128 v[212:215], v171 offset:20480
	ds_read_b128 v[216:219], v171 offset:21504
	ds_read_b128 v[220:223], v171 offset:22528
	ds_read_b128 v[224:227], v171 offset:23552
	global_load_lds_dwordx4 v[14:15], off
	v_lshl_add_u64 v[16:17], s[6:7], 0, v[146:147]
	s_mov_b32 m0, s1
	s_addc_u32 s23, s7, 0
	global_load_lds_dwordx4 v[16:17], off
	v_lshl_add_u64 v[182:183], s[22:23], 0, v[150:151]
	s_mov_b32 m0, s27
	v_lshl_add_u64 v[184:185], s[20:21], 0, v[148:149]
	global_load_lds_dwordx4 v[182:183], off
	v_lshl_add_u64 v[182:183], s[22:23], 0, v[146:147]
	s_mov_b32 m0, s41
	s_nop 0
	global_load_lds_dwordx4 v[182:183], off
	v_lshl_add_u64 v[182:183], s[20:21], 0, v[152:153]
	s_mov_b32 m0, s39
	s_nop 0
	global_load_lds_dwordx4 v[182:183], off
	s_mov_b32 m0, s46
	s_nop 0
	global_load_lds_dwordx4 v[184:185], off
	s_waitcnt vmcnt(8)
	s_waitcnt lgkmcnt(0)
	s_setprio 1
	s_barrier
	v_mfma_scale_f32_16x16x128_f8f6f4 v[66:69], v[2:9], v[196:203], v[66:69], v186, v186 op_sel_hi:[0,0,0]
	v_mfma_scale_f32_16x16x128_f8f6f4 v[70:73], v[158:165], v[196:203], v[70:73], v186, v186 op_sel_hi:[0,0,0]
	v_mfma_scale_f32_16x16x128_f8f6f4 v[50:53], v[2:9], v[204:211], v[50:53], v186, v186 op_sel_hi:[0,0,0]
	v_mfma_scale_f32_16x16x128_f8f6f4 v[54:57], v[158:165], v[204:211], v[54:57], v186, v186 op_sel_hi:[0,0,0]
	v_mfma_scale_f32_16x16x128_f8f6f4 v[34:37], v[2:9], v[212:219], v[34:37], v186, v186 op_sel_hi:[0,0,0]
	v_mfma_scale_f32_16x16x128_f8f6f4 v[38:41], v[158:165], v[212:219], v[38:41], v186, v186 op_sel_hi:[0,0,0]
	v_mfma_scale_f32_16x16x128_f8f6f4 v[22:25], v[2:9], v[220:227], v[22:25], v186, v186 op_sel_hi:[0,0,0]
	v_mfma_scale_f32_16x16x128_f8f6f4 v[26:29], v[158:165], v[220:227], v[26:29], v186, v186 op_sel_hi:[0,0,0]
	s_setprio 0
	s_setprio 1
	v_mfma_scale_f32_16x16x128_f8f6f4 v[74:77], v[174:181], v[196:203], v[74:77], v186, v186 op_sel_hi:[0,0,0]
	v_mfma_scale_f32_16x16x128_f8f6f4 v[78:81], v[188:195], v[196:203], v[78:81], v186, v186 op_sel_hi:[0,0,0]
	v_mfma_scale_f32_16x16x128_f8f6f4 v[58:61], v[174:181], v[204:211], v[58:61], v186, v186 op_sel_hi:[0,0,0]
	v_mfma_scale_f32_16x16x128_f8f6f4 v[62:65], v[188:195], v[204:211], v[62:65], v186, v186 op_sel_hi:[0,0,0]
	v_mfma_scale_f32_16x16x128_f8f6f4 v[42:45], v[174:181], v[212:219], v[42:45], v186, v186 op_sel_hi:[0,0,0]
	v_mfma_scale_f32_16x16x128_f8f6f4 v[46:49], v[188:195], v[212:219], v[46:49], v186, v186 op_sel_hi:[0,0,0]
	v_mfma_scale_f32_16x16x128_f8f6f4 v[30:33], v[174:181], v[220:227], v[30:33], v186, v186 op_sel_hi:[0,0,0]
	v_mfma_scale_f32_16x16x128_f8f6f4 v[10:13], v[188:195], v[220:227], v[10:13], v186, v186 op_sel_hi:[0,0,0]
	s_setprio 0
	s_barrier
	ds_read_b128 v[2:5], v187
	ds_read_b128 v[6:9], v187 offset:1024
	ds_read_b128 v[158:161], v187 offset:2048
	ds_read_b128 v[162:165], v187 offset:3072
	ds_read_b128 v[174:177], v236
	ds_read_b128 v[178:181], v236 offset:1024
	ds_read_b128 v[188:191], v236 offset:2048
	ds_read_b128 v[192:195], v236 offset:3072
	s_add_u32 s20, s20, 0x10000
	s_addc_u32 s21, s21, 0
	s_mov_b32 m0, s47
	v_lshl_add_u64 v[228:229], s[20:21], 0, v[152:153]
	ds_read_b128 v[196:199], v171 offset:32768
	ds_read_b128 v[200:203], v171 offset:33792
	ds_read_b128 v[204:207], v171 offset:34816
	ds_read_b128 v[208:211], v171 offset:35840
	ds_read_b128 v[212:215], v171 offset:36864
	ds_read_b128 v[216:219], v171 offset:37888
	ds_read_b128 v[220:223], v171 offset:38912
	ds_read_b128 v[224:227], v171 offset:39936
	global_load_lds_dwordx4 v[228:229], off
	v_lshl_add_u64 v[228:229], s[20:21], 0, v[148:149]
	s_mov_b32 m0, s48
	s_nop 0
	global_load_lds_dwordx4 v[228:229], off
	s_waitcnt vmcnt(8)
	s_waitcnt lgkmcnt(0)
	s_setprio 1
	s_barrier
	v_mfma_scale_f32_16x16x128_f8f6f4 v[130:133], v[2:9], v[196:203], v[130:133], v186, v186 op_sel_hi:[0,0,0]
	v_mfma_scale_f32_16x16x128_f8f6f4 v[134:137], v[158:165], v[196:203], v[134:137], v186, v186 op_sel_hi:[0,0,0]
	v_mfma_scale_f32_16x16x128_f8f6f4 v[114:117], v[2:9], v[204:211], v[114:117], v186, v186 op_sel_hi:[0,0,0]
	v_mfma_scale_f32_16x16x128_f8f6f4 v[118:121], v[158:165], v[204:211], v[118:121], v186, v186 op_sel_hi:[0,0,0]
	v_mfma_scale_f32_16x16x128_f8f6f4 v[98:101], v[2:9], v[212:219], v[98:101], v186, v186 op_sel_hi:[0,0,0]
	v_mfma_scale_f32_16x16x128_f8f6f4 v[102:105], v[158:165], v[212:219], v[102:105], v186, v186 op_sel_hi:[0,0,0]
	v_mfma_scale_f32_16x16x128_f8f6f4 v[82:85], v[2:9], v[220:227], v[82:85], v186, v186 op_sel_hi:[0,0,0]
	v_mfma_scale_f32_16x16x128_f8f6f4 v[86:89], v[158:165], v[220:227], v[86:89], v186, v186 op_sel_hi:[0,0,0]
	s_setprio 0
	s_setprio 1
	v_mfma_scale_f32_16x16x128_f8f6f4 v[138:141], v[174:181], v[196:203], v[138:141], v186, v186 op_sel_hi:[0,0,0]
	v_mfma_scale_f32_16x16x128_f8f6f4 v[142:145], v[188:195], v[196:203], v[142:145], v186, v186 op_sel_hi:[0,0,0]
	v_mfma_scale_f32_16x16x128_f8f6f4 v[122:125], v[174:181], v[204:211], v[122:125], v186, v186 op_sel_hi:[0,0,0]
	v_mfma_scale_f32_16x16x128_f8f6f4 v[126:129], v[188:195], v[204:211], v[126:129], v186, v186 op_sel_hi:[0,0,0]
	v_mfma_scale_f32_16x16x128_f8f6f4 v[106:109], v[174:181], v[212:219], v[106:109], v186, v186 op_sel_hi:[0,0,0]
	v_mfma_scale_f32_16x16x128_f8f6f4 v[110:113], v[188:195], v[212:219], v[110:113], v186, v186 op_sel_hi:[0,0,0]
	v_mfma_scale_f32_16x16x128_f8f6f4 v[90:93], v[174:181], v[220:227], v[90:93], v186, v186 op_sel_hi:[0,0,0]
	v_mfma_scale_f32_16x16x128_f8f6f4 v[94:97], v[188:195], v[220:227], v[94:97], v186, v186 op_sel_hi:[0,0,0]
	s_setprio 0
	s_barrier
	s_mov_b32 m0, s67
	v_lshl_add_u64 v[14:15], v[14:15], 0, s[12:13]
	s_add_u32 s6, s6, 0x10080
	ds_read_b128 v[196:199], v171 offset:49152
	ds_read_b128 v[200:203], v171 offset:50176
	ds_read_b128 v[204:207], v171 offset:51200
	ds_read_b128 v[208:211], v171 offset:52224
	ds_read_b128 v[212:215], v171 offset:53248
	ds_read_b128 v[216:219], v171 offset:54272
	ds_read_b128 v[220:223], v171 offset:55296
	ds_read_b128 v[224:227], v171 offset:56320
	global_load_lds_dwordx4 v[14:15], off
	v_lshl_add_u64 v[14:15], v[16:17], 0, s[12:13]
	s_mov_b32 m0, s66
	s_addc_u32 s7, s7, 0
	global_load_lds_dwordx4 v[14:15], off
	v_lshl_add_u64 v[14:15], s[6:7], 0, v[150:151]
	s_mov_b32 m0, s30
	s_nop 0
	global_load_lds_dwordx4 v[14:15], off
	v_lshl_add_u64 v[14:15], s[6:7], 0, v[146:147]
	s_mov_b32 m0, s31
	s_nop 0
	global_load_lds_dwordx4 v[14:15], off
	v_lshl_add_u64 v[14:15], v[182:183], 0, s[12:13]
	s_mov_b32 m0, s55
	s_nop 0
	global_load_lds_dwordx4 v[14:15], off
	v_lshl_add_u64 v[14:15], v[184:185], 0, s[12:13]
	s_mov_b32 m0, s57
	s_nop 0
	global_load_lds_dwordx4 v[14:15], off
	s_waitcnt vmcnt(8)
	s_waitcnt lgkmcnt(0)
	s_setprio 1
	s_barrier
	v_mfma_scale_f32_16x16x128_f8f6f4 v[66:69], v[2:9], v[196:203], v[66:69], v186, v186 op_sel_hi:[0,0,0]
	v_mfma_scale_f32_16x16x128_f8f6f4 v[70:73], v[158:165], v[196:203], v[70:73], v186, v186 op_sel_hi:[0,0,0]
	v_mfma_scale_f32_16x16x128_f8f6f4 v[50:53], v[2:9], v[204:211], v[50:53], v186, v186 op_sel_hi:[0,0,0]
	v_mfma_scale_f32_16x16x128_f8f6f4 v[54:57], v[158:165], v[204:211], v[54:57], v186, v186 op_sel_hi:[0,0,0]
	v_mfma_scale_f32_16x16x128_f8f6f4 v[34:37], v[2:9], v[212:219], v[34:37], v186, v186 op_sel_hi:[0,0,0]
	v_mfma_scale_f32_16x16x128_f8f6f4 v[38:41], v[158:165], v[212:219], v[38:41], v186, v186 op_sel_hi:[0,0,0]
	v_mfma_scale_f32_16x16x128_f8f6f4 v[22:25], v[2:9], v[220:227], v[22:25], v186, v186 op_sel_hi:[0,0,0]
	v_mfma_scale_f32_16x16x128_f8f6f4 v[26:29], v[158:165], v[220:227], v[26:29], v186, v186 op_sel_hi:[0,0,0]
	s_setprio 0
	s_setprio 1
	v_mfma_scale_f32_16x16x128_f8f6f4 v[74:77], v[174:181], v[196:203], v[74:77], v186, v186 op_sel_hi:[0,0,0]
	v_mfma_scale_f32_16x16x128_f8f6f4 v[78:81], v[188:195], v[196:203], v[78:81], v186, v186 op_sel_hi:[0,0,0]
	v_mfma_scale_f32_16x16x128_f8f6f4 v[58:61], v[174:181], v[204:211], v[58:61], v186, v186 op_sel_hi:[0,0,0]
	v_mfma_scale_f32_16x16x128_f8f6f4 v[62:65], v[188:195], v[204:211], v[62:65], v186, v186 op_sel_hi:[0,0,0]
	v_mfma_scale_f32_16x16x128_f8f6f4 v[42:45], v[174:181], v[212:219], v[42:45], v186, v186 op_sel_hi:[0,0,0]
	v_mfma_scale_f32_16x16x128_f8f6f4 v[46:49], v[188:195], v[212:219], v[46:49], v186, v186 op_sel_hi:[0,0,0]
	v_mfma_scale_f32_16x16x128_f8f6f4 v[30:33], v[174:181], v[220:227], v[30:33], v186, v186 op_sel_hi:[0,0,0]
	v_mfma_scale_f32_16x16x128_f8f6f4 v[10:13], v[188:195], v[220:227], v[10:13], v186, v186 op_sel_hi:[0,0,0]
	s_setprio 0
	s_barrier
	s_andn2_b64 vcc, exec, s[14:15]
	s_cbranch_vccnz .LBB0_324
	s_barrier

.LBB0_569:
	ds_read_b128 v[146:149], v152
	ds_read_b128 v[156:159], v152 offset:1024
	ds_read_b128 v[160:163], v152 offset:2048
	ds_read_b128 v[164:167], v152 offset:3072
	ds_read_b128 v[168:171], v153
	ds_read_b128 v[172:175], v153 offset:1024
	ds_read_b128 v[176:179], v153 offset:2048
	ds_read_b128 v[180:183], v153 offset:3072
	s_add_u32 s22, s20, 0xfff80080
	s_addc_u32 s23, s21, -1
	s_cmp_eq_u32 s55, 28
	s_cselect_b32 s31, s27, s23
	s_cselect_b32 s30, s51, s22
	s_cselect_b32 s23, s25, s54
	s_cselect_b32 s22, s52, s53
	v_lshl_add_u64 v[216:217], s[20:21], 0, v[138:139]
	s_add_i32 m0, s38, 0xc000
	ds_read_b128 v[184:187], v154
	ds_read_b128 v[188:191], v154 offset:1024
	ds_read_b128 v[192:195], v154 offset:2048
	ds_read_b128 v[196:199], v154 offset:3072
	ds_read_b128 v[200:203], v154 offset:4096
	ds_read_b128 v[204:207], v154 offset:5120
	ds_read_b128 v[208:211], v154 offset:6144
	ds_read_b128 v[212:215], v154 offset:7168
	global_load_lds_dwordx4 v[216:217], off
	v_lshl_add_u64 v[216:217], s[20:21], 0, v[140:141]
	s_add_i32 m0, s38, 0xe000
	s_nop 0
	global_load_lds_dwordx4 v[216:217], off
	s_waitcnt vmcnt(8)
	s_waitcnt lgkmcnt(0)
	s_setprio 1
	s_barrier
	v_mfma_f32_16x16x32_bf16 v[126:129], v[146:149], v[184:187], v[126:129]
	v_mfma_f32_16x16x32_bf16 v[122:125], v[160:163], v[184:187], v[122:125]
	v_mfma_f32_16x16x32_bf16 v[110:113], v[146:149], v[192:195], v[110:113]
	v_mfma_f32_16x16x32_bf16 v[106:109], v[160:163], v[192:195], v[106:109]
	v_mfma_f32_16x16x32_bf16 v[94:97], v[146:149], v[200:203], v[94:97]
	v_mfma_f32_16x16x32_bf16 v[90:93], v[160:163], v[200:203], v[90:93]
	v_mfma_f32_16x16x32_bf16 v[78:81], v[146:149], v[208:211], v[78:81]
	v_mfma_f32_16x16x32_bf16 v[74:77], v[160:163], v[208:211], v[74:77]
	v_mfma_f32_16x16x32_bf16 v[126:129], v[156:159], v[188:191], v[126:129]
	v_mfma_f32_16x16x32_bf16 v[122:125], v[164:167], v[188:191], v[122:125]
	v_mfma_f32_16x16x32_bf16 v[110:113], v[156:159], v[196:199], v[110:113]
	v_mfma_f32_16x16x32_bf16 v[106:109], v[164:167], v[196:199], v[106:109]
	v_mfma_f32_16x16x32_bf16 v[94:97], v[156:159], v[204:207], v[94:97]
	v_mfma_f32_16x16x32_bf16 v[90:93], v[164:167], v[204:207], v[90:93]
	v_mfma_f32_16x16x32_bf16 v[78:81], v[156:159], v[212:215], v[78:81]
	v_mfma_f32_16x16x32_bf16 v[74:77], v[164:167], v[212:215], v[74:77]
	s_setprio 0
	s_setprio 1
	v_mfma_f32_16x16x32_bf16 v[118:121], v[168:171], v[184:187], v[118:121]
	v_mfma_f32_16x16x32_bf16 v[114:117], v[176:179], v[184:187], v[114:117]
	v_mfma_f32_16x16x32_bf16 v[102:105], v[168:171], v[192:195], v[102:105]
	v_mfma_f32_16x16x32_bf16 v[98:101], v[176:179], v[192:195], v[98:101]
	v_mfma_f32_16x16x32_bf16 v[86:89], v[168:171], v[200:203], v[86:89]
	v_mfma_f32_16x16x32_bf16 v[82:85], v[176:179], v[200:203], v[82:85]
	v_mfma_f32_16x16x32_bf16 v[70:73], v[168:171], v[208:211], v[70:73]
	v_mfma_f32_16x16x32_bf16 v[66:69], v[176:179], v[208:211], v[66:69]
	v_mfma_f32_16x16x32_bf16 v[118:121], v[172:175], v[188:191], v[118:121]
	v_mfma_f32_16x16x32_bf16 v[114:117], v[180:183], v[188:191], v[114:117]
	v_mfma_f32_16x16x32_bf16 v[102:105], v[172:175], v[196:199], v[102:105]
	v_mfma_f32_16x16x32_bf16 v[98:101], v[180:183], v[196:199], v[98:101]
	v_mfma_f32_16x16x32_bf16 v[86:89], v[172:175], v[204:207], v[86:89]
	v_mfma_f32_16x16x32_bf16 v[82:85], v[180:183], v[204:207], v[82:85]
	v_mfma_f32_16x16x32_bf16 v[70:73], v[172:175], v[212:215], v[70:73]
	v_mfma_f32_16x16x32_bf16 v[66:69], v[180:183], v[212:215], v[66:69]
	s_setprio 0
	s_barrier
	s_add_i32 s57, s49, s35
	v_lshl_add_u64 v[216:217], s[22:23], 0, v[134:135]
	s_mov_b32 m0, s57
	ds_read_b128 v[184:187], v154 offset:16384
	ds_read_b128 v[188:191], v154 offset:17408
	ds_read_b128 v[192:195], v154 offset:18432
	ds_read_b128 v[196:199], v154 offset:19456
	ds_read_b128 v[200:203], v154 offset:20480
	ds_read_b128 v[204:207], v154 offset:21504
	ds_read_b128 v[208:211], v154 offset:22528
	ds_read_b128 v[212:215], v154 offset:23552
	global_load_lds_dwordx4 v[216:217], off
	s_add_i32 m0, s57, 0x2000
	s_add_u32 s60, s22, 0x80000
	v_lshl_add_u64 v[218:219], s[22:23], 0, v[130:131]
	s_addc_u32 s61, s23, 0
	s_add_i32 s57, s50, s35
	global_load_lds_dwordx4 v[218:219], off
	v_lshl_add_u64 v[220:221], s[60:61], 0, v[134:135]
	s_mov_b32 m0, s57
	v_lshl_add_u64 v[222:223], s[30:31], 0, v[132:133]
	global_load_lds_dwordx4 v[220:221], off
	v_lshl_add_u64 v[220:221], s[60:61], 0, v[130:131]
	s_add_i32 m0, s57, 0x2000
	s_nop 0
	global_load_lds_dwordx4 v[220:221], off
	v_lshl_add_u64 v[220:221], s[30:31], 0, v[136:137]
	s_mov_b32 m0, s38
	s_nop 0
	global_load_lds_dwordx4 v[220:221], off
	s_mov_b32 m0, s39
	s_nop 0
	global_load_lds_dwordx4 v[222:223], off
	s_waitcnt vmcnt(8)
	s_waitcnt lgkmcnt(0)
	s_setprio 1
	s_barrier
	v_mfma_f32_16x16x32_bf16 v[62:65], v[146:149], v[184:187], v[62:65]
	v_mfma_f32_16x16x32_bf16 v[58:61], v[160:163], v[184:187], v[58:61]
	v_mfma_f32_16x16x32_bf16 v[46:49], v[146:149], v[192:195], v[46:49]
	v_mfma_f32_16x16x32_bf16 v[42:45], v[160:163], v[192:195], v[42:45]
	v_mfma_f32_16x16x32_bf16 v[30:33], v[146:149], v[200:203], v[30:33]
	v_mfma_f32_16x16x32_bf16 v[26:29], v[160:163], v[200:203], v[26:29]
	v_mfma_f32_16x16x32_bf16 v[14:17], v[146:149], v[208:211], v[14:17]
	v_mfma_f32_16x16x32_bf16 v[10:13], v[160:163], v[208:211], v[10:13]
	v_mfma_f32_16x16x32_bf16 v[62:65], v[156:159], v[188:191], v[62:65]
	v_mfma_f32_16x16x32_bf16 v[58:61], v[164:167], v[188:191], v[58:61]
	v_mfma_f32_16x16x32_bf16 v[46:49], v[156:159], v[196:199], v[46:49]
	v_mfma_f32_16x16x32_bf16 v[42:45], v[164:167], v[196:199], v[42:45]
	v_mfma_f32_16x16x32_bf16 v[30:33], v[156:159], v[204:207], v[30:33]
	v_mfma_f32_16x16x32_bf16 v[26:29], v[164:167], v[204:207], v[26:29]
	v_mfma_f32_16x16x32_bf16 v[14:17], v[156:159], v[212:215], v[14:17]
	v_mfma_f32_16x16x32_bf16 v[10:13], v[164:167], v[212:215], v[10:13]
	s_setprio 0
	s_setprio 1
	v_mfma_f32_16x16x32_bf16 v[54:57], v[168:171], v[184:187], v[54:57]
	v_mfma_f32_16x16x32_bf16 v[50:53], v[176:179], v[184:187], v[50:53]
	v_mfma_f32_16x16x32_bf16 v[38:41], v[168:171], v[192:195], v[38:41]
	v_mfma_f32_16x16x32_bf16 v[34:37], v[176:179], v[192:195], v[34:37]
	v_mfma_f32_16x16x32_bf16 v[22:25], v[168:171], v[200:203], v[22:25]
	v_mfma_f32_16x16x32_bf16 v[18:21], v[176:179], v[200:203], v[18:21]
	v_mfma_f32_16x16x32_bf16 v[6:9], v[168:171], v[208:211], v[6:9]
	v_mfma_f32_16x16x32_bf16 v[2:5], v[176:179], v[208:211], v[2:5]
	v_mfma_f32_16x16x32_bf16 v[54:57], v[172:175], v[188:191], v[54:57]
	v_mfma_f32_16x16x32_bf16 v[50:53], v[180:183], v[188:191], v[50:53]
	v_mfma_f32_16x16x32_bf16 v[38:41], v[172:175], v[196:199], v[38:41]
	v_mfma_f32_16x16x32_bf16 v[34:37], v[180:183], v[196:199], v[34:37]
	v_mfma_f32_16x16x32_bf16 v[22:25], v[172:175], v[204:207], v[22:25]
	v_mfma_f32_16x16x32_bf16 v[18:21], v[180:183], v[204:207], v[18:21]
	v_mfma_f32_16x16x32_bf16 v[6:9], v[172:175], v[212:215], v[6:9]
	v_mfma_f32_16x16x32_bf16 v[2:5], v[180:183], v[212:215], v[2:5]
	s_setprio 0
	s_barrier
	s_add_i32 s57, 0, 0x18000
	v_add_u32_e32 v155, s57, v151
	s_add_i32 s59, 0, 0x1c000
	ds_read_b128 v[146:149], v155
	ds_read_b128 v[156:159], v155 offset:1024
	ds_read_b128 v[160:163], v155 offset:2048
	ds_read_b128 v[164:167], v155 offset:3072
	v_add_u32_e32 v155, s59, v151
	ds_read_b128 v[168:171], v155
	ds_read_b128 v[172:175], v155 offset:1024
	ds_read_b128 v[176:179], v155 offset:2048
	ds_read_b128 v[180:183], v155 offset:3072
	s_add_u32 s30, s30, 0x80000
	s_addc_u32 s31, s31, 0
	s_mov_b32 m0, s42
	v_lshl_add_u64 v[224:225], s[30:31], 0, v[136:137]
	ds_read_b128 v[184:187], v154 offset:32768
	ds_read_b128 v[188:191], v154 offset:33792
	ds_read_b128 v[192:195], v154 offset:34816
	ds_read_b128 v[196:199], v154 offset:35840
	ds_read_b128 v[200:203], v154 offset:36864
	ds_read_b128 v[204:207], v154 offset:37888
	ds_read_b128 v[208:211], v154 offset:38912
	ds_read_b128 v[212:215], v154 offset:39936
	global_load_lds_dwordx4 v[224:225], off
	v_lshl_add_u64 v[224:225], s[30:31], 0, v[132:133]
	s_mov_b32 m0, s43
	s_nop 0
	global_load_lds_dwordx4 v[224:225], off
	s_waitcnt vmcnt(8)
	s_waitcnt lgkmcnt(0)
	s_setprio 1
	s_barrier
	v_mfma_f32_16x16x32_bf16 v[126:129], v[146:149], v[184:187], v[126:129]
	v_mfma_f32_16x16x32_bf16 v[122:125], v[160:163], v[184:187], v[122:125]
	v_mfma_f32_16x16x32_bf16 v[110:113], v[146:149], v[192:195], v[110:113]
	v_mfma_f32_16x16x32_bf16 v[106:109], v[160:163], v[192:195], v[106:109]
	v_mfma_f32_16x16x32_bf16 v[94:97], v[146:149], v[200:203], v[94:97]
	v_mfma_f32_16x16x32_bf16 v[90:93], v[160:163], v[200:203], v[90:93]
	v_mfma_f32_16x16x32_bf16 v[78:81], v[146:149], v[208:211], v[78:81]
	v_mfma_f32_16x16x32_bf16 v[74:77], v[160:163], v[208:211], v[74:77]
	v_mfma_f32_16x16x32_bf16 v[126:129], v[156:159], v[188:191], v[126:129]
	v_mfma_f32_16x16x32_bf16 v[122:125], v[164:167], v[188:191], v[122:125]
	v_mfma_f32_16x16x32_bf16 v[110:113], v[156:159], v[196:199], v[110:113]
	v_mfma_f32_16x16x32_bf16 v[106:109], v[164:167], v[196:199], v[106:109]
	v_mfma_f32_16x16x32_bf16 v[94:97], v[156:159], v[204:207], v[94:97]
	v_mfma_f32_16x16x32_bf16 v[90:93], v[164:167], v[204:207], v[90:93]
	v_mfma_f32_16x16x32_bf16 v[78:81], v[156:159], v[212:215], v[78:81]
	v_mfma_f32_16x16x32_bf16 v[74:77], v[164:167], v[212:215], v[74:77]
	s_setprio 0
	s_setprio 1
	v_mfma_f32_16x16x32_bf16 v[118:121], v[168:171], v[184:187], v[118:121]
	v_mfma_f32_16x16x32_bf16 v[114:117], v[176:179], v[184:187], v[114:117]
	v_mfma_f32_16x16x32_bf16 v[102:105], v[168:171], v[192:195], v[102:105]
	v_mfma_f32_16x16x32_bf16 v[98:101], v[176:179], v[192:195], v[98:101]
	v_mfma_f32_16x16x32_bf16 v[86:89], v[168:171], v[200:203], v[86:89]
	v_mfma_f32_16x16x32_bf16 v[82:85], v[176:179], v[200:203], v[82:85]
	v_mfma_f32_16x16x32_bf16 v[70:73], v[168:171], v[208:211], v[70:73]
	v_mfma_f32_16x16x32_bf16 v[66:69], v[176:179], v[208:211], v[66:69]
	v_mfma_f32_16x16x32_bf16 v[118:121], v[172:175], v[188:191], v[118:121]
	v_mfma_f32_16x16x32_bf16 v[114:117], v[180:183], v[188:191], v[114:117]
	v_mfma_f32_16x16x32_bf16 v[102:105], v[172:175], v[196:199], v[102:105]
	v_mfma_f32_16x16x32_bf16 v[98:101], v[180:183], v[196:199], v[98:101]
	v_mfma_f32_16x16x32_bf16 v[86:89], v[172:175], v[204:207], v[86:89]
	v_mfma_f32_16x16x32_bf16 v[82:85], v[180:183], v[204:207], v[82:85]
	v_mfma_f32_16x16x32_bf16 v[70:73], v[172:175], v[212:215], v[70:73]
	v_mfma_f32_16x16x32_bf16 v[66:69], v[180:183], v[212:215], v[66:69]
	s_setprio 0
	s_barrier
	s_add_i32 s30, s57, s35
	v_lshl_add_u64 v[216:217], v[216:217], 0, s[16:17]
	s_mov_b32 m0, s30
	ds_read_b128 v[184:187], v154 offset:49152
	ds_read_b128 v[188:191], v154 offset:50176
	ds_read_b128 v[192:195], v154 offset:51200
	ds_read_b128 v[196:199], v154 offset:52224
	ds_read_b128 v[200:203], v154 offset:53248
	ds_read_b128 v[204:207], v154 offset:54272
	ds_read_b128 v[208:211], v154 offset:55296
	ds_read_b128 v[212:215], v154 offset:56320
	global_load_lds_dwordx4 v[216:217], off
	s_add_i32 m0, s30, 0x2000
	s_add_u32 s22, s22, 0x80080
	v_lshl_add_u64 v[216:217], v[218:219], 0, s[16:17]
	s_addc_u32 s23, s23, 0
	s_add_i32 s30, s59, s35
	global_load_lds_dwordx4 v[216:217], off
	v_lshl_add_u64 v[216:217], s[22:23], 0, v[134:135]
	s_mov_b32 m0, s30
	s_nop 0
	global_load_lds_dwordx4 v[216:217], off
	v_lshl_add_u64 v[216:217], s[22:23], 0, v[130:131]
	s_add_i32 m0, s30, 0x2000
	s_nop 0
	global_load_lds_dwordx4 v[216:217], off
	v_lshl_add_u64 v[216:217], v[220:221], 0, s[16:17]
	s_mov_b32 m0, s47
	s_nop 0
	global_load_lds_dwordx4 v[216:217], off
	v_lshl_add_u64 v[216:217], v[222:223], 0, s[16:17]
	s_mov_b32 m0, s48
	s_nop 0
	global_load_lds_dwordx4 v[216:217], off
	s_waitcnt vmcnt(8)
	s_waitcnt lgkmcnt(0)
	s_setprio 1
	s_barrier
	v_mfma_f32_16x16x32_bf16 v[62:65], v[146:149], v[184:187], v[62:65]
	v_mfma_f32_16x16x32_bf16 v[58:61], v[160:163], v[184:187], v[58:61]
	v_mfma_f32_16x16x32_bf16 v[46:49], v[146:149], v[192:195], v[46:49]
	v_mfma_f32_16x16x32_bf16 v[42:45], v[160:163], v[192:195], v[42:45]
	v_mfma_f32_16x16x32_bf16 v[30:33], v[146:149], v[200:203], v[30:33]
	v_mfma_f32_16x16x32_bf16 v[26:29], v[160:163], v[200:203], v[26:29]
	v_mfma_f32_16x16x32_bf16 v[14:17], v[146:149], v[208:211], v[14:17]
	v_mfma_f32_16x16x32_bf16 v[10:13], v[160:163], v[208:211], v[10:13]
	v_mfma_f32_16x16x32_bf16 v[62:65], v[156:159], v[188:191], v[62:65]
	v_mfma_f32_16x16x32_bf16 v[58:61], v[164:167], v[188:191], v[58:61]
	v_mfma_f32_16x16x32_bf16 v[46:49], v[156:159], v[196:199], v[46:49]
	v_mfma_f32_16x16x32_bf16 v[42:45], v[164:167], v[196:199], v[42:45]
	v_mfma_f32_16x16x32_bf16 v[30:33], v[156:159], v[204:207], v[30:33]
	v_mfma_f32_16x16x32_bf16 v[26:29], v[164:167], v[204:207], v[26:29]
	v_mfma_f32_16x16x32_bf16 v[14:17], v[156:159], v[212:215], v[14:17]
	v_mfma_f32_16x16x32_bf16 v[10:13], v[164:167], v[212:215], v[10:13]
	s_setprio 0
	s_setprio 1
	v_mfma_f32_16x16x32_bf16 v[54:57], v[168:171], v[184:187], v[54:57]
	v_mfma_f32_16x16x32_bf16 v[50:53], v[176:179], v[184:187], v[50:53]
	v_mfma_f32_16x16x32_bf16 v[38:41], v[168:171], v[192:195], v[38:41]
	v_mfma_f32_16x16x32_bf16 v[34:37], v[176:179], v[192:195], v[34:37]
	v_mfma_f32_16x16x32_bf16 v[22:25], v[168:171], v[200:203], v[22:25]
	v_mfma_f32_16x16x32_bf16 v[18:21], v[176:179], v[200:203], v[18:21]
	v_mfma_f32_16x16x32_bf16 v[6:9], v[168:171], v[208:211], v[6:9]
	v_mfma_f32_16x16x32_bf16 v[2:5], v[176:179], v[208:211], v[2:5]
	v_mfma_f32_16x16x32_bf16 v[54:57], v[172:175], v[188:191], v[54:57]
	v_mfma_f32_16x16x32_bf16 v[50:53], v[180:183], v[188:191], v[50:53]
	v_mfma_f32_16x16x32_bf16 v[38:41], v[172:175], v[196:199], v[38:41]
	v_mfma_f32_16x16x32_bf16 v[34:37], v[180:183], v[196:199], v[34:37]
	v_mfma_f32_16x16x32_bf16 v[22:25], v[172:175], v[204:207], v[22:25]
	v_mfma_f32_16x16x32_bf16 v[18:21], v[180:183], v[204:207], v[18:21]
	v_mfma_f32_16x16x32_bf16 v[6:9], v[172:175], v[212:215], v[6:9]
	v_mfma_f32_16x16x32_bf16 v[2:5], v[180:183], v[212:215], v[2:5]
	s_setprio 0
	s_barrier
	s_add_i32 s55, s55, 2
	s_add_u32 s20, s20, 0x100
	s_addc_u32 s21, s21, 0
	s_add_u32 s53, s53, 0x100
	s_addc_u32 s54, s54, 0
	s_cmp_gt_u32 s55, 29
	s_cbranch_scc0 .LBB0_569
	s_and_b64 vcc, exec, s[18:19]
	s_cbranch_vccz .LBB0_572
	s_barrier

.LBB0_585:
	ds_read_b128 v[26:29], v189
	ds_read_b128 v[30:33], v189 offset:1024
	ds_read_b128 v[18:21], v189 offset:2048
	ds_read_b128 v[22:25], v189 offset:3072
	ds_read_b128 v[10:13], v190
	ds_read_b128 v[14:17], v190 offset:1024
	ds_read_b128 v[2:5], v190 offset:2048
	ds_read_b128 v[6:9], v190 offset:3072
	s_add_u32 s22, s20, 0xfffc0080
	s_addc_u32 s23, s21, -1
	s_cmp_eq_u32 s55, 12
	s_cselect_b32 s31, s27, s23
	s_cselect_b32 s30, s51, s22
	s_cselect_b32 s23, s25, s54
	s_cselect_b32 s22, s52, s53
	v_lshl_add_u64 v[216:217], s[20:21], 0, v[170:171]
	s_add_i32 m0, s37, 0xc000
	ds_read_b128 v[178:181], v191
	ds_read_b128 v[182:185], v191 offset:1024
	ds_read_b128 v[192:195], v191 offset:2048
	ds_read_b128 v[196:199], v191 offset:3072
	ds_read_b128 v[200:203], v191 offset:4096
	ds_read_b128 v[204:207], v191 offset:5120
	ds_read_b128 v[208:211], v191 offset:6144
	ds_read_b128 v[212:215], v191 offset:7168
	global_load_lds_dwordx4 v[216:217], off
	v_lshl_add_u64 v[216:217], s[20:21], 0, v[172:173]
	s_add_i32 m0, s37, 0xe000
	s_nop 0
	global_load_lds_dwordx4 v[216:217], off
	s_waitcnt vmcnt(8)
	s_waitcnt lgkmcnt(0)
	s_setprio 1
	s_barrier
	v_mfma_scale_f32_16x16x128_f8f6f4 v[158:161], v[26:33], v[178:185], v[158:161], v1, v1 op_sel_hi:[0,0,0]
	v_mfma_scale_f32_16x16x128_f8f6f4 v[154:157], v[18:25], v[178:185], v[154:157], v1, v1 op_sel_hi:[0,0,0]
	v_mfma_scale_f32_16x16x128_f8f6f4 v[142:145], v[26:33], v[192:199], v[142:145], v1, v1 op_sel_hi:[0,0,0]
	v_mfma_scale_f32_16x16x128_f8f6f4 v[138:141], v[18:25], v[192:199], v[138:141], v1, v1 op_sel_hi:[0,0,0]
	v_mfma_scale_f32_16x16x128_f8f6f4 v[126:129], v[26:33], v[200:207], v[126:129], v1, v1 op_sel_hi:[0,0,0]
	v_mfma_scale_f32_16x16x128_f8f6f4 v[122:125], v[18:25], v[200:207], v[122:125], v1, v1 op_sel_hi:[0,0,0]
	v_mfma_scale_f32_16x16x128_f8f6f4 v[110:113], v[26:33], v[208:215], v[110:113], v1, v1 op_sel_hi:[0,0,0]
	v_mfma_scale_f32_16x16x128_f8f6f4 v[106:109], v[18:25], v[208:215], v[106:109], v1, v1 op_sel_hi:[0,0,0]
	s_setprio 0
	s_setprio 1
	v_mfma_scale_f32_16x16x128_f8f6f4 v[150:153], v[10:17], v[178:185], v[150:153], v1, v1 op_sel_hi:[0,0,0]
	v_mfma_scale_f32_16x16x128_f8f6f4 v[146:149], v[2:9], v[178:185], v[146:149], v1, v1 op_sel_hi:[0,0,0]
	v_mfma_scale_f32_16x16x128_f8f6f4 v[134:137], v[10:17], v[192:199], v[134:137], v1, v1 op_sel_hi:[0,0,0]
	v_mfma_scale_f32_16x16x128_f8f6f4 v[130:133], v[2:9], v[192:199], v[130:133], v1, v1 op_sel_hi:[0,0,0]
	v_mfma_scale_f32_16x16x128_f8f6f4 v[118:121], v[10:17], v[200:207], v[118:121], v1, v1 op_sel_hi:[0,0,0]
	v_mfma_scale_f32_16x16x128_f8f6f4 v[114:117], v[2:9], v[200:207], v[114:117], v1, v1 op_sel_hi:[0,0,0]
	v_mfma_scale_f32_16x16x128_f8f6f4 v[102:105], v[10:17], v[208:215], v[102:105], v1, v1 op_sel_hi:[0,0,0]
	v_mfma_scale_f32_16x16x128_f8f6f4 v[98:101], v[2:9], v[208:215], v[98:101], v1, v1 op_sel_hi:[0,0,0]
	s_setprio 0
	s_barrier
	s_add_i32 s57, s49, s4
	v_lshl_add_u64 v[178:179], s[22:23], 0, v[166:167]
	s_mov_b32 m0, s57
	ds_read_b128 v[192:195], v191 offset:16384
	ds_read_b128 v[196:199], v191 offset:17408
	ds_read_b128 v[200:203], v191 offset:18432
	ds_read_b128 v[204:207], v191 offset:19456
	ds_read_b128 v[208:211], v191 offset:20480
	ds_read_b128 v[212:215], v191 offset:21504
	ds_read_b128 v[216:219], v191 offset:22528
	ds_read_b128 v[220:223], v191 offset:23552
	global_load_lds_dwordx4 v[178:179], off
	s_add_i32 m0, s57, 0x2000
	s_add_u32 s60, s22, 0x40000
	v_lshl_add_u64 v[180:181], s[22:23], 0, v[162:163]
	s_addc_u32 s61, s23, 0
	s_add_i32 s57, s50, s4
	global_load_lds_dwordx4 v[180:181], off
	v_lshl_add_u64 v[182:183], s[60:61], 0, v[166:167]
	s_mov_b32 m0, s57
	v_lshl_add_u64 v[184:185], s[30:31], 0, v[164:165]
	global_load_lds_dwordx4 v[182:183], off
	v_lshl_add_u64 v[182:183], s[60:61], 0, v[162:163]
	s_add_i32 m0, s57, 0x2000
	s_nop 0
	global_load_lds_dwordx4 v[182:183], off
	v_lshl_add_u64 v[182:183], s[30:31], 0, v[168:169]
	s_mov_b32 m0, s37
	s_nop 0
	global_load_lds_dwordx4 v[182:183], off
	s_mov_b32 m0, s38
	s_nop 0
	global_load_lds_dwordx4 v[184:185], off
	s_waitcnt vmcnt(8)
	s_waitcnt lgkmcnt(0)
	s_setprio 1
	s_barrier
	v_mfma_scale_f32_16x16x128_f8f6f4 v[94:97], v[26:33], v[192:199], v[94:97], v1, v1 op_sel_hi:[0,0,0]
	v_mfma_scale_f32_16x16x128_f8f6f4 v[90:93], v[18:25], v[192:199], v[90:93], v1, v1 op_sel_hi:[0,0,0]
	v_mfma_scale_f32_16x16x128_f8f6f4 v[78:81], v[26:33], v[200:207], v[78:81], v1, v1 op_sel_hi:[0,0,0]
	v_mfma_scale_f32_16x16x128_f8f6f4 v[74:77], v[18:25], v[200:207], v[74:77], v1, v1 op_sel_hi:[0,0,0]
	v_mfma_scale_f32_16x16x128_f8f6f4 v[62:65], v[26:33], v[208:215], v[62:65], v1, v1 op_sel_hi:[0,0,0]
	v_mfma_scale_f32_16x16x128_f8f6f4 v[58:61], v[18:25], v[208:215], v[58:61], v1, v1 op_sel_hi:[0,0,0]
	v_mfma_scale_f32_16x16x128_f8f6f4 v[46:49], v[26:33], v[216:223], v[46:49], v1, v1 op_sel_hi:[0,0,0]
	v_mfma_scale_f32_16x16x128_f8f6f4 v[42:45], v[18:25], v[216:223], v[42:45], v1, v1 op_sel_hi:[0,0,0]
	s_setprio 0
	s_setprio 1
	v_mfma_scale_f32_16x16x128_f8f6f4 v[86:89], v[10:17], v[192:199], v[86:89], v1, v1 op_sel_hi:[0,0,0]
	v_mfma_scale_f32_16x16x128_f8f6f4 v[82:85], v[2:9], v[192:199], v[82:85], v1, v1 op_sel_hi:[0,0,0]
	v_mfma_scale_f32_16x16x128_f8f6f4 v[70:73], v[10:17], v[200:207], v[70:73], v1, v1 op_sel_hi:[0,0,0]
	v_mfma_scale_f32_16x16x128_f8f6f4 v[66:69], v[2:9], v[200:207], v[66:69], v1, v1 op_sel_hi:[0,0,0]
	v_mfma_scale_f32_16x16x128_f8f6f4 v[54:57], v[10:17], v[208:215], v[54:57], v1, v1 op_sel_hi:[0,0,0]
	v_mfma_scale_f32_16x16x128_f8f6f4 v[50:53], v[2:9], v[208:215], v[50:53], v1, v1 op_sel_hi:[0,0,0]
	v_mfma_scale_f32_16x16x128_f8f6f4 v[38:41], v[10:17], v[216:223], v[38:41], v1, v1 op_sel_hi:[0,0,0]
	v_mfma_scale_f32_16x16x128_f8f6f4 v[34:37], v[2:9], v[216:223], v[34:37], v1, v1 op_sel_hi:[0,0,0]
	s_setprio 0
	s_barrier
	s_add_i32 s57, 0, 0x18000
	s_add_i32 s59, 0, 0x1c000
	v_add_u32_e32 v14, s57, v188
	v_add_u32_e32 v30, s59, v188
	ds_read_b128 v[2:5], v14
	ds_read_b128 v[6:9], v14 offset:1024
	ds_read_b128 v[10:13], v14 offset:2048
	ds_read_b128 v[14:17], v14 offset:3072
	ds_read_b128 v[18:21], v30
	ds_read_b128 v[22:25], v30 offset:1024
	ds_read_b128 v[26:29], v30 offset:2048
	ds_read_b128 v[30:33], v30 offset:3072
	s_add_u32 s30, s30, 0x40000
	s_addc_u32 s31, s31, 0
	s_mov_b32 m0, s39
	v_lshl_add_u64 v[224:225], s[30:31], 0, v[168:169]
	ds_read_b128 v[192:195], v191 offset:32768
	ds_read_b128 v[196:199], v191 offset:33792
	ds_read_b128 v[200:203], v191 offset:34816
	ds_read_b128 v[204:207], v191 offset:35840
	ds_read_b128 v[208:211], v191 offset:36864
	ds_read_b128 v[212:215], v191 offset:37888
	ds_read_b128 v[216:219], v191 offset:38912
	ds_read_b128 v[220:223], v191 offset:39936
	global_load_lds_dwordx4 v[224:225], off
	v_lshl_add_u64 v[224:225], s[30:31], 0, v[164:165]
	s_mov_b32 m0, s42
	s_nop 0
	global_load_lds_dwordx4 v[224:225], off
	s_waitcnt vmcnt(8)
	s_waitcnt lgkmcnt(0)
	s_setprio 1
	s_barrier
	v_mfma_scale_f32_16x16x128_f8f6f4 v[158:161], v[2:9], v[192:199], v[158:161], v1, v1 op_sel_hi:[0,0,0]
	v_mfma_scale_f32_16x16x128_f8f6f4 v[154:157], v[10:17], v[192:199], v[154:157], v1, v1 op_sel_hi:[0,0,0]
	v_mfma_scale_f32_16x16x128_f8f6f4 v[142:145], v[2:9], v[200:207], v[142:145], v1, v1 op_sel_hi:[0,0,0]
	v_mfma_scale_f32_16x16x128_f8f6f4 v[138:141], v[10:17], v[200:207], v[138:141], v1, v1 op_sel_hi:[0,0,0]
	v_mfma_scale_f32_16x16x128_f8f6f4 v[126:129], v[2:9], v[208:215], v[126:129], v1, v1 op_sel_hi:[0,0,0]
	v_mfma_scale_f32_16x16x128_f8f6f4 v[122:125], v[10:17], v[208:215], v[122:125], v1, v1 op_sel_hi:[0,0,0]
	v_mfma_scale_f32_16x16x128_f8f6f4 v[110:113], v[2:9], v[216:223], v[110:113], v1, v1 op_sel_hi:[0,0,0]
	v_mfma_scale_f32_16x16x128_f8f6f4 v[106:109], v[10:17], v[216:223], v[106:109], v1, v1 op_sel_hi:[0,0,0]
	s_setprio 0
	s_setprio 1
	v_mfma_scale_f32_16x16x128_f8f6f4 v[150:153], v[18:25], v[192:199], v[150:153], v1, v1 op_sel_hi:[0,0,0]
	v_mfma_scale_f32_16x16x128_f8f6f4 v[146:149], v[26:33], v[192:199], v[146:149], v1, v1 op_sel_hi:[0,0,0]
	v_mfma_scale_f32_16x16x128_f8f6f4 v[134:137], v[18:25], v[200:207], v[134:137], v1, v1 op_sel_hi:[0,0,0]
	v_mfma_scale_f32_16x16x128_f8f6f4 v[130:133], v[26:33], v[200:207], v[130:133], v1, v1 op_sel_hi:[0,0,0]
	v_mfma_scale_f32_16x16x128_f8f6f4 v[118:121], v[18:25], v[208:215], v[118:121], v1, v1 op_sel_hi:[0,0,0]
	v_mfma_scale_f32_16x16x128_f8f6f4 v[114:117], v[26:33], v[208:215], v[114:117], v1, v1 op_sel_hi:[0,0,0]
	v_mfma_scale_f32_16x16x128_f8f6f4 v[102:105], v[18:25], v[216:223], v[102:105], v1, v1 op_sel_hi:[0,0,0]
	v_mfma_scale_f32_16x16x128_f8f6f4 v[98:101], v[26:33], v[216:223], v[98:101], v1, v1 op_sel_hi:[0,0,0]
	s_setprio 0
	s_barrier
	s_add_i32 s30, s57, s4
	v_lshl_add_u64 v[178:179], v[178:179], 0, s[14:15]
	s_mov_b32 m0, s30
	ds_read_b128 v[192:195], v191 offset:49152
	ds_read_b128 v[196:199], v191 offset:50176
	ds_read_b128 v[200:203], v191 offset:51200
	ds_read_b128 v[204:207], v191 offset:52224
	ds_read_b128 v[208:211], v191 offset:53248
	ds_read_b128 v[212:215], v191 offset:54272
	ds_read_b128 v[216:219], v191 offset:55296
	ds_read_b128 v[220:223], v191 offset:56320
	global_load_lds_dwordx4 v[178:179], off
	s_add_i32 m0, s30, 0x2000
	s_add_u32 s22, s22, 0x40080
	v_lshl_add_u64 v[178:179], v[180:181], 0, s[14:15]
	s_addc_u32 s23, s23, 0
	s_add_i32 s30, s59, s4
	global_load_lds_dwordx4 v[178:179], off
	v_lshl_add_u64 v[178:179], s[22:23], 0, v[166:167]
	s_mov_b32 m0, s30
	s_nop 0
	global_load_lds_dwordx4 v[178:179], off
	v_lshl_add_u64 v[178:179], s[22:23], 0, v[162:163]
	s_add_i32 m0, s30, 0x2000
	s_nop 0
	global_load_lds_dwordx4 v[178:179], off
	v_lshl_add_u64 v[178:179], v[182:183], 0, s[14:15]
	s_mov_b32 m0, s47
	s_nop 0
	global_load_lds_dwordx4 v[178:179], off
	v_lshl_add_u64 v[178:179], v[184:185], 0, s[14:15]
	s_mov_b32 m0, s48
	s_nop 0
	global_load_lds_dwordx4 v[178:179], off
	s_waitcnt vmcnt(8)
	s_waitcnt lgkmcnt(0)
	s_setprio 1
	s_barrier
	v_mfma_scale_f32_16x16x128_f8f6f4 v[94:97], v[2:9], v[192:199], v[94:97], v1, v1 op_sel_hi:[0,0,0]
	v_mfma_scale_f32_16x16x128_f8f6f4 v[90:93], v[10:17], v[192:199], v[90:93], v1, v1 op_sel_hi:[0,0,0]
	v_mfma_scale_f32_16x16x128_f8f6f4 v[78:81], v[2:9], v[200:207], v[78:81], v1, v1 op_sel_hi:[0,0,0]
	v_mfma_scale_f32_16x16x128_f8f6f4 v[74:77], v[10:17], v[200:207], v[74:77], v1, v1 op_sel_hi:[0,0,0]
	v_mfma_scale_f32_16x16x128_f8f6f4 v[62:65], v[2:9], v[208:215], v[62:65], v1, v1 op_sel_hi:[0,0,0]
	v_mfma_scale_f32_16x16x128_f8f6f4 v[58:61], v[10:17], v[208:215], v[58:61], v1, v1 op_sel_hi:[0,0,0]
	v_mfma_scale_f32_16x16x128_f8f6f4 v[46:49], v[2:9], v[216:223], v[46:49], v1, v1 op_sel_hi:[0,0,0]
	v_mfma_scale_f32_16x16x128_f8f6f4 v[42:45], v[10:17], v[216:223], v[42:45], v1, v1 op_sel_hi:[0,0,0]
	s_setprio 0
	s_setprio 1
	v_mfma_scale_f32_16x16x128_f8f6f4 v[86:89], v[18:25], v[192:199], v[86:89], v1, v1 op_sel_hi:[0,0,0]
	v_mfma_scale_f32_16x16x128_f8f6f4 v[82:85], v[26:33], v[192:199], v[82:85], v1, v1 op_sel_hi:[0,0,0]
	v_mfma_scale_f32_16x16x128_f8f6f4 v[70:73], v[18:25], v[200:207], v[70:73], v1, v1 op_sel_hi:[0,0,0]
	v_mfma_scale_f32_16x16x128_f8f6f4 v[66:69], v[26:33], v[200:207], v[66:69], v1, v1 op_sel_hi:[0,0,0]
	v_mfma_scale_f32_16x16x128_f8f6f4 v[54:57], v[18:25], v[208:215], v[54:57], v1, v1 op_sel_hi:[0,0,0]
	v_mfma_scale_f32_16x16x128_f8f6f4 v[50:53], v[26:33], v[208:215], v[50:53], v1, v1 op_sel_hi:[0,0,0]
	v_mfma_scale_f32_16x16x128_f8f6f4 v[38:41], v[18:25], v[216:223], v[38:41], v1, v1 op_sel_hi:[0,0,0]
	v_mfma_scale_f32_16x16x128_f8f6f4 v[34:37], v[26:33], v[216:223], v[34:37], v1, v1 op_sel_hi:[0,0,0]
	s_setprio 0
	s_barrier
	s_add_i32 s55, s55, 2
	s_add_u32 s20, s20, 0x100
	s_addc_u32 s21, s21, 0
	s_add_u32 s53, s53, 0x100
	s_addc_u32 s54, s54, 0
	s_cmp_gt_u32 s55, 13
	s_cbranch_scc0 .LBB0_585
	s_and_b64 vcc, exec, s[16:17]
	s_cbranch_vccz .LBB0_588
	s_barrier

.LBB0_655:
	ds_read_b128 v[146:149], v152
	ds_read_b128 v[156:159], v152 offset:1024
	ds_read_b128 v[160:163], v152 offset:2048
	ds_read_b128 v[164:167], v152 offset:3072
	ds_read_b128 v[168:171], v153
	ds_read_b128 v[172:175], v153 offset:1024
	ds_read_b128 v[176:179], v153 offset:2048
	ds_read_b128 v[180:183], v153 offset:3072
	s_add_u32 s30, s22, 0xfff00080
	s_addc_u32 s31, s23, -1
	s_cmp_eq_u32 s74, 60
	s_cselect_b32 s35, s1, s31
	s_cselect_b32 s34, s12, s30
	s_cselect_b32 s31, s21, s73
	s_cselect_b32 s30, s49, s51
	v_lshl_add_u64 v[216:217], s[22:23], 0, v[138:139]
	s_add_i32 m0, s38, 0xc000
	ds_read_b128 v[184:187], v154
	ds_read_b128 v[188:191], v154 offset:1024
	ds_read_b128 v[192:195], v154 offset:2048
	ds_read_b128 v[196:199], v154 offset:3072
	ds_read_b128 v[200:203], v154 offset:4096
	ds_read_b128 v[204:207], v154 offset:5120
	ds_read_b128 v[208:211], v154 offset:6144
	ds_read_b128 v[212:215], v154 offset:7168
	global_load_lds_dwordx4 v[216:217], off
	v_lshl_add_u64 v[216:217], s[22:23], 0, v[140:141]
	s_add_i32 m0, s38, 0xe000
	s_nop 0
	global_load_lds_dwordx4 v[216:217], off
	s_waitcnt vmcnt(8)
	s_waitcnt lgkmcnt(0)
	s_setprio 1
	s_barrier
	v_mfma_f32_16x16x32_bf16 v[126:129], v[146:149], v[184:187], v[126:129]
	v_mfma_f32_16x16x32_bf16 v[122:125], v[160:163], v[184:187], v[122:125]
	v_mfma_f32_16x16x32_bf16 v[110:113], v[146:149], v[192:195], v[110:113]
	v_mfma_f32_16x16x32_bf16 v[106:109], v[160:163], v[192:195], v[106:109]
	v_mfma_f32_16x16x32_bf16 v[94:97], v[146:149], v[200:203], v[94:97]
	v_mfma_f32_16x16x32_bf16 v[90:93], v[160:163], v[200:203], v[90:93]
	v_mfma_f32_16x16x32_bf16 v[78:81], v[146:149], v[208:211], v[78:81]
	v_mfma_f32_16x16x32_bf16 v[74:77], v[160:163], v[208:211], v[74:77]
	v_mfma_f32_16x16x32_bf16 v[126:129], v[156:159], v[188:191], v[126:129]
	v_mfma_f32_16x16x32_bf16 v[122:125], v[164:167], v[188:191], v[122:125]
	v_mfma_f32_16x16x32_bf16 v[110:113], v[156:159], v[196:199], v[110:113]
	v_mfma_f32_16x16x32_bf16 v[106:109], v[164:167], v[196:199], v[106:109]
	v_mfma_f32_16x16x32_bf16 v[94:97], v[156:159], v[204:207], v[94:97]
	v_mfma_f32_16x16x32_bf16 v[90:93], v[164:167], v[204:207], v[90:93]
	v_mfma_f32_16x16x32_bf16 v[78:81], v[156:159], v[212:215], v[78:81]
	v_mfma_f32_16x16x32_bf16 v[74:77], v[164:167], v[212:215], v[74:77]
	s_setprio 0
	s_setprio 1
	v_mfma_f32_16x16x32_bf16 v[118:121], v[168:171], v[184:187], v[118:121]
	v_mfma_f32_16x16x32_bf16 v[114:117], v[176:179], v[184:187], v[114:117]
	v_mfma_f32_16x16x32_bf16 v[102:105], v[168:171], v[192:195], v[102:105]
	v_mfma_f32_16x16x32_bf16 v[98:101], v[176:179], v[192:195], v[98:101]
	v_mfma_f32_16x16x32_bf16 v[86:89], v[168:171], v[200:203], v[86:89]
	v_mfma_f32_16x16x32_bf16 v[82:85], v[176:179], v[200:203], v[82:85]
	v_mfma_f32_16x16x32_bf16 v[70:73], v[168:171], v[208:211], v[70:73]
	v_mfma_f32_16x16x32_bf16 v[66:69], v[176:179], v[208:211], v[66:69]
	v_mfma_f32_16x16x32_bf16 v[118:121], v[172:175], v[188:191], v[118:121]
	v_mfma_f32_16x16x32_bf16 v[114:117], v[180:183], v[188:191], v[114:117]
	v_mfma_f32_16x16x32_bf16 v[102:105], v[172:175], v[196:199], v[102:105]
	v_mfma_f32_16x16x32_bf16 v[98:101], v[180:183], v[196:199], v[98:101]
	v_mfma_f32_16x16x32_bf16 v[86:89], v[172:175], v[204:207], v[86:89]
	v_mfma_f32_16x16x32_bf16 v[82:85], v[180:183], v[204:207], v[82:85]
	v_mfma_f32_16x16x32_bf16 v[70:73], v[172:175], v[212:215], v[70:73]
	v_mfma_f32_16x16x32_bf16 v[66:69], v[180:183], v[212:215], v[66:69]
	s_setprio 0
	s_barrier
	s_add_i32 s75, s70, s37
	v_lshl_add_u64 v[216:217], s[30:31], 0, v[132:133]
	s_mov_b32 m0, s75
	ds_read_b128 v[184:187], v154 offset:16384
	ds_read_b128 v[188:191], v154 offset:17408
	ds_read_b128 v[192:195], v154 offset:18432
	ds_read_b128 v[196:199], v154 offset:19456
	ds_read_b128 v[200:203], v154 offset:20480
	ds_read_b128 v[204:207], v154 offset:21504
	ds_read_b128 v[208:211], v154 offset:22528
	ds_read_b128 v[212:215], v154 offset:23552
	global_load_lds_dwordx4 v[216:217], off
	s_add_i32 m0, s75, 0x2000
	s_add_u32 s76, s30, 0x100000
	v_lshl_add_u64 v[218:219], s[30:31], 0, v[136:137]
	s_addc_u32 s77, s31, 0
	s_add_i32 s75, s71, s37
	global_load_lds_dwordx4 v[218:219], off
	v_lshl_add_u64 v[220:221], s[76:77], 0, v[132:133]
	s_mov_b32 m0, s75
	v_lshl_add_u64 v[222:223], s[34:35], 0, v[134:135]
	global_load_lds_dwordx4 v[220:221], off
	v_lshl_add_u64 v[220:221], s[76:77], 0, v[136:137]
	s_add_i32 m0, s75, 0x2000
	s_nop 0
	global_load_lds_dwordx4 v[220:221], off
	v_lshl_add_u64 v[220:221], s[34:35], 0, v[130:131]
	s_mov_b32 m0, s38
	s_nop 0
	global_load_lds_dwordx4 v[220:221], off
	s_mov_b32 m0, s39
	s_nop 0
	global_load_lds_dwordx4 v[222:223], off
	s_waitcnt vmcnt(8)
	s_waitcnt lgkmcnt(0)
	s_setprio 1
	s_barrier
	v_mfma_f32_16x16x32_bf16 v[62:65], v[146:149], v[184:187], v[62:65]
	v_mfma_f32_16x16x32_bf16 v[58:61], v[160:163], v[184:187], v[58:61]
	v_mfma_f32_16x16x32_bf16 v[46:49], v[146:149], v[192:195], v[46:49]
	v_mfma_f32_16x16x32_bf16 v[42:45], v[160:163], v[192:195], v[42:45]
	v_mfma_f32_16x16x32_bf16 v[30:33], v[146:149], v[200:203], v[30:33]
	v_mfma_f32_16x16x32_bf16 v[26:29], v[160:163], v[200:203], v[26:29]
	v_mfma_f32_16x16x32_bf16 v[14:17], v[146:149], v[208:211], v[14:17]
	v_mfma_f32_16x16x32_bf16 v[10:13], v[160:163], v[208:211], v[10:13]
	v_mfma_f32_16x16x32_bf16 v[62:65], v[156:159], v[188:191], v[62:65]
	v_mfma_f32_16x16x32_bf16 v[58:61], v[164:167], v[188:191], v[58:61]
	v_mfma_f32_16x16x32_bf16 v[46:49], v[156:159], v[196:199], v[46:49]
	v_mfma_f32_16x16x32_bf16 v[42:45], v[164:167], v[196:199], v[42:45]
	v_mfma_f32_16x16x32_bf16 v[30:33], v[156:159], v[204:207], v[30:33]
	v_mfma_f32_16x16x32_bf16 v[26:29], v[164:167], v[204:207], v[26:29]
	v_mfma_f32_16x16x32_bf16 v[14:17], v[156:159], v[212:215], v[14:17]
	v_mfma_f32_16x16x32_bf16 v[10:13], v[164:167], v[212:215], v[10:13]
	s_setprio 0
	s_setprio 1
	v_mfma_f32_16x16x32_bf16 v[54:57], v[168:171], v[184:187], v[54:57]
	v_mfma_f32_16x16x32_bf16 v[50:53], v[176:179], v[184:187], v[50:53]
	v_mfma_f32_16x16x32_bf16 v[38:41], v[168:171], v[192:195], v[38:41]
	v_mfma_f32_16x16x32_bf16 v[34:37], v[176:179], v[192:195], v[34:37]
	v_mfma_f32_16x16x32_bf16 v[22:25], v[168:171], v[200:203], v[22:25]
	v_mfma_f32_16x16x32_bf16 v[18:21], v[176:179], v[200:203], v[18:21]
	v_mfma_f32_16x16x32_bf16 v[6:9], v[168:171], v[208:211], v[6:9]
	v_mfma_f32_16x16x32_bf16 v[2:5], v[176:179], v[208:211], v[2:5]
	v_mfma_f32_16x16x32_bf16 v[54:57], v[172:175], v[188:191], v[54:57]
	v_mfma_f32_16x16x32_bf16 v[50:53], v[180:183], v[188:191], v[50:53]
	v_mfma_f32_16x16x32_bf16 v[38:41], v[172:175], v[196:199], v[38:41]
	v_mfma_f32_16x16x32_bf16 v[34:37], v[180:183], v[196:199], v[34:37]
	v_mfma_f32_16x16x32_bf16 v[22:25], v[172:175], v[204:207], v[22:25]
	v_mfma_f32_16x16x32_bf16 v[18:21], v[180:183], v[204:207], v[18:21]
	v_mfma_f32_16x16x32_bf16 v[6:9], v[172:175], v[212:215], v[6:9]
	v_mfma_f32_16x16x32_bf16 v[2:5], v[180:183], v[212:215], v[2:5]
	s_setprio 0
	s_barrier
	s_add_i32 s75, 0, 0x18000
	v_add_u32_e32 v155, s75, v151
	s_add_i32 s76, 0, 0x1c000
	ds_read_b128 v[146:149], v155
	ds_read_b128 v[156:159], v155 offset:1024
	ds_read_b128 v[160:163], v155 offset:2048
	ds_read_b128 v[164:167], v155 offset:3072
	v_add_u32_e32 v155, s76, v151
	ds_read_b128 v[168:171], v155
	ds_read_b128 v[172:175], v155 offset:1024
	ds_read_b128 v[176:179], v155 offset:2048
	ds_read_b128 v[180:183], v155 offset:3072
	s_add_u32 s34, s34, 0x100000
	s_addc_u32 s35, s35, 0
	s_mov_b32 m0, s57
	v_lshl_add_u64 v[224:225], s[34:35], 0, v[130:131]
	ds_read_b128 v[184:187], v154 offset:32768
	ds_read_b128 v[188:191], v154 offset:33792
	ds_read_b128 v[192:195], v154 offset:34816
	ds_read_b128 v[196:199], v154 offset:35840
	ds_read_b128 v[200:203], v154 offset:36864
	ds_read_b128 v[204:207], v154 offset:37888
	ds_read_b128 v[208:211], v154 offset:38912
	ds_read_b128 v[212:215], v154 offset:39936
	global_load_lds_dwordx4 v[224:225], off
	v_lshl_add_u64 v[224:225], s[34:35], 0, v[134:135]
	s_mov_b32 m0, s59
	s_nop 0
	global_load_lds_dwordx4 v[224:225], off
	s_waitcnt vmcnt(8)
	s_waitcnt lgkmcnt(0)
	s_setprio 1
	s_barrier
	v_mfma_f32_16x16x32_bf16 v[126:129], v[146:149], v[184:187], v[126:129]
	v_mfma_f32_16x16x32_bf16 v[122:125], v[160:163], v[184:187], v[122:125]
	v_mfma_f32_16x16x32_bf16 v[110:113], v[146:149], v[192:195], v[110:113]
	v_mfma_f32_16x16x32_bf16 v[106:109], v[160:163], v[192:195], v[106:109]
	v_mfma_f32_16x16x32_bf16 v[94:97], v[146:149], v[200:203], v[94:97]
	v_mfma_f32_16x16x32_bf16 v[90:93], v[160:163], v[200:203], v[90:93]
	v_mfma_f32_16x16x32_bf16 v[78:81], v[146:149], v[208:211], v[78:81]
	v_mfma_f32_16x16x32_bf16 v[74:77], v[160:163], v[208:211], v[74:77]
	v_mfma_f32_16x16x32_bf16 v[126:129], v[156:159], v[188:191], v[126:129]
	v_mfma_f32_16x16x32_bf16 v[122:125], v[164:167], v[188:191], v[122:125]
	v_mfma_f32_16x16x32_bf16 v[110:113], v[156:159], v[196:199], v[110:113]
	v_mfma_f32_16x16x32_bf16 v[106:109], v[164:167], v[196:199], v[106:109]
	v_mfma_f32_16x16x32_bf16 v[94:97], v[156:159], v[204:207], v[94:97]
	v_mfma_f32_16x16x32_bf16 v[90:93], v[164:167], v[204:207], v[90:93]
	v_mfma_f32_16x16x32_bf16 v[78:81], v[156:159], v[212:215], v[78:81]
	v_mfma_f32_16x16x32_bf16 v[74:77], v[164:167], v[212:215], v[74:77]
	s_setprio 0
	s_setprio 1
	v_mfma_f32_16x16x32_bf16 v[118:121], v[168:171], v[184:187], v[118:121]
	v_mfma_f32_16x16x32_bf16 v[114:117], v[176:179], v[184:187], v[114:117]
	v_mfma_f32_16x16x32_bf16 v[102:105], v[168:171], v[192:195], v[102:105]
	v_mfma_f32_16x16x32_bf16 v[98:101], v[176:179], v[192:195], v[98:101]
	v_mfma_f32_16x16x32_bf16 v[86:89], v[168:171], v[200:203], v[86:89]
	v_mfma_f32_16x16x32_bf16 v[82:85], v[176:179], v[200:203], v[82:85]
	v_mfma_f32_16x16x32_bf16 v[70:73], v[168:171], v[208:211], v[70:73]
	v_mfma_f32_16x16x32_bf16 v[66:69], v[176:179], v[208:211], v[66:69]
	v_mfma_f32_16x16x32_bf16 v[118:121], v[172:175], v[188:191], v[118:121]
	v_mfma_f32_16x16x32_bf16 v[114:117], v[180:183], v[188:191], v[114:117]
	v_mfma_f32_16x16x32_bf16 v[102:105], v[172:175], v[196:199], v[102:105]
	v_mfma_f32_16x16x32_bf16 v[98:101], v[180:183], v[196:199], v[98:101]
	v_mfma_f32_16x16x32_bf16 v[86:89], v[172:175], v[204:207], v[86:89]
	v_mfma_f32_16x16x32_bf16 v[82:85], v[180:183], v[204:207], v[82:85]
	v_mfma_f32_16x16x32_bf16 v[70:73], v[172:175], v[212:215], v[70:73]
	v_mfma_f32_16x16x32_bf16 v[66:69], v[180:183], v[212:215], v[66:69]
	s_setprio 0
	s_barrier
	s_add_i32 s34, s75, s37
	v_lshl_add_u64 v[216:217], v[216:217], 0, s[16:17]
	s_mov_b32 m0, s34
	ds_read_b128 v[184:187], v154 offset:49152
	ds_read_b128 v[188:191], v154 offset:50176
	ds_read_b128 v[192:195], v154 offset:51200
	ds_read_b128 v[196:199], v154 offset:52224
	ds_read_b128 v[200:203], v154 offset:53248
	ds_read_b128 v[204:207], v154 offset:54272
	ds_read_b128 v[208:211], v154 offset:55296
	ds_read_b128 v[212:215], v154 offset:56320
	global_load_lds_dwordx4 v[216:217], off
	s_add_i32 m0, s34, 0x2000
	s_add_u32 s30, s30, 0x100080
	v_lshl_add_u64 v[216:217], v[218:219], 0, s[16:17]
	s_addc_u32 s31, s31, 0
	s_add_i32 s34, s76, s37
	global_load_lds_dwordx4 v[216:217], off
	v_lshl_add_u64 v[216:217], s[30:31], 0, v[132:133]
	s_mov_b32 m0, s34
	s_nop 0
	global_load_lds_dwordx4 v[216:217], off
	v_lshl_add_u64 v[216:217], s[30:31], 0, v[136:137]
	s_add_i32 m0, s34, 0x2000
	s_nop 0
	global_load_lds_dwordx4 v[216:217], off
	v_lshl_add_u64 v[216:217], v[220:221], 0, s[16:17]
	s_mov_b32 m0, s66
	s_nop 0
	global_load_lds_dwordx4 v[216:217], off
	v_lshl_add_u64 v[216:217], v[222:223], 0, s[16:17]
	s_mov_b32 m0, s67
	s_nop 0
	global_load_lds_dwordx4 v[216:217], off
	s_waitcnt vmcnt(8)
	s_waitcnt lgkmcnt(0)
	s_setprio 1
	s_barrier
	v_mfma_f32_16x16x32_bf16 v[62:65], v[146:149], v[184:187], v[62:65]
	v_mfma_f32_16x16x32_bf16 v[58:61], v[160:163], v[184:187], v[58:61]
	v_mfma_f32_16x16x32_bf16 v[46:49], v[146:149], v[192:195], v[46:49]
	v_mfma_f32_16x16x32_bf16 v[42:45], v[160:163], v[192:195], v[42:45]
	v_mfma_f32_16x16x32_bf16 v[30:33], v[146:149], v[200:203], v[30:33]
	v_mfma_f32_16x16x32_bf16 v[26:29], v[160:163], v[200:203], v[26:29]
	v_mfma_f32_16x16x32_bf16 v[14:17], v[146:149], v[208:211], v[14:17]
	v_mfma_f32_16x16x32_bf16 v[10:13], v[160:163], v[208:211], v[10:13]
	v_mfma_f32_16x16x32_bf16 v[62:65], v[156:159], v[188:191], v[62:65]
	v_mfma_f32_16x16x32_bf16 v[58:61], v[164:167], v[188:191], v[58:61]
	v_mfma_f32_16x16x32_bf16 v[46:49], v[156:159], v[196:199], v[46:49]
	v_mfma_f32_16x16x32_bf16 v[42:45], v[164:167], v[196:199], v[42:45]
	v_mfma_f32_16x16x32_bf16 v[30:33], v[156:159], v[204:207], v[30:33]
	v_mfma_f32_16x16x32_bf16 v[26:29], v[164:167], v[204:207], v[26:29]
	v_mfma_f32_16x16x32_bf16 v[14:17], v[156:159], v[212:215], v[14:17]
	v_mfma_f32_16x16x32_bf16 v[10:13], v[164:167], v[212:215], v[10:13]
	s_setprio 0
	s_setprio 1
	v_mfma_f32_16x16x32_bf16 v[54:57], v[168:171], v[184:187], v[54:57]
	v_mfma_f32_16x16x32_bf16 v[50:53], v[176:179], v[184:187], v[50:53]
	v_mfma_f32_16x16x32_bf16 v[38:41], v[168:171], v[192:195], v[38:41]
	v_mfma_f32_16x16x32_bf16 v[34:37], v[176:179], v[192:195], v[34:37]
	v_mfma_f32_16x16x32_bf16 v[22:25], v[168:171], v[200:203], v[22:25]
	v_mfma_f32_16x16x32_bf16 v[18:21], v[176:179], v[200:203], v[18:21]
	v_mfma_f32_16x16x32_bf16 v[6:9], v[168:171], v[208:211], v[6:9]
	v_mfma_f32_16x16x32_bf16 v[2:5], v[176:179], v[208:211], v[2:5]
	v_mfma_f32_16x16x32_bf16 v[54:57], v[172:175], v[188:191], v[54:57]
	v_mfma_f32_16x16x32_bf16 v[50:53], v[180:183], v[188:191], v[50:53]
	v_mfma_f32_16x16x32_bf16 v[38:41], v[172:175], v[196:199], v[38:41]
	v_mfma_f32_16x16x32_bf16 v[34:37], v[180:183], v[196:199], v[34:37]
	v_mfma_f32_16x16x32_bf16 v[22:25], v[172:175], v[204:207], v[22:25]
	v_mfma_f32_16x16x32_bf16 v[18:21], v[180:183], v[204:207], v[18:21]
	v_mfma_f32_16x16x32_bf16 v[6:9], v[172:175], v[212:215], v[6:9]
	v_mfma_f32_16x16x32_bf16 v[2:5], v[180:183], v[212:215], v[2:5]
	s_setprio 0
	s_barrier
	s_add_i32 s74, s74, 2
	s_add_u32 s22, s22, 0x100
	s_addc_u32 s23, s23, 0
	s_add_u32 s51, s51, 0x100
	s_addc_u32 s73, s73, 0
	s_cmp_gt_u32 s74, 61
	s_cbranch_scc0 .LBB0_655
	s_and_b64 vcc, exec, s[24:25]
	s_cbranch_vccz .LBB0_658
	s_barrier

.LBB0_834:
	v_add_u32_e32 v146, s55, v247
	v_add_u32_e32 v162, s61, v247
	s_add_u32 s8, s58, s0
	ds_read_b128 v[134:137], v146
	ds_read_b128 v[138:141], v146 offset:1024
	ds_read_b128 v[142:145], v146 offset:2048
	ds_read_b128 v[146:149], v146 offset:3072
	ds_read_b128 v[150:153], v162
	ds_read_b128 v[154:157], v162 offset:1024
	ds_read_b128 v[158:161], v162 offset:2048
	ds_read_b128 v[162:165], v162 offset:3072
	s_addc_u32 s9, s59, s1
	s_add_u32 s8, s8, 0x100
	s_addc_u32 s9, s9, 0
	s_add_u32 s17, s20, s0
	s_addc_u32 s22, s21, s1
	s_cmpk_eq_i32 s0, 0x1f00
	s_cselect_b32 s11, s12, s9
	s_cselect_b32 s10, s13, s8
	s_cselect_b32 s9, s14, s22
	s_cselect_b32 s8, s15, s17
	v_lshl_add_u64 v[210:211], v[130:131], 0, s[0:1]
	s_add_i32 m0, s39, 0xc000
	s_waitcnt lgkmcnt(0)
	ds_read_b128 v[166:169], v248
	ds_read_b128 v[170:173], v248 offset:1024
	ds_read_b128 v[174:177], v248 offset:2048
	ds_read_b128 v[178:181], v248 offset:3072
	ds_read_b128 v[182:185], v248 offset:4096
	ds_read_b128 v[186:189], v248 offset:5120
	ds_read_b128 v[190:193], v248 offset:6144
	ds_read_b128 v[206:209], v248 offset:7168
	global_load_lds_dwordx4 v[210:211], off
	v_lshl_add_u64 v[210:211], v[132:133], 0, s[0:1]
	s_add_i32 m0, s39, 0xe000
	s_nop 0
	global_load_lds_dwordx4 v[210:211], off
	s_waitcnt vmcnt(8)
	s_waitcnt lgkmcnt(0)
	s_setprio 1
	s_barrier
	v_mfma_f32_16x16x32_bf16 v[126:129], v[134:137], v[166:169], v[126:129]
	v_mfma_f32_16x16x32_bf16 v[122:125], v[142:145], v[166:169], v[122:125]
	v_mfma_f32_16x16x32_bf16 v[118:121], v[134:137], v[174:177], v[118:121]
	v_mfma_f32_16x16x32_bf16 v[114:117], v[142:145], v[174:177], v[114:117]
	v_mfma_f32_16x16x32_bf16 v[110:113], v[134:137], v[182:185], v[110:113]
	v_mfma_f32_16x16x32_bf16 v[106:109], v[142:145], v[182:185], v[106:109]
	v_mfma_f32_16x16x32_bf16 v[102:105], v[134:137], v[190:193], v[102:105]
	v_mfma_f32_16x16x32_bf16 v[98:101], v[142:145], v[190:193], v[98:101]
	v_mfma_f32_16x16x32_bf16 v[126:129], v[138:141], v[170:173], v[126:129]
	v_mfma_f32_16x16x32_bf16 v[122:125], v[146:149], v[170:173], v[122:125]
	v_mfma_f32_16x16x32_bf16 v[118:121], v[138:141], v[178:181], v[118:121]
	v_mfma_f32_16x16x32_bf16 v[114:117], v[146:149], v[178:181], v[114:117]
	v_mfma_f32_16x16x32_bf16 v[110:113], v[138:141], v[186:189], v[110:113]
	v_mfma_f32_16x16x32_bf16 v[106:109], v[146:149], v[186:189], v[106:109]
	v_mfma_f32_16x16x32_bf16 v[102:105], v[138:141], v[206:209], v[102:105]
	v_mfma_f32_16x16x32_bf16 v[98:101], v[146:149], v[206:209], v[98:101]
	s_setprio 0
	s_setprio 1
	v_mfma_f32_16x16x32_bf16 v[94:97], v[150:153], v[166:169], v[94:97]
	v_mfma_f32_16x16x32_bf16 v[90:93], v[158:161], v[166:169], v[90:93]
	v_mfma_f32_16x16x32_bf16 v[86:89], v[150:153], v[174:177], v[86:89]
	v_mfma_f32_16x16x32_bf16 v[82:85], v[158:161], v[174:177], v[82:85]
	v_mfma_f32_16x16x32_bf16 v[78:81], v[150:153], v[182:185], v[78:81]
	v_mfma_f32_16x16x32_bf16 v[74:77], v[158:161], v[182:185], v[74:77]
	v_mfma_f32_16x16x32_bf16 v[70:73], v[150:153], v[190:193], v[70:73]
	v_mfma_f32_16x16x32_bf16 v[66:69], v[158:161], v[190:193], v[66:69]
	v_mfma_f32_16x16x32_bf16 v[94:97], v[154:157], v[170:173], v[94:97]
	v_mfma_f32_16x16x32_bf16 v[90:93], v[162:165], v[170:173], v[90:93]
	v_mfma_f32_16x16x32_bf16 v[86:89], v[154:157], v[178:181], v[86:89]
	v_mfma_f32_16x16x32_bf16 v[82:85], v[162:165], v[178:181], v[82:85]
	v_mfma_f32_16x16x32_bf16 v[78:81], v[154:157], v[186:189], v[78:81]
	v_mfma_f32_16x16x32_bf16 v[74:77], v[162:165], v[186:189], v[74:77]
	v_mfma_f32_16x16x32_bf16 v[70:73], v[154:157], v[206:209], v[70:73]
	v_mfma_f32_16x16x32_bf16 v[66:69], v[162:165], v[206:209], v[66:69]
	s_setprio 0
	s_barrier
	s_add_i32 s17, s55, s71
	v_lshl_add_u64 v[210:211], s[8:9], 0, v[194:195]
	s_mov_b32 m0, s17
	ds_read_b128 v[166:169], v248 offset:16384
	ds_read_b128 v[170:173], v248 offset:17408
	ds_read_b128 v[174:177], v248 offset:18432
	ds_read_b128 v[178:181], v248 offset:19456
	ds_read_b128 v[182:185], v248 offset:20480
	ds_read_b128 v[186:189], v248 offset:21504
	ds_read_b128 v[190:193], v248 offset:22528
	ds_read_b128 v[206:209], v248 offset:23552
	global_load_lds_dwordx4 v[210:211], off
	s_add_i32 m0, s17, 0x2000
	s_add_u32 s22, s8, 0x100000
	v_lshl_add_u64 v[212:213], s[8:9], 0, v[196:197]
	s_addc_u32 s23, s9, 0
	s_add_i32 s17, s61, s71
	global_load_lds_dwordx4 v[212:213], off
	v_lshl_add_u64 v[214:215], s[22:23], 0, v[194:195]
	s_mov_b32 m0, s17
	v_lshl_add_u64 v[216:217], s[10:11], 0, v[196:197]
	global_load_lds_dwordx4 v[214:215], off
	v_lshl_add_u64 v[214:215], s[22:23], 0, v[196:197]
	s_add_i32 m0, s17, 0x2000
	s_nop 0
	global_load_lds_dwordx4 v[214:215], off
	v_lshl_add_u64 v[214:215], s[10:11], 0, v[194:195]
	s_mov_b32 m0, s39
	s_nop 0
	global_load_lds_dwordx4 v[214:215], off
	s_mov_b32 m0, s41
	s_nop 0
	global_load_lds_dwordx4 v[216:217], off
	s_waitcnt vmcnt(8)
	s_waitcnt lgkmcnt(0)
	s_setprio 1
	s_barrier
	v_mfma_f32_16x16x32_bf16 v[62:65], v[134:137], v[166:169], v[62:65]
	v_mfma_f32_16x16x32_bf16 v[58:61], v[142:145], v[166:169], v[58:61]
	v_mfma_f32_16x16x32_bf16 v[54:57], v[134:137], v[174:177], v[54:57]
	v_mfma_f32_16x16x32_bf16 v[50:53], v[142:145], v[174:177], v[50:53]
	v_mfma_f32_16x16x32_bf16 v[46:49], v[134:137], v[182:185], v[46:49]
	v_mfma_f32_16x16x32_bf16 v[42:45], v[142:145], v[182:185], v[42:45]
	v_mfma_f32_16x16x32_bf16 v[38:41], v[134:137], v[190:193], v[38:41]
	v_mfma_f32_16x16x32_bf16 v[34:37], v[142:145], v[190:193], v[34:37]
	v_mfma_f32_16x16x32_bf16 v[62:65], v[138:141], v[170:173], v[62:65]
	v_mfma_f32_16x16x32_bf16 v[58:61], v[146:149], v[170:173], v[58:61]
	v_mfma_f32_16x16x32_bf16 v[54:57], v[138:141], v[178:181], v[54:57]
	v_mfma_f32_16x16x32_bf16 v[50:53], v[146:149], v[178:181], v[50:53]
	v_mfma_f32_16x16x32_bf16 v[46:49], v[138:141], v[186:189], v[46:49]
	v_mfma_f32_16x16x32_bf16 v[42:45], v[146:149], v[186:189], v[42:45]
	v_mfma_f32_16x16x32_bf16 v[38:41], v[138:141], v[206:209], v[38:41]
	v_mfma_f32_16x16x32_bf16 v[34:37], v[146:149], v[206:209], v[34:37]
	s_setprio 0
	s_setprio 1
	v_mfma_f32_16x16x32_bf16 v[30:33], v[150:153], v[166:169], v[30:33]
	v_mfma_f32_16x16x32_bf16 v[26:29], v[158:161], v[166:169], v[26:29]
	v_mfma_f32_16x16x32_bf16 v[22:25], v[150:153], v[174:177], v[22:25]
	v_mfma_f32_16x16x32_bf16 v[18:21], v[158:161], v[174:177], v[18:21]
	v_mfma_f32_16x16x32_bf16 v[14:17], v[150:153], v[182:185], v[14:17]
	v_mfma_f32_16x16x32_bf16 v[10:13], v[158:161], v[182:185], v[10:13]
	v_mfma_f32_16x16x32_bf16 v[6:9], v[150:153], v[190:193], v[6:9]
	v_mfma_f32_16x16x32_bf16 v[2:5], v[158:161], v[190:193], v[2:5]
	v_mfma_f32_16x16x32_bf16 v[30:33], v[154:157], v[170:173], v[30:33]
	v_mfma_f32_16x16x32_bf16 v[26:29], v[162:165], v[170:173], v[26:29]
	v_mfma_f32_16x16x32_bf16 v[22:25], v[154:157], v[178:181], v[22:25]
	v_mfma_f32_16x16x32_bf16 v[18:21], v[162:165], v[178:181], v[18:21]
	v_mfma_f32_16x16x32_bf16 v[14:17], v[154:157], v[186:189], v[14:17]
	v_mfma_f32_16x16x32_bf16 v[10:13], v[162:165], v[186:189], v[10:13]
	v_mfma_f32_16x16x32_bf16 v[6:9], v[154:157], v[206:209], v[6:9]
	v_mfma_f32_16x16x32_bf16 v[2:5], v[162:165], v[206:209], v[2:5]
	s_setprio 0
	s_barrier
	s_add_i32 s17, 0, 0x18000
	s_add_i32 s22, 0, 0x1c000
	v_add_u32_e32 v146, s17, v247
	v_add_u32_e32 v162, s22, v247
	ds_read_b128 v[134:137], v146
	ds_read_b128 v[138:141], v146 offset:1024
	ds_read_b128 v[142:145], v146 offset:2048
	ds_read_b128 v[146:149], v146 offset:3072
	ds_read_b128 v[150:153], v162
	ds_read_b128 v[154:157], v162 offset:1024
	ds_read_b128 v[158:161], v162 offset:2048
	ds_read_b128 v[162:165], v162 offset:3072
	s_add_u32 s10, s10, 0x100000
	s_addc_u32 s11, s11, 0
	s_mov_b32 m0, s68
	v_lshl_add_u64 v[218:219], s[10:11], 0, v[194:195]
	ds_read_b128 v[166:169], v248 offset:32768
	ds_read_b128 v[170:173], v248 offset:33792
	ds_read_b128 v[174:177], v248 offset:34816
	ds_read_b128 v[178:181], v248 offset:35840
	ds_read_b128 v[182:185], v248 offset:36864
	ds_read_b128 v[186:189], v248 offset:37888
	ds_read_b128 v[190:193], v248 offset:38912
	ds_read_b128 v[206:209], v248 offset:39936
	global_load_lds_dwordx4 v[218:219], off
	v_lshl_add_u64 v[218:219], s[10:11], 0, v[196:197]
	s_mov_b32 m0, s69
	s_nop 0
	global_load_lds_dwordx4 v[218:219], off
	s_waitcnt vmcnt(8)
	s_waitcnt lgkmcnt(0)
	s_setprio 1
	s_barrier
	v_mfma_f32_16x16x32_bf16 v[126:129], v[134:137], v[166:169], v[126:129]
	v_mfma_f32_16x16x32_bf16 v[122:125], v[142:145], v[166:169], v[122:125]
	v_mfma_f32_16x16x32_bf16 v[118:121], v[134:137], v[174:177], v[118:121]
	v_mfma_f32_16x16x32_bf16 v[114:117], v[142:145], v[174:177], v[114:117]
	v_mfma_f32_16x16x32_bf16 v[110:113], v[134:137], v[182:185], v[110:113]
	v_mfma_f32_16x16x32_bf16 v[106:109], v[142:145], v[182:185], v[106:109]
	v_mfma_f32_16x16x32_bf16 v[102:105], v[134:137], v[190:193], v[102:105]
	v_mfma_f32_16x16x32_bf16 v[98:101], v[142:145], v[190:193], v[98:101]
	v_mfma_f32_16x16x32_bf16 v[126:129], v[138:141], v[170:173], v[126:129]
	v_mfma_f32_16x16x32_bf16 v[122:125], v[146:149], v[170:173], v[122:125]
	v_mfma_f32_16x16x32_bf16 v[118:121], v[138:141], v[178:181], v[118:121]
	v_mfma_f32_16x16x32_bf16 v[114:117], v[146:149], v[178:181], v[114:117]
	v_mfma_f32_16x16x32_bf16 v[110:113], v[138:141], v[186:189], v[110:113]
	v_mfma_f32_16x16x32_bf16 v[106:109], v[146:149], v[186:189], v[106:109]
	v_mfma_f32_16x16x32_bf16 v[102:105], v[138:141], v[206:209], v[102:105]
	v_mfma_f32_16x16x32_bf16 v[98:101], v[146:149], v[206:209], v[98:101]
	s_setprio 0
	s_setprio 1
	v_mfma_f32_16x16x32_bf16 v[94:97], v[150:153], v[166:169], v[94:97]
	v_mfma_f32_16x16x32_bf16 v[90:93], v[158:161], v[166:169], v[90:93]
	v_mfma_f32_16x16x32_bf16 v[86:89], v[150:153], v[174:177], v[86:89]
	v_mfma_f32_16x16x32_bf16 v[82:85], v[158:161], v[174:177], v[82:85]
	v_mfma_f32_16x16x32_bf16 v[78:81], v[150:153], v[182:185], v[78:81]
	v_mfma_f32_16x16x32_bf16 v[74:77], v[158:161], v[182:185], v[74:77]
	v_mfma_f32_16x16x32_bf16 v[70:73], v[150:153], v[190:193], v[70:73]
	v_mfma_f32_16x16x32_bf16 v[66:69], v[158:161], v[190:193], v[66:69]
	v_mfma_f32_16x16x32_bf16 v[94:97], v[154:157], v[170:173], v[94:97]
	v_mfma_f32_16x16x32_bf16 v[90:93], v[162:165], v[170:173], v[90:93]
	v_mfma_f32_16x16x32_bf16 v[86:89], v[154:157], v[178:181], v[86:89]
	v_mfma_f32_16x16x32_bf16 v[82:85], v[162:165], v[178:181], v[82:85]
	v_mfma_f32_16x16x32_bf16 v[78:81], v[154:157], v[186:189], v[78:81]
	v_mfma_f32_16x16x32_bf16 v[74:77], v[162:165], v[186:189], v[74:77]
	v_mfma_f32_16x16x32_bf16 v[70:73], v[154:157], v[206:209], v[70:73]
	v_mfma_f32_16x16x32_bf16 v[66:69], v[162:165], v[206:209], v[66:69]
	s_setprio 0
	s_barrier
	s_add_i32 s10, s17, s71
	v_lshl_add_u64 v[210:211], v[210:211], 0, s[50:51]
	s_mov_b32 m0, s10
	ds_read_b128 v[166:169], v248 offset:49152
	ds_read_b128 v[170:173], v248 offset:50176
	ds_read_b128 v[174:177], v248 offset:51200
	ds_read_b128 v[178:181], v248 offset:52224
	ds_read_b128 v[182:185], v248 offset:53248
	ds_read_b128 v[186:189], v248 offset:54272
	ds_read_b128 v[190:193], v248 offset:55296
	ds_read_b128 v[206:209], v248 offset:56320
	global_load_lds_dwordx4 v[210:211], off
	s_add_i32 m0, s10, 0x2000
	s_add_u32 s8, s8, 0x100080
	v_lshl_add_u64 v[210:211], v[212:213], 0, s[50:51]
	s_addc_u32 s9, s9, 0
	s_add_i32 s10, s22, s71
	global_load_lds_dwordx4 v[210:211], off
	v_lshl_add_u64 v[210:211], s[8:9], 0, v[194:195]
	s_mov_b32 m0, s10
	s_nop 0
	global_load_lds_dwordx4 v[210:211], off
	v_lshl_add_u64 v[210:211], s[8:9], 0, v[196:197]
	s_add_i32 m0, s10, 0x2000
	s_nop 0
	global_load_lds_dwordx4 v[210:211], off
	v_lshl_add_u64 v[210:211], v[214:215], 0, s[50:51]
	s_mov_b32 m0, s64
	s_nop 0
	global_load_lds_dwordx4 v[210:211], off
	v_lshl_add_u64 v[210:211], v[216:217], 0, s[50:51]
	s_mov_b32 m0, s62
	s_nop 0
	global_load_lds_dwordx4 v[210:211], off
	s_waitcnt vmcnt(8)
	s_waitcnt lgkmcnt(0)
	s_setprio 1
	s_barrier
	v_mfma_f32_16x16x32_bf16 v[62:65], v[134:137], v[166:169], v[62:65]
	v_mfma_f32_16x16x32_bf16 v[58:61], v[142:145], v[166:169], v[58:61]
	v_mfma_f32_16x16x32_bf16 v[54:57], v[134:137], v[174:177], v[54:57]
	v_mfma_f32_16x16x32_bf16 v[50:53], v[142:145], v[174:177], v[50:53]
	v_mfma_f32_16x16x32_bf16 v[46:49], v[134:137], v[182:185], v[46:49]
	v_mfma_f32_16x16x32_bf16 v[42:45], v[142:145], v[182:185], v[42:45]
	v_mfma_f32_16x16x32_bf16 v[38:41], v[134:137], v[190:193], v[38:41]
	v_mfma_f32_16x16x32_bf16 v[34:37], v[142:145], v[190:193], v[34:37]
	v_mfma_f32_16x16x32_bf16 v[62:65], v[138:141], v[170:173], v[62:65]
	v_mfma_f32_16x16x32_bf16 v[58:61], v[146:149], v[170:173], v[58:61]
	v_mfma_f32_16x16x32_bf16 v[54:57], v[138:141], v[178:181], v[54:57]
	v_mfma_f32_16x16x32_bf16 v[50:53], v[146:149], v[178:181], v[50:53]
	v_mfma_f32_16x16x32_bf16 v[46:49], v[138:141], v[186:189], v[46:49]
	v_mfma_f32_16x16x32_bf16 v[42:45], v[146:149], v[186:189], v[42:45]
	v_mfma_f32_16x16x32_bf16 v[38:41], v[138:141], v[206:209], v[38:41]
	v_mfma_f32_16x16x32_bf16 v[34:37], v[146:149], v[206:209], v[34:37]
	s_setprio 0
	s_setprio 1
	v_mfma_f32_16x16x32_bf16 v[30:33], v[150:153], v[166:169], v[30:33]
	v_mfma_f32_16x16x32_bf16 v[26:29], v[158:161], v[166:169], v[26:29]
	v_mfma_f32_16x16x32_bf16 v[22:25], v[150:153], v[174:177], v[22:25]
	v_mfma_f32_16x16x32_bf16 v[18:21], v[158:161], v[174:177], v[18:21]
	v_mfma_f32_16x16x32_bf16 v[14:17], v[150:153], v[182:185], v[14:17]
	v_mfma_f32_16x16x32_bf16 v[10:13], v[158:161], v[182:185], v[10:13]
	v_mfma_f32_16x16x32_bf16 v[6:9], v[150:153], v[190:193], v[6:9]
	v_mfma_f32_16x16x32_bf16 v[2:5], v[158:161], v[190:193], v[2:5]
	v_mfma_f32_16x16x32_bf16 v[30:33], v[154:157], v[170:173], v[30:33]
	v_mfma_f32_16x16x32_bf16 v[26:29], v[162:165], v[170:173], v[26:29]
	v_mfma_f32_16x16x32_bf16 v[22:25], v[154:157], v[178:181], v[22:25]
	v_mfma_f32_16x16x32_bf16 v[18:21], v[162:165], v[178:181], v[18:21]
	v_mfma_f32_16x16x32_bf16 v[14:17], v[154:157], v[186:189], v[14:17]
	v_mfma_f32_16x16x32_bf16 v[10:13], v[162:165], v[186:189], v[10:13]
	v_mfma_f32_16x16x32_bf16 v[6:9], v[154:157], v[206:209], v[6:9]
	v_mfma_f32_16x16x32_bf16 v[2:5], v[162:165], v[206:209], v[2:5]
	s_setprio 0
	s_barrier
	s_add_i32 s16, s16, 2
	s_add_u32 s0, s0, 0x100
	s_addc_u32 s1, s1, 0
	s_cmp_gt_u32 s16, 61
	s_cbranch_scc0 .LBB0_834
	s_and_b64 vcc, exec, s[52:53]
	s_cbranch_vccz .LBB0_837
	s_barrier

.LBB0_1035:
	ds_read_b128 v[148:151], v145
	ds_read_b128 v[152:155], v145 offset:1024
	ds_read_b128 v[156:159], v145 offset:2048
	ds_read_b128 v[160:163], v145 offset:3072
	ds_read_b128 v[164:167], v146
	ds_read_b128 v[168:171], v146 offset:1024
	ds_read_b128 v[172:175], v146 offset:2048
	ds_read_b128 v[176:179], v146 offset:3072
	s_add_u32 s36, s34, 0x100
	s_addc_u32 s37, s35, 0
	s_cmpk_eq_i32 s65, 0xa8
	s_cselect_b32 s41, s5, s37
	s_cselect_b32 s40, s4, s36
	s_cselect_b32 s39, s29, s64
	s_cselect_b32 s38, s28, s31
	v_lshl_add_u64 v[140:141], s[34:35], 0, v[132:133]
	s_add_i32 m0, s48, 0xc000
	ds_read_b128 v[180:183], v147
	ds_read_b128 v[184:187], v147 offset:1024
	ds_read_b128 v[188:191], v147 offset:2048
	ds_read_b128 v[192:195], v147 offset:3072
	ds_read_b128 v[196:199], v147 offset:4096
	ds_read_b128 v[200:203], v147 offset:5120
	ds_read_b128 v[204:207], v147 offset:6144
	ds_read_b128 v[208:211], v147 offset:7168
	global_load_lds_dwordx4 v[140:141], off
	v_lshl_add_u64 v[140:141], s[34:35], 0, v[134:135]
	s_add_i32 m0, s48, 0xe000
	s_nop 0
	global_load_lds_dwordx4 v[140:141], off
	s_waitcnt vmcnt(8)
	s_waitcnt lgkmcnt(0)
	s_setprio 1
	s_barrier
	v_mfma_f32_16x16x32_bf16 v[124:127], v[148:151], v[180:183], v[124:127]
	v_mfma_f32_16x16x32_bf16 v[120:123], v[156:159], v[180:183], v[120:123]
	v_mfma_f32_16x16x32_bf16 v[112:115], v[148:151], v[188:191], v[112:115]
	v_mfma_f32_16x16x32_bf16 v[104:107], v[156:159], v[188:191], v[104:107]
	v_mfma_f32_16x16x32_bf16 v[96:99], v[148:151], v[196:199], v[96:99]
	v_mfma_f32_16x16x32_bf16 v[88:91], v[156:159], v[196:199], v[88:91]
	v_mfma_f32_16x16x32_bf16 v[80:83], v[148:151], v[204:207], v[80:83]
	v_mfma_f32_16x16x32_bf16 v[72:75], v[156:159], v[204:207], v[72:75]
	v_mfma_f32_16x16x32_bf16 v[124:127], v[152:155], v[184:187], v[124:127]
	v_mfma_f32_16x16x32_bf16 v[120:123], v[160:163], v[184:187], v[120:123]
	v_mfma_f32_16x16x32_bf16 v[112:115], v[152:155], v[192:195], v[112:115]
	v_mfma_f32_16x16x32_bf16 v[104:107], v[160:163], v[192:195], v[104:107]
	v_mfma_f32_16x16x32_bf16 v[96:99], v[152:155], v[200:203], v[96:99]
	v_mfma_f32_16x16x32_bf16 v[88:91], v[160:163], v[200:203], v[88:91]
	v_mfma_f32_16x16x32_bf16 v[80:83], v[152:155], v[208:211], v[80:83]
	v_mfma_f32_16x16x32_bf16 v[72:75], v[160:163], v[208:211], v[72:75]
	s_setprio 0
	s_setprio 1
	v_mfma_f32_16x16x32_bf16 v[116:119], v[164:167], v[180:183], v[116:119]
	v_mfma_f32_16x16x32_bf16 v[108:111], v[172:175], v[180:183], v[108:111]
	v_mfma_f32_16x16x32_bf16 v[100:103], v[164:167], v[188:191], v[100:103]
	v_mfma_f32_16x16x32_bf16 v[92:95], v[172:175], v[188:191], v[92:95]
	v_mfma_f32_16x16x32_bf16 v[84:87], v[164:167], v[196:199], v[84:87]
	v_mfma_f32_16x16x32_bf16 v[76:79], v[172:175], v[196:199], v[76:79]
	v_mfma_f32_16x16x32_bf16 v[68:71], v[164:167], v[204:207], v[68:71]
	v_mfma_f32_16x16x32_bf16 v[64:67], v[172:175], v[204:207], v[64:67]
	v_mfma_f32_16x16x32_bf16 v[116:119], v[168:171], v[184:187], v[116:119]
	v_mfma_f32_16x16x32_bf16 v[108:111], v[176:179], v[184:187], v[108:111]
	v_mfma_f32_16x16x32_bf16 v[100:103], v[168:171], v[192:195], v[100:103]
	v_mfma_f32_16x16x32_bf16 v[92:95], v[176:179], v[192:195], v[92:95]
	v_mfma_f32_16x16x32_bf16 v[84:87], v[168:171], v[200:203], v[84:87]
	v_mfma_f32_16x16x32_bf16 v[76:79], v[176:179], v[200:203], v[76:79]
	v_mfma_f32_16x16x32_bf16 v[68:71], v[168:171], v[208:211], v[68:71]
	v_mfma_f32_16x16x32_bf16 v[64:67], v[176:179], v[208:211], v[64:67]
	s_setprio 0
	s_barrier
	s_add_i32 s34, s59, s45
	v_lshl_add_u64 v[140:141], s[38:39], 0, v[130:131]
	s_mov_b32 m0, s34
	ds_read_b128 v[180:183], v147 offset:16384
	ds_read_b128 v[184:187], v147 offset:17408
	ds_read_b128 v[188:191], v147 offset:18432
	ds_read_b128 v[192:195], v147 offset:19456
	ds_read_b128 v[196:199], v147 offset:20480
	ds_read_b128 v[200:203], v147 offset:21504
	ds_read_b128 v[204:207], v147 offset:22528
	ds_read_b128 v[208:211], v147 offset:23552
	global_load_lds_dwordx4 v[140:141], off
	s_add_i32 m0, s34, 0x2000
	s_add_u32 s34, s38, 0x2b0000
	v_lshl_add_u64 v[212:213], s[38:39], 0, v[128:129]
	s_addc_u32 s35, s39, 0
	s_add_i32 s66, s60, s45
	global_load_lds_dwordx4 v[212:213], off
	v_lshl_add_u64 v[214:215], s[34:35], 0, v[130:131]
	s_mov_b32 m0, s66
	v_lshl_add_u64 v[216:217], s[40:41], 0, v[128:129]
	global_load_lds_dwordx4 v[214:215], off
	v_lshl_add_u64 v[214:215], s[34:35], 0, v[128:129]
	s_add_i32 m0, s66, 0x2000
	s_nop 0
	global_load_lds_dwordx4 v[214:215], off
	v_lshl_add_u64 v[214:215], s[40:41], 0, v[130:131]
	s_mov_b32 m0, s48
	s_nop 0
	global_load_lds_dwordx4 v[214:215], off
	s_mov_b32 m0, s49
	s_nop 0
	global_load_lds_dwordx4 v[216:217], off
	s_waitcnt vmcnt(8)
	s_waitcnt lgkmcnt(0)
	s_setprio 1
	s_barrier
	v_mfma_f32_16x16x32_bf16 v[60:63], v[148:151], v[180:183], v[60:63]
	v_mfma_f32_16x16x32_bf16 v[56:59], v[156:159], v[180:183], v[56:59]
	v_mfma_f32_16x16x32_bf16 v[48:51], v[148:151], v[188:191], v[48:51]
	v_mfma_f32_16x16x32_bf16 v[40:43], v[156:159], v[188:191], v[40:43]
	v_mfma_f32_16x16x32_bf16 v[32:35], v[148:151], v[196:199], v[32:35]
	v_mfma_f32_16x16x32_bf16 v[24:27], v[156:159], v[196:199], v[24:27]
	v_mfma_f32_16x16x32_bf16 v[16:19], v[148:151], v[204:207], v[16:19]
	v_mfma_f32_16x16x32_bf16 v[8:11], v[156:159], v[204:207], v[8:11]
	v_mfma_f32_16x16x32_bf16 v[60:63], v[152:155], v[184:187], v[60:63]
	v_mfma_f32_16x16x32_bf16 v[56:59], v[160:163], v[184:187], v[56:59]
	v_mfma_f32_16x16x32_bf16 v[48:51], v[152:155], v[192:195], v[48:51]
	v_mfma_f32_16x16x32_bf16 v[40:43], v[160:163], v[192:195], v[40:43]
	v_mfma_f32_16x16x32_bf16 v[32:35], v[152:155], v[200:203], v[32:35]
	v_mfma_f32_16x16x32_bf16 v[24:27], v[160:163], v[200:203], v[24:27]
	v_mfma_f32_16x16x32_bf16 v[16:19], v[152:155], v[208:211], v[16:19]
	v_mfma_f32_16x16x32_bf16 v[8:11], v[160:163], v[208:211], v[8:11]
	s_setprio 0
	s_setprio 1
	v_mfma_f32_16x16x32_bf16 v[52:55], v[164:167], v[180:183], v[52:55]
	v_mfma_f32_16x16x32_bf16 v[44:47], v[172:175], v[180:183], v[44:47]
	v_mfma_f32_16x16x32_bf16 v[36:39], v[164:167], v[188:191], v[36:39]
	v_mfma_f32_16x16x32_bf16 v[28:31], v[172:175], v[188:191], v[28:31]
	v_mfma_f32_16x16x32_bf16 v[20:23], v[164:167], v[196:199], v[20:23]
	v_mfma_f32_16x16x32_bf16 v[12:15], v[172:175], v[196:199], v[12:15]
	v_mfma_f32_16x16x32_bf16 v[4:7], v[164:167], v[204:207], v[4:7]
	v_mfma_f32_16x16x32_bf16 v[0:3], v[172:175], v[204:207], v[0:3]
	v_mfma_f32_16x16x32_bf16 v[52:55], v[168:171], v[184:187], v[52:55]
	v_mfma_f32_16x16x32_bf16 v[44:47], v[176:179], v[184:187], v[44:47]
	v_mfma_f32_16x16x32_bf16 v[36:39], v[168:171], v[192:195], v[36:39]
	v_mfma_f32_16x16x32_bf16 v[28:31], v[176:179], v[192:195], v[28:31]
	v_mfma_f32_16x16x32_bf16 v[20:23], v[168:171], v[200:203], v[20:23]
	v_mfma_f32_16x16x32_bf16 v[12:15], v[176:179], v[200:203], v[12:15]
	v_mfma_f32_16x16x32_bf16 v[4:7], v[168:171], v[208:211], v[4:7]
	v_mfma_f32_16x16x32_bf16 v[0:3], v[176:179], v[208:211], v[0:3]
	s_setprio 0
	s_barrier
	s_add_i32 s66, 0, 0x18000
	s_add_i32 s67, 0, 0x1c000
	v_add_u32_e32 v160, s66, v144
	v_add_u32_e32 v176, s67, v144
	ds_read_b128 v[148:151], v160
	ds_read_b128 v[152:155], v160 offset:1024
	ds_read_b128 v[156:159], v160 offset:2048
	ds_read_b128 v[160:163], v160 offset:3072
	ds_read_b128 v[164:167], v176
	ds_read_b128 v[168:171], v176 offset:1024
	ds_read_b128 v[172:175], v176 offset:2048
	ds_read_b128 v[176:179], v176 offset:3072
	s_add_u32 s34, s40, 0x2b0000
	s_addc_u32 s35, s41, 0
	s_mov_b32 m0, s50
	v_lshl_add_u64 v[218:219], s[34:35], 0, v[130:131]
	ds_read_b128 v[180:183], v147 offset:32768
	ds_read_b128 v[184:187], v147 offset:33792
	ds_read_b128 v[188:191], v147 offset:34816
	ds_read_b128 v[192:195], v147 offset:35840
	ds_read_b128 v[196:199], v147 offset:36864
	ds_read_b128 v[200:203], v147 offset:37888
	ds_read_b128 v[204:207], v147 offset:38912
	ds_read_b128 v[208:211], v147 offset:39936
	global_load_lds_dwordx4 v[218:219], off
	v_lshl_add_u64 v[218:219], s[34:35], 0, v[128:129]
	s_mov_b32 m0, s51
	s_nop 0
	global_load_lds_dwordx4 v[218:219], off
	s_waitcnt vmcnt(8)
	s_waitcnt lgkmcnt(0)
	s_setprio 1
	s_barrier
	v_mfma_f32_16x16x32_bf16 v[124:127], v[148:151], v[180:183], v[124:127]
	v_mfma_f32_16x16x32_bf16 v[120:123], v[156:159], v[180:183], v[120:123]
	v_mfma_f32_16x16x32_bf16 v[112:115], v[148:151], v[188:191], v[112:115]
	v_mfma_f32_16x16x32_bf16 v[104:107], v[156:159], v[188:191], v[104:107]
	v_mfma_f32_16x16x32_bf16 v[96:99], v[148:151], v[196:199], v[96:99]
	v_mfma_f32_16x16x32_bf16 v[88:91], v[156:159], v[196:199], v[88:91]
	v_mfma_f32_16x16x32_bf16 v[80:83], v[148:151], v[204:207], v[80:83]
	v_mfma_f32_16x16x32_bf16 v[72:75], v[156:159], v[204:207], v[72:75]
	v_mfma_f32_16x16x32_bf16 v[124:127], v[152:155], v[184:187], v[124:127]
	v_mfma_f32_16x16x32_bf16 v[120:123], v[160:163], v[184:187], v[120:123]
	v_mfma_f32_16x16x32_bf16 v[112:115], v[152:155], v[192:195], v[112:115]
	v_mfma_f32_16x16x32_bf16 v[104:107], v[160:163], v[192:195], v[104:107]
	v_mfma_f32_16x16x32_bf16 v[96:99], v[152:155], v[200:203], v[96:99]
	v_mfma_f32_16x16x32_bf16 v[88:91], v[160:163], v[200:203], v[88:91]
	v_mfma_f32_16x16x32_bf16 v[80:83], v[152:155], v[208:211], v[80:83]
	v_mfma_f32_16x16x32_bf16 v[72:75], v[160:163], v[208:211], v[72:75]
	s_setprio 0
	s_setprio 1
	v_mfma_f32_16x16x32_bf16 v[116:119], v[164:167], v[180:183], v[116:119]
	v_mfma_f32_16x16x32_bf16 v[108:111], v[172:175], v[180:183], v[108:111]
	v_mfma_f32_16x16x32_bf16 v[100:103], v[164:167], v[188:191], v[100:103]
	v_mfma_f32_16x16x32_bf16 v[92:95], v[172:175], v[188:191], v[92:95]
	v_mfma_f32_16x16x32_bf16 v[84:87], v[164:167], v[196:199], v[84:87]
	v_mfma_f32_16x16x32_bf16 v[76:79], v[172:175], v[196:199], v[76:79]
	v_mfma_f32_16x16x32_bf16 v[68:71], v[164:167], v[204:207], v[68:71]
	v_mfma_f32_16x16x32_bf16 v[64:67], v[172:175], v[204:207], v[64:67]
	v_mfma_f32_16x16x32_bf16 v[116:119], v[168:171], v[184:187], v[116:119]
	v_mfma_f32_16x16x32_bf16 v[108:111], v[176:179], v[184:187], v[108:111]
	v_mfma_f32_16x16x32_bf16 v[100:103], v[168:171], v[192:195], v[100:103]
	v_mfma_f32_16x16x32_bf16 v[92:95], v[176:179], v[192:195], v[92:95]
	v_mfma_f32_16x16x32_bf16 v[84:87], v[168:171], v[200:203], v[84:87]
	v_mfma_f32_16x16x32_bf16 v[76:79], v[176:179], v[200:203], v[76:79]
	v_mfma_f32_16x16x32_bf16 v[68:71], v[168:171], v[208:211], v[68:71]
	v_mfma_f32_16x16x32_bf16 v[64:67], v[176:179], v[208:211], v[64:67]
	s_setprio 0
	s_barrier
	s_add_i32 s34, s66, s45
	v_lshl_add_u64 v[140:141], v[140:141], 0, s[10:11]
	s_mov_b32 m0, s34
	ds_read_b128 v[180:183], v147 offset:49152
	ds_read_b128 v[184:187], v147 offset:50176
	ds_read_b128 v[188:191], v147 offset:51200
	ds_read_b128 v[192:195], v147 offset:52224
	ds_read_b128 v[196:199], v147 offset:53248
	ds_read_b128 v[200:203], v147 offset:54272
	ds_read_b128 v[204:207], v147 offset:55296
	ds_read_b128 v[208:211], v147 offset:56320
	global_load_lds_dwordx4 v[140:141], off
	s_add_i32 m0, s34, 0x2000
	s_add_u32 s34, s38, 0x2b0080
	v_lshl_add_u64 v[140:141], v[212:213], 0, s[10:11]
	s_addc_u32 s35, s39, 0
	s_add_i32 s38, s67, s45
	global_load_lds_dwordx4 v[140:141], off
	v_lshl_add_u64 v[140:141], s[34:35], 0, v[130:131]
	s_mov_b32 m0, s38
	s_nop 0
	global_load_lds_dwordx4 v[140:141], off
	v_lshl_add_u64 v[140:141], s[34:35], 0, v[128:129]
	s_add_i32 m0, s38, 0x2000
	s_nop 0
	global_load_lds_dwordx4 v[140:141], off
	v_lshl_add_u64 v[140:141], v[214:215], 0, s[10:11]
	s_mov_b32 m0, s57
	s_nop 0
	global_load_lds_dwordx4 v[140:141], off
	v_lshl_add_u64 v[140:141], v[216:217], 0, s[10:11]
	s_mov_b32 m0, s58
	s_nop 0
	global_load_lds_dwordx4 v[140:141], off
	s_waitcnt vmcnt(8)
	s_waitcnt lgkmcnt(0)
	s_setprio 1
	s_barrier
	v_mfma_f32_16x16x32_bf16 v[60:63], v[148:151], v[180:183], v[60:63]
	v_mfma_f32_16x16x32_bf16 v[56:59], v[156:159], v[180:183], v[56:59]
	v_mfma_f32_16x16x32_bf16 v[48:51], v[148:151], v[188:191], v[48:51]
	v_mfma_f32_16x16x32_bf16 v[40:43], v[156:159], v[188:191], v[40:43]
	v_mfma_f32_16x16x32_bf16 v[32:35], v[148:151], v[196:199], v[32:35]
	v_mfma_f32_16x16x32_bf16 v[24:27], v[156:159], v[196:199], v[24:27]
	v_mfma_f32_16x16x32_bf16 v[16:19], v[148:151], v[204:207], v[16:19]
	v_mfma_f32_16x16x32_bf16 v[8:11], v[156:159], v[204:207], v[8:11]
	v_mfma_f32_16x16x32_bf16 v[60:63], v[152:155], v[184:187], v[60:63]
	v_mfma_f32_16x16x32_bf16 v[56:59], v[160:163], v[184:187], v[56:59]
	v_mfma_f32_16x16x32_bf16 v[48:51], v[152:155], v[192:195], v[48:51]
	v_mfma_f32_16x16x32_bf16 v[40:43], v[160:163], v[192:195], v[40:43]
	v_mfma_f32_16x16x32_bf16 v[32:35], v[152:155], v[200:203], v[32:35]
	v_mfma_f32_16x16x32_bf16 v[24:27], v[160:163], v[200:203], v[24:27]
	v_mfma_f32_16x16x32_bf16 v[16:19], v[152:155], v[208:211], v[16:19]
	v_mfma_f32_16x16x32_bf16 v[8:11], v[160:163], v[208:211], v[8:11]
	s_setprio 0
	s_setprio 1
	v_mfma_f32_16x16x32_bf16 v[52:55], v[164:167], v[180:183], v[52:55]
	v_mfma_f32_16x16x32_bf16 v[44:47], v[172:175], v[180:183], v[44:47]
	v_mfma_f32_16x16x32_bf16 v[36:39], v[164:167], v[188:191], v[36:39]
	v_mfma_f32_16x16x32_bf16 v[28:31], v[172:175], v[188:191], v[28:31]
	v_mfma_f32_16x16x32_bf16 v[20:23], v[164:167], v[196:199], v[20:23]
	v_mfma_f32_16x16x32_bf16 v[12:15], v[172:175], v[196:199], v[12:15]
	v_mfma_f32_16x16x32_bf16 v[4:7], v[164:167], v[204:207], v[4:7]
	v_mfma_f32_16x16x32_bf16 v[0:3], v[172:175], v[204:207], v[0:3]
	v_mfma_f32_16x16x32_bf16 v[52:55], v[168:171], v[184:187], v[52:55]
	v_mfma_f32_16x16x32_bf16 v[44:47], v[176:179], v[184:187], v[44:47]
	v_mfma_f32_16x16x32_bf16 v[36:39], v[168:171], v[192:195], v[36:39]
	v_mfma_f32_16x16x32_bf16 v[28:31], v[176:179], v[192:195], v[28:31]
	v_mfma_f32_16x16x32_bf16 v[20:23], v[168:171], v[200:203], v[20:23]
	v_mfma_f32_16x16x32_bf16 v[12:15], v[176:179], v[200:203], v[12:15]
	v_mfma_f32_16x16x32_bf16 v[4:7], v[168:171], v[208:211], v[4:7]
	v_mfma_f32_16x16x32_bf16 v[0:3], v[176:179], v[208:211], v[0:3]
	s_setprio 0
	s_barrier
	s_add_i32 s65, s65, 2
	s_add_u32 s31, s31, 0x100
	s_addc_u32 s64, s64, 0
	s_cmpk_gt_u32 s65, 0xa9
	s_mov_b64 s[34:35], s[36:37]
	s_cbranch_scc0 .LBB0_1035
	s_and_b64 vcc, exec, s[12:13]
	s_cbranch_vccz .LBB0_1038
	s_barrier
